# v10: v9 plus one wait state after packed-f32 mul/fma/add results before a dependent VALU read (matches hipcc spacing)
# speedup vs baseline: 1.0083x; 1.0016x over previous
; __device__ __forceinline__ unsigned pk2(float lo, float hi) { return f2bf(lo) | (f2bf(hi) << 16); }
; __device__ __forceinline__ void phase_prologue(const Params& P, LAS unsigned char* lds) {
;     ...
;     for (int m0 = gw; m0 < NTOK; m0 += RP * NGW) {
;         f32x4 v[RP][4];
; #pragma unroll
;         for (int q = 0; q < RP; ++q) {
;             const f32x4* xr = (const f32x4*)(P.x + (size_t)(m0 + q * NGW) * DM) + lane;
; #pragma unroll
;             for (int j = 0; j < 4; ++j) v[q][j] = __builtin_nontemporal_load(xr + 64 * j);
;         }
; #pragma unroll
;         for (int q = 0; q < RP; ++q) {
;             float ss = 0.f;
; #pragma unroll
;             for (int j = 0; j < 4; ++j) ss += (v[q][j][0] * v[q][j][0] + v[q][j][1] * v[q][j][1]) + (v[q][j][2] * v[q][j][2] + v[q][j][3] * v[q][j][3]);
;             const float rstd = 1.0f / sqrtf(wave_sum(ss) * (1.0f / DM) + RMS_EPS);
;             unsigned long long* o8 = (unsigned long long*)(HB + (size_t)(m0 + q * NGW) * DM) + lane;
; #pragma unroll
;             for (int j = 0; j < 4; ++j) { v[q][j] = v[q][j] * rstd * ng[j]; o8[64 * j] = (unsigned long long)pk2(v[q][j][0], v[q][j][1]) | ((unsigned long long)pk2(v[q][j][2], v[q][j][3]) << 32); }
.LBB0_100:
	v_lshl_add_u64 v[28:29], v[78:79], 0, v[68:69]
	global_load_dwordx4 v[24:27], v[28:29], off nt
	global_load_dwordx4 v[20:23], v[28:29], off offset:1024 nt
	s_waitcnt lgkmcnt(0)
	global_load_dwordx4 v[16:19], v[28:29], off offset:3072 nt
	s_nop 0
	global_load_dwordx4 v[28:31], v[28:29], off offset:2048 nt
	v_lshl_add_u64 v[36:37], v[84:85], 0, v[68:69]
	global_load_dwordx4 v[44:47], v[36:37], off nt
	global_load_dwordx4 v[40:43], v[36:37], off offset:1024 nt
	global_load_dwordx4 v[32:35], v[36:37], off offset:3072 nt
	s_nop 0
	global_load_dwordx4 v[36:39], v[36:37], off offset:2048 nt
	v_add_u32_e32 v92, s1, v64
	v_ashrrev_i32_e32 v93, 31, v92
	v_lshl_add_u64 v[110:111], v[82:83], 0, v[66:67]
	s_waitcnt vmcnt(7)
	v_pk_mul_f32 v[48:49], v[26:27], v[26:27]
	v_pk_mul_f32 v[50:51], v[24:25], v[24:25]
	s_waitcnt vmcnt(6)
	v_pk_mul_f32 v[52:53], v[22:23], v[22:23]
	v_pk_mul_f32 v[54:55], v[20:21], v[20:21]
	v_pk_mov_b32 v[60:61], v[50:51], v[48:49] op_sel:[1,0]
	v_mov_b32_e32 v51, v49
	v_pk_mov_b32 v[48:49], v[54:55], v[52:53] op_sel:[1,0]
	v_mov_b32_e32 v55, v53
	s_waitcnt vmcnt(5)
	v_mul_f32_e32 v59, v16, v16
	s_waitcnt vmcnt(4)
	v_mul_f32_e32 v56, v29, v29
	v_mul_f32_e32 v58, v31, v31
	v_pk_add_f32 v[50:51], v[60:61], v[50:51]
	v_pk_add_f32 v[48:49], v[48:49], v[54:55]
	v_mul_f32_e32 v62, v17, v17
	v_mul_f32_e32 v63, v18, v18
	v_mul_f32_e32 v90, v19, v19
	v_pk_fma_f32 v[52:53], v[28:29], v[28:29], v[56:57] op_sel_hi:[1,1,0]
	v_pk_fma_f32 v[56:57], v[30:31], v[30:31], v[58:59] op_sel_hi:[1,1,0]
	v_pk_add_f32 v[50:51], v[50:51], v[50:51] op_sel:[0,1] op_sel_hi:[1,0]
	v_pk_add_f32 v[48:49], v[48:49], v[48:49] op_sel:[0,1] op_sel_hi:[1,0]
	v_mov_b32_e32 v53, v63
	v_mov_b32_e32 v57, v90
	v_mov_b32_e32 v51, v59
	v_mov_b32_e32 v49, v62
	v_pk_add_f32 v[52:53], v[52:53], v[56:57]
	v_pk_add_f32 v[48:49], v[50:51], v[48:49]
	s_waitcnt vmcnt(3)
	v_pk_mul_f32 v[50:51], v[46:47], v[46:47]
	v_pk_add_f32 v[48:49], v[48:49], v[52:53]
	v_pk_mul_f32 v[52:53], v[44:45], v[44:45]
	v_add_f32_e32 v48, v48, v49
	ds_bpermute_b32 v49, v112, v48
	s_waitcnt vmcnt(2)
	v_pk_mul_f32 v[54:55], v[42:43], v[42:43]
	s_waitcnt vmcnt(1)
	v_mul_f32_e32 v61, v32, v32
	s_waitcnt vmcnt(0)
	v_mul_f32_e32 v58, v37, v37
	v_pk_mov_b32 v[62:63], v[52:53], v[50:51] op_sel:[1,0]
	s_waitcnt lgkmcnt(0)
	v_add_f32_e32 v56, v48, v49
	ds_bpermute_b32 v57, v113, v56
	v_mov_b32_e32 v53, v51
	v_pk_add_f32 v[52:53], v[62:63], v[52:53]
	v_mul_f32_e32 v94, v33, v33
	v_pk_add_f32 v[52:53], v[52:53], v[52:53] op_sel:[0,1] op_sel_hi:[1,0]
	s_waitcnt lgkmcnt(0)
	v_add_f32_e32 v59, v56, v57
	ds_bpermute_b32 v60, v114, v59
	v_pk_mul_f32 v[56:57], v[40:41], v[40:41]
	v_mul_f32_e32 v96, v34, v34
	v_pk_mov_b32 v[50:51], v[56:57], v[54:55] op_sel:[1,0]
	v_mov_b32_e32 v57, v55
	s_waitcnt lgkmcnt(0)
	v_add_f32_e32 v59, v59, v60
	ds_bpermute_b32 v95, v115, v59
	v_mul_f32_e32 v60, v39, v39
	v_pk_fma_f32 v[54:55], v[36:37], v[36:37], v[58:59] op_sel_hi:[1,1,0]
	v_pk_add_f32 v[50:51], v[50:51], v[56:57]
	v_mov_b32_e32 v55, v96
	s_waitcnt lgkmcnt(0)
	v_add_f32_e32 v95, v59, v95
	ds_bpermute_b32 v97, v116, v95
	v_pk_fma_f32 v[58:59], v[38:39], v[38:39], v[60:61] op_sel_hi:[1,1,0]
	v_pk_add_f32 v[50:51], v[50:51], v[50:51] op_sel:[0,1] op_sel_hi:[1,0]
	v_lshlrev_b64 v[48:49], 12, v[92:93]
	v_mov_b32_e32 v51, v94
	s_waitcnt lgkmcnt(0)
	v_add_f32_e32 v59, v95, v97
	ds_bpermute_b32 v60, v117, v59
	v_add_u32_e32 v90, s3, v64
	v_ashrrev_i32_e32 v91, 31, v90
	s_waitcnt lgkmcnt(0)
	v_add_f32_e32 v53, v59, v60
	v_fmamk_f32 v53, v53, 0x3a800000, v65
	v_mul_f32_e32 v56, 0x4f800000, v53
	v_cmp_gt_f32_e32 vcc, s16, v53
	s_nop 1
	v_cndmask_b32_e32 v56, v53, v56, vcc
	v_sqrt_f32_e32 v57, v56
	v_mov_b32_e32 v53, v61
	v_pk_add_f32 v[50:51], v[52:53], v[50:51]
	v_add_u32_e32 v59, -1, v57
	v_add_u32_e32 v60, 1, v57
	v_fma_f32 v61, -v59, v57, v56
	v_fma_f32 v62, -v60, v57, v56
	v_cmp_ge_f32_e64 s[14:15], 0, v61
	s_nop 1
	v_cndmask_b32_e64 v57, v57, v59, s[14:15]
	v_cmp_lt_f32_e64 s[14:15], 0, v62
	s_nop 1
	v_cndmask_b32_e64 v57, v57, v60, s[14:15]
	v_mul_f32_e32 v59, 0x37800000, v57
	v_cndmask_b32_e32 v57, v57, v59, vcc
	v_cmp_class_f32_e32 vcc, v56, v119
	s_nop 1
	v_cndmask_b32_e32 v56, v57, v56, vcc
	v_div_scale_f32 v57, s[14:15], v56, v56, 1.0
	v_rcp_f32_e32 v59, v57
	v_div_scale_f32 v52, vcc, 1.0, v56, 1.0
	v_fma_f32 v53, -v57, v59, 1.0
	v_fmac_f32_e32 v59, v53, v59
	v_mul_f32_e32 v53, v52, v59
	v_fma_f32 v60, -v57, v53, v52
	v_fmac_f32_e32 v53, v60, v59
	v_fma_f32 v52, -v57, v53, v52
	v_div_fmas_f32 v52, v52, v59, v53
	v_div_fixup_f32 v52, v52, v56, 1.0
	v_pk_mul_f32 v[24:25], v[24:25], v[52:53] op_sel_hi:[1,0]
	v_pk_mul_f32 v[20:21], v[20:21], v[52:53] op_sel_hi:[1,0]
	v_pk_mul_f32 v[108:109], v[0:1], v[24:25]
	v_pk_mul_f32 v[100:101], v[16:17], v[52:53] op_sel_hi:[1,0]
	v_pk_mul_f32 v[104:105], v[4:5], v[20:21]
	v_mul_f32_e32 v59, v35, v35
	v_cvt_pk_bf16_f32 v120, v108, v109
	v_pk_add_f32 v[16:17], v[54:55], v[58:59]
	v_pk_mul_f32 v[26:27], v[26:27], v[52:53] op_sel_hi:[1,0]
	v_pk_add_f32 v[16:17], v[50:51], v[16:17]
	v_pk_mul_f32 v[106:107], v[2:3], v[26:27]
	v_cvt_pk_bf16_f32 v122, v104, v105
	v_add_f32_e32 v20, v16, v17
	v_pk_mul_f32 v[98:99], v[18:19], v[52:53] op_sel_hi:[1,0]
	ds_bpermute_b32 v21, v112, v20
	v_cvt_pk_bf16_f32 v121, v106, v107
	v_lshl_add_u64 v[18:19], v[74:75], 0, v[48:49]
	v_pk_mul_f32 v[22:23], v[22:23], v[52:53] op_sel_hi:[1,0]
	v_pk_mul_f32 v[28:29], v[28:29], v[52:53] op_sel_hi:[1,0]
	v_pk_mul_f32 v[30:31], v[30:31], v[52:53] op_sel_hi:[1,0]
	global_load_dwordx4 v[60:63], v[18:19], off nt
	global_load_dwordx4 v[56:59], v[18:19], off offset:1024 nt
	global_load_dwordx4 v[52:55], v[18:19], off offset:2048 nt
	global_load_dwordx4 v[48:51], v[18:19], off offset:3072 nt
	s_waitcnt lgkmcnt(0)
; __device__ __forceinline__ unsigned pk2(float lo, float hi) { return f2bf(lo) | (f2bf(hi) << 16); }
; __device__ __forceinline__ void phase_prologue(const Params& P, LAS unsigned char* lds) {
;     ...
;         for (int q = 0; q < RP; ++q) {
;             float ss = 0.f;
; #pragma unroll
;             for (int j = 0; j < 4; ++j) ss += (v[q][j][0] * v[q][j][0] + v[q][j][1] * v[q][j][1]) + (v[q][j][2] * v[q][j][2] + v[q][j][3] * v[q][j][3]);
;             const float rstd = 1.0f / sqrtf(wave_sum(ss) * (1.0f / DM) + RMS_EPS);
;             unsigned long long* o8 = (unsigned long long*)(HB + (size_t)(m0 + q * NGW) * DM) + lane;
; #pragma unroll
;             for (int j = 0; j < 4; ++j) { v[q][j] = v[q][j] * rstd * ng[j]; o8[64 * j] = (unsigned long long)pk2(v[q][j][0], v[q][j][1]) | ((unsigned long long)pk2(v[q][j][2], v[q][j][3]) << 32); }
	v_add_f32_e32 v20, v20, v21
	ds_bpermute_b32 v21, v113, v20
	v_pk_mul_f32 v[102:103], v[6:7], v[22:23]
	v_pk_mul_f32 v[94:95], v[10:11], v[30:31]
	v_pk_mul_f32 v[96:97], v[8:9], v[28:29]
	s_waitcnt lgkmcnt(0)
	v_add_f32_e32 v126, v20, v21
	ds_bpermute_b32 v127, v114, v126
	s_waitcnt lgkmcnt(0)
	v_add_f32_e32 v126, v126, v127
	ds_bpermute_b32 v127, v115, v126
	v_lshlrev_b64 v[16:17], 12, v[90:91]
	v_lshl_add_u64 v[16:17], v[74:75], 0, v[16:17]
	v_cvt_pk_bf16_f32 v123, v102, v103
	v_cvt_pk_bf16_f32 v124, v96, v97
	v_cvt_pk_bf16_f32 v125, v94, v95
	global_load_dwordx4 v[28:31], v[16:17], off nt
	global_load_dwordx4 v[24:27], v[16:17], off offset:1024 nt
	global_load_dwordx4 v[20:23], v[16:17], off offset:2048 nt
	s_nop 0
	global_load_dwordx4 v[16:19], v[16:17], off offset:3072 nt
	s_nop 0
	global_store_dwordx2 v[110:111], v[120:121], off
	global_store_dwordx2 v[110:111], v[122:123], off offset:512
	global_store_dwordx2 v[110:111], v[124:125], off offset:1024
	s_waitcnt lgkmcnt(0)
	v_add_f32_e32 v120, v126, v127
	ds_bpermute_b32 v121, v116, v120
	v_pk_mul_f32 v[100:101], v[12:13], v[100:101]
	v_pk_mul_f32 v[98:99], v[14:15], v[98:99]
	s_waitcnt lgkmcnt(0)
	v_add_f32_e32 v121, v120, v121
	ds_bpermute_b32 v124, v117, v121
	v_cvt_pk_bf16_f32 v120, v100, v101
	s_waitcnt lgkmcnt(0)
	v_add_f32_e32 v121, v121, v124
	v_fmamk_f32 v121, v121, 0x3a800000, v65
	v_mul_f32_e32 v123, 0x4f800000, v121
	v_cmp_gt_f32_e32 vcc, s16, v121
	s_nop 1
	v_cndmask_b32_e32 v121, v121, v123, vcc
	v_sqrt_f32_e32 v123, v121
	s_nop 0
	v_add_u32_e32 v125, -1, v123
	v_fma_f32 v126, -v125, v123, v121
	v_cmp_ge_f32_e64 s[14:15], 0, v126
	v_add_u32_e32 v126, 1, v123
	s_nop 0
	v_cndmask_b32_e64 v125, v123, v125, s[14:15]
	v_fma_f32 v123, -v126, v123, v121
	v_cmp_lt_f32_e64 s[14:15], 0, v123
	s_nop 1
	v_cndmask_b32_e64 v123, v125, v126, s[14:15]
	v_mul_f32_e32 v125, 0x37800000, v123
	v_cndmask_b32_e32 v123, v123, v125, vcc
	v_cmp_class_f32_e32 vcc, v121, v119
	s_nop 1
	v_cndmask_b32_e32 v123, v123, v121, vcc
	v_div_scale_f32 v125, s[14:15], v123, v123, 1.0
	v_rcp_f32_e32 v126, v125
	v_cvt_pk_bf16_f32 v121, v98, v99
	global_store_dwordx2 v[110:111], v[120:121], off offset:1536
	v_fma_f32 v110, -v125, v126, 1.0
	v_fmac_f32_e32 v126, v110, v126
	v_div_scale_f32 v110, vcc, 1.0, v123, 1.0
	v_mul_f32_e32 v111, v110, v126
	v_fma_f32 v120, -v125, v111, v110
	v_fmac_f32_e32 v111, v120, v126
	v_fma_f32 v110, -v125, v111, v110
	v_div_fmas_f32 v110, v110, v126, v111
	v_div_fixup_f32 v110, v110, v123, 1.0
	v_pk_mul_f32 v[44:45], v[44:45], v[110:111] op_sel_hi:[1,0]
	v_pk_mul_f32 v[122:123], v[38:39], v[110:111] op_sel_hi:[1,0]
	v_pk_mul_f32 v[38:39], v[0:1], v[44:45]
	v_pk_mul_f32 v[124:125], v[32:33], v[110:111] op_sel_hi:[1,0]
	v_pk_mul_f32 v[46:47], v[46:47], v[110:111] op_sel_hi:[1,0]
	v_pk_mul_f32 v[120:121], v[36:37], v[110:111] op_sel_hi:[1,0]
	v_pk_mul_f32 v[36:37], v[2:3], v[46:47]
	v_cvt_pk_bf16_f32 v32, v38, v39
	v_pk_mul_f32 v[40:41], v[40:41], v[110:111] op_sel_hi:[1,0]
	v_pk_mul_f32 v[42:43], v[42:43], v[110:111] op_sel_hi:[1,0]
	v_pk_mul_f32 v[110:111], v[34:35], v[110:111] op_sel_hi:[1,0]
	v_cvt_pk_bf16_f32 v33, v36, v37
	v_pk_mul_f32 v[34:35], v[4:5], v[40:41]
	v_lshl_add_u64 v[126:127], v[80:81], 0, v[66:67]
	global_store_dwordx2 v[126:127], v[32:33], off
	v_pk_mul_f32 v[32:33], v[6:7], v[42:43]
	v_cvt_pk_bf16_f32 v40, v34, v35
	v_cvt_pk_bf16_f32 v41, v32, v33
	global_store_dwordx2 v[126:127], v[40:41], off offset:512
	s_waitcnt vmcnt(13)
	v_pk_mul_f32 v[40:41], v[62:63], v[62:63]
	v_pk_mul_f32 v[42:43], v[60:61], v[60:61]
	s_nop 0
	v_pk_mov_b32 v[44:45], v[42:43], v[40:41] op_sel:[1,0]
	v_mov_b32_e32 v43, v41
	v_pk_add_f32 v[40:41], v[44:45], v[42:43]
	s_waitcnt vmcnt(12)
	v_pk_mul_f32 v[42:43], v[58:59], v[58:59]
	v_pk_mul_f32 v[44:45], v[56:57], v[56:57]
	v_pk_add_f32 v[40:41], v[40:41], v[40:41] op_sel:[0,1] op_sel_hi:[1,0]
	v_pk_mov_b32 v[46:47], v[44:45], v[42:43] op_sel:[1,0]
	v_mov_b32_e32 v45, v43
	v_pk_add_f32 v[42:43], v[46:47], v[44:45]
	s_waitcnt vmcnt(10)
	v_mul_f32_e32 v41, v48, v48
	v_pk_add_f32 v[42:43], v[42:43], v[42:43] op_sel:[0,1] op_sel_hi:[1,0]
	v_mul_f32_e32 v44, v55, v55
	v_mul_f32_e32 v43, v49, v49
	v_pk_add_f32 v[40:41], v[40:41], v[42:43]
	v_mul_f32_e32 v42, v53, v53
	v_pk_fma_f32 v[42:43], v[52:53], v[52:53], v[42:43] op_sel_hi:[1,1,0]
	v_pk_fma_f32 v[44:45], v[54:55], v[54:55], v[44:45] op_sel_hi:[1,1,0]
	v_mul_f32_e32 v43, v50, v50
	v_mul_f32_e32 v45, v51, v51
	v_pk_add_f32 v[42:43], v[42:43], v[44:45]
	v_pk_mul_f32 v[44:45], v[8:9], v[120:121]
	v_pk_add_f32 v[40:41], v[40:41], v[42:43]
	s_nop 0
	v_add_f32_e32 v40, v40, v41
	ds_bpermute_b32 v41, v112, v40
	v_pk_mul_f32 v[42:43], v[10:11], v[122:123]
	s_waitcnt lgkmcnt(0)
	v_add_f32_e32 v41, v40, v41
	ds_bpermute_b32 v47, v113, v41
	v_cvt_pk_bf16_f32 v40, v44, v45
	s_waitcnt lgkmcnt(0)
	v_add_f32_e32 v41, v41, v47
	ds_bpermute_b32 v46, v114, v41
	s_waitcnt lgkmcnt(0)
	v_add_f32_e32 v46, v41, v46
	ds_bpermute_b32 v121, v115, v46
	v_cvt_pk_bf16_f32 v41, v42, v43
	global_store_dwordx2 v[126:127], v[40:41], off offset:1024
	v_pk_mul_f32 v[40:41], v[14:15], v[110:111]
	s_waitcnt lgkmcnt(0)
	v_add_f32_e32 v110, v46, v121
	ds_bpermute_b32 v111, v116, v110
	v_pk_mul_f32 v[46:47], v[12:13], v[124:125]
	s_waitcnt lgkmcnt(0)
	v_add_f32_e32 v111, v110, v111
	ds_bpermute_b32 v121, v117, v111
	v_cvt_pk_bf16_f32 v110, v46, v47
	s_waitcnt lgkmcnt(0)
; #define LAS __attribute__((address_space(3)))
; __device__ __forceinline__ unsigned pk2(float lo, float hi) { return f2bf(lo) | (f2bf(hi) << 16); }
; __device__ __forceinline__ void phase_prologue(const Params& P, LAS unsigned char* lds) {
;     ...
;         for (int q = 0; q < RP; ++q) {
;             float ss = 0.f;
; #pragma unroll
;             for (int j = 0; j < 4; ++j) ss += (v[q][j][0] * v[q][j][0] + v[q][j][1] * v[q][j][1]) + (v[q][j][2] * v[q][j][2] + v[q][j][3] * v[q][j][3]);
;             const float rstd = 1.0f / sqrtf(wave_sum(ss) * (1.0f / DM) + RMS_EPS);
;             unsigned long long* o8 = (unsigned long long*)(HB + (size_t)(m0 + q * NGW) * DM) + lane;
; #pragma unroll
;             for (int j = 0; j < 4; ++j) { v[q][j] = v[q][j] * rstd * ng[j]; o8[64 * j] = (unsigned long long)pk2(v[q][j][0], v[q][j][1]) | ((unsigned long long)pk2(v[q][j][2], v[q][j][3]) << 32); }
;     ...
;         for (int r = 0; r < 16; ++r) {
;             float sacc[RP];
; #pragma unroll
;             for (int q = 0; q < RP; ++q) sacc[q] = 0.f;
; #pragma unroll
;             for (int j = 0; j < 4; ++j) { const f32x4 wv = *(const LAS f32x4*)(Wl + r * 1024 + 4 * lane + 256 * j);
; #pragma unroll
;                 for (int q = 0; q < RP; ++q) sacc[q] += (v[q][j][0] * wv[0] + v[q][j][1] * wv[1]) + (v[q][j][2] * wv[2] + v[q][j][3] * wv[3]); }
	v_add_f32_e32 v111, v111, v121
	v_fmamk_f32 v111, v111, 0x3a800000, v65
	v_mul_f32_e32 v121, 0x4f800000, v111
	v_cmp_gt_f32_e32 vcc, s16, v111
	s_nop 1
	v_cndmask_b32_e32 v111, v111, v121, vcc
	v_sqrt_f32_e32 v121, v111
	s_nop 0
	v_add_u32_e32 v123, -1, v121
	v_fma_f32 v124, -v123, v121, v111
	v_cmp_ge_f32_e64 s[14:15], 0, v124
	v_add_u32_e32 v124, 1, v121
	s_nop 0
	v_cndmask_b32_e64 v123, v121, v123, s[14:15]
	v_fma_f32 v121, -v124, v121, v111
	v_cmp_lt_f32_e64 s[14:15], 0, v121
	s_nop 1
	v_cndmask_b32_e64 v121, v123, v124, s[14:15]
	v_mul_f32_e32 v123, 0x37800000, v121
	v_cndmask_b32_e32 v121, v121, v123, vcc
	v_cmp_class_f32_e32 vcc, v111, v119
	s_nop 1
	v_cndmask_b32_e32 v121, v121, v111, vcc
	v_div_scale_f32 v123, s[14:15], v121, v121, 1.0
	v_rcp_f32_e32 v124, v123
	v_cvt_pk_bf16_f32 v111, v40, v41
	global_store_dwordx2 v[126:127], v[110:111], off offset:1536
	v_fma_f32 v110, -v123, v124, 1.0
	v_fmac_f32_e32 v124, v110, v124
	v_div_scale_f32 v110, vcc, 1.0, v121, 1.0
	v_mul_f32_e32 v111, v110, v124
	v_fma_f32 v120, -v123, v111, v110
	v_fmac_f32_e32 v111, v120, v124
	v_fma_f32 v110, -v123, v111, v110
	v_div_fmas_f32 v110, v110, v124, v111
	v_div_fixup_f32 v110, v110, v121, 1.0
	v_pk_mul_f32 v[60:61], v[60:61], v[110:111] op_sel_hi:[1,0]
	v_pk_mul_f32 v[122:123], v[54:55], v[110:111] op_sel_hi:[1,0]
	v_pk_mul_f32 v[54:55], v[0:1], v[60:61]
	v_pk_mul_f32 v[124:125], v[48:49], v[110:111] op_sel_hi:[1,0]
	v_pk_mul_f32 v[62:63], v[62:63], v[110:111] op_sel_hi:[1,0]
	v_pk_mul_f32 v[120:121], v[52:53], v[110:111] op_sel_hi:[1,0]
	v_pk_mul_f32 v[52:53], v[2:3], v[62:63]
	v_cvt_pk_bf16_f32 v48, v54, v55
	v_pk_mul_f32 v[56:57], v[56:57], v[110:111] op_sel_hi:[1,0]
	v_pk_mul_f32 v[58:59], v[58:59], v[110:111] op_sel_hi:[1,0]
	v_pk_mul_f32 v[110:111], v[50:51], v[110:111] op_sel_hi:[1,0]
	v_cvt_pk_bf16_f32 v49, v52, v53
	v_lshlrev_b64 v[50:51], 11, v[92:93]
	v_lshl_add_u64 v[126:127], v[70:71], 0, v[50:51]
	v_pk_mul_f32 v[50:51], v[4:5], v[56:57]
	global_store_dwordx2 v[126:127], v[48:49], off
	v_pk_mul_f32 v[48:49], v[6:7], v[58:59]
	v_cvt_pk_bf16_f32 v56, v50, v51
	v_cvt_pk_bf16_f32 v57, v48, v49
	global_store_dwordx2 v[126:127], v[56:57], off offset:512
	s_waitcnt vmcnt(13)
	v_pk_mul_f32 v[56:57], v[30:31], v[30:31]
	v_pk_mul_f32 v[58:59], v[28:29], v[28:29]
	s_nop 0
	v_pk_mov_b32 v[60:61], v[58:59], v[56:57] op_sel:[1,0]
	v_mov_b32_e32 v59, v57
	v_pk_add_f32 v[56:57], v[60:61], v[58:59]
	s_waitcnt vmcnt(12)
	v_pk_mul_f32 v[58:59], v[26:27], v[26:27]
	v_pk_mul_f32 v[60:61], v[24:25], v[24:25]
	v_pk_add_f32 v[56:57], v[56:57], v[56:57] op_sel:[0,1] op_sel_hi:[1,0]
	v_pk_mov_b32 v[62:63], v[60:61], v[58:59] op_sel:[1,0]
	v_mov_b32_e32 v61, v59
	v_pk_add_f32 v[58:59], v[62:63], v[60:61]
	s_waitcnt vmcnt(10)
	v_mul_f32_e32 v57, v16, v16
	v_pk_add_f32 v[58:59], v[58:59], v[58:59] op_sel:[0,1] op_sel_hi:[1,0]
	v_mul_f32_e32 v60, v23, v23
	v_mul_f32_e32 v59, v17, v17
	v_pk_add_f32 v[56:57], v[56:57], v[58:59]
	v_mul_f32_e32 v58, v21, v21
	v_pk_fma_f32 v[58:59], v[20:21], v[20:21], v[58:59] op_sel_hi:[1,1,0]
	v_pk_fma_f32 v[60:61], v[22:23], v[22:23], v[60:61] op_sel_hi:[1,1,0]
	v_mul_f32_e32 v59, v18, v18
	v_mul_f32_e32 v61, v19, v19
	v_pk_add_f32 v[58:59], v[58:59], v[60:61]
	v_pk_mul_f32 v[62:63], v[8:9], v[120:121]
	v_pk_add_f32 v[56:57], v[56:57], v[58:59]
	s_nop 0
	v_add_f32_e32 v56, v56, v57
	ds_bpermute_b32 v57, v112, v56
	v_pk_mul_f32 v[58:59], v[10:11], v[122:123]
	s_waitcnt lgkmcnt(0)
	v_add_f32_e32 v57, v56, v57
	ds_bpermute_b32 v61, v113, v57
	v_cvt_pk_bf16_f32 v56, v62, v63
	s_waitcnt lgkmcnt(0)
	v_add_f32_e32 v57, v57, v61
	ds_bpermute_b32 v60, v114, v57
	s_waitcnt lgkmcnt(0)
	v_add_f32_e32 v60, v57, v60
	ds_bpermute_b32 v121, v115, v60
	v_cvt_pk_bf16_f32 v57, v58, v59
	global_store_dwordx2 v[126:127], v[56:57], off offset:1024
	v_pk_mul_f32 v[56:57], v[14:15], v[110:111]
	s_waitcnt lgkmcnt(0)
	v_add_f32_e32 v110, v60, v121
	ds_bpermute_b32 v111, v116, v110
	v_pk_mul_f32 v[60:61], v[12:13], v[124:125]
	s_waitcnt lgkmcnt(0)
	v_add_f32_e32 v111, v110, v111
	ds_bpermute_b32 v121, v117, v111
	v_cvt_pk_bf16_f32 v110, v60, v61
	s_waitcnt lgkmcnt(0)
	v_add_f32_e32 v111, v111, v121
	v_fmamk_f32 v111, v111, 0x3a800000, v65
	v_mul_f32_e32 v121, 0x4f800000, v111
	v_cmp_gt_f32_e32 vcc, s16, v111
	s_nop 1
	v_cndmask_b32_e32 v111, v111, v121, vcc
	v_sqrt_f32_e32 v121, v111
	s_nop 0
	v_add_u32_e32 v123, -1, v121
	v_fma_f32 v124, -v123, v121, v111
	v_cmp_ge_f32_e64 s[14:15], 0, v124
	v_add_u32_e32 v124, 1, v121
	s_nop 0
	v_cndmask_b32_e64 v123, v121, v123, s[14:15]
	v_fma_f32 v121, -v124, v121, v111
	v_cmp_lt_f32_e64 s[14:15], 0, v121
	s_nop 1
	v_cndmask_b32_e64 v121, v123, v124, s[14:15]
	v_mul_f32_e32 v123, 0x37800000, v121
	v_cndmask_b32_e32 v121, v121, v123, vcc
	v_cmp_class_f32_e32 vcc, v111, v119
	s_nop 1
	v_cndmask_b32_e32 v121, v121, v111, vcc
	v_div_scale_f32 v123, s[14:15], v121, v121, 1.0
	v_rcp_f32_e32 v124, v123
	v_cvt_pk_bf16_f32 v111, v56, v57
	global_store_dwordx2 v[126:127], v[110:111], off offset:1536
	v_fma_f32 v110, -v123, v124, 1.0
	v_fmac_f32_e32 v124, v110, v124
	v_div_scale_f32 v110, vcc, 1.0, v121, 1.0
	v_mul_f32_e32 v111, v110, v124
	v_fma_f32 v120, -v123, v111, v110
	v_fmac_f32_e32 v111, v120, v124
	v_fma_f32 v110, -v123, v111, v110
	v_div_fmas_f32 v110, v110, v124, v111
	v_div_fixup_f32 v110, v110, v121, 1.0
	v_pk_mul_f32 v[120:121], v[28:29], v[110:111] op_sel_hi:[1,0]
	v_pk_mul_f32 v[28:29], v[30:31], v[110:111] op_sel_hi:[1,0]
	v_pk_mul_f32 v[30:31], v[0:1], v[120:121]
	v_pk_mul_f32 v[126:127], v[16:17], v[110:111] op_sel_hi:[1,0]
	v_pk_mul_f32 v[16:17], v[18:19], v[110:111] op_sel_hi:[1,0]
	v_pk_mul_f32 v[28:29], v[2:3], v[28:29]
	v_cvt_pk_bf16_f32 v18, v30, v31
	v_pk_mul_f32 v[124:125], v[20:21], v[110:111] op_sel_hi:[1,0]
	v_pk_mul_f32 v[20:21], v[22:23], v[110:111] op_sel_hi:[1,0]
	v_pk_mul_f32 v[122:123], v[24:25], v[110:111] op_sel_hi:[1,0]
	v_cvt_pk_bf16_f32 v19, v28, v29
	v_lshlrev_b64 v[22:23], 11, v[90:91]
	v_pk_mul_f32 v[24:25], v[26:27], v[110:111] op_sel_hi:[1,0]
	v_lshl_add_u64 v[110:111], v[70:71], 0, v[22:23]
	v_pk_mul_f32 v[26:27], v[4:5], v[122:123]
	global_store_dwordx2 v[110:111], v[18:19], off
	v_pk_mul_f32 v[24:25], v[6:7], v[24:25]
	v_cvt_pk_bf16_f32 v18, v26, v27
	v_cvt_pk_bf16_f32 v19, v24, v25
	v_pk_mul_f32 v[22:23], v[8:9], v[124:125]
	global_store_dwordx2 v[110:111], v[18:19], off offset:512
	v_pk_mul_f32 v[20:21], v[10:11], v[20:21]
	v_cvt_pk_bf16_f32 v18, v22, v23
	v_cvt_pk_bf16_f32 v19, v20, v21
	global_store_dwordx2 v[110:111], v[18:19], off offset:1024
	v_pk_mul_f32 v[18:19], v[12:13], v[126:127]
	v_pk_mul_f32 v[16:17], v[14:15], v[16:17]
	v_cvt_pk_bf16_f32 v124, v18, v19
	ds_read_b128 v[120:123], v118
	v_cvt_pk_bf16_f32 v125, v16, v17
	global_store_dwordx2 v[110:111], v[124:125], off offset:1536
	ds_read_b128 v[124:127], v118 offset:1024
	s_waitcnt lgkmcnt(1)
; #define LAS __attribute__((address_space(3)))
; __device__ __forceinline__ void phase_prologue(const Params& P, LAS unsigned char* lds) {
;     ...
;         for (int r = 0; r < 16; ++r) {
;             float sacc[RP];
; #pragma unroll
;             for (int q = 0; q < RP; ++q) sacc[q] = 0.f;
; #pragma unroll
;             for (int j = 0; j < 4; ++j) { const f32x4 wv = *(const LAS f32x4*)(Wl + r * 1024 + 4 * lane + 256 * j);
; #pragma unroll
;                 for (int q = 0; q < RP; ++q) sacc[q] += (v[q][j][0] * wv[0] + v[q][j][1] * wv[1]) + (v[q][j][2] * wv[2] + v[q][j][3] * wv[3]); }
;             asm volatile("" : "+v"(sacc[0]), "+v"(sacc[1]), "+v"(sacc[2]), "+v"(sacc[3]) :: "memory");
; #pragma unroll
;             for (int q = 0; q < RP; ++q) a[q][r] = sacc[q];
;         }
	v_mul_f32_e32 v110, v109, v121
	v_mul_f32_e32 v111, v107, v123
	v_mul_f32_e32 v128, v39, v121
	v_mul_f32_e32 v129, v37, v123
	v_mul_f32_e32 v130, v55, v121
	v_mul_f32_e32 v131, v53, v123
	v_mul_f32_e32 v132, v121, v31
	v_mul_f32_e32 v133, v123, v29
	v_fmac_f32_e32 v110, v108, v120
	v_fmac_f32_e32 v111, v106, v122
	v_fmac_f32_e32 v128, v38, v120
	v_fmac_f32_e32 v129, v36, v122
	v_fmac_f32_e32 v130, v54, v120
	v_fmac_f32_e32 v131, v52, v122
	v_fmac_f32_e32 v132, v120, v30
	v_fmac_f32_e32 v133, v122, v28
	ds_read_b128 v[120:123], v118 offset:2048
	s_waitcnt lgkmcnt(1)
	v_mul_f32_e32 v134, v105, v125
	v_mul_f32_e32 v135, v103, v127
	v_mul_f32_e32 v136, v35, v125
	v_mul_f32_e32 v137, v33, v127
	v_mul_f32_e32 v138, v51, v125
	v_mul_f32_e32 v139, v49, v127
	v_mul_f32_e32 v140, v125, v27
	v_mul_f32_e32 v141, v127, v25
	v_fmac_f32_e32 v134, v104, v124
	v_fmac_f32_e32 v135, v102, v126
	v_fmac_f32_e32 v136, v34, v124
	v_fmac_f32_e32 v137, v32, v126
	v_fmac_f32_e32 v138, v50, v124
	v_fmac_f32_e32 v139, v48, v126
	v_fmac_f32_e32 v140, v124, v26
	v_fmac_f32_e32 v141, v126, v24
	ds_read_b128 v[124:127], v118 offset:3072
	s_waitcnt lgkmcnt(1)
	v_mul_f32_e32 v142, v97, v121
	v_mul_f32_e32 v144, v45, v121
	v_mul_f32_e32 v146, v63, v121
	v_mul_f32_e32 v121, v121, v23
	v_fmac_f32_e32 v142, v96, v120
	v_mul_f32_e32 v143, v95, v123
	v_fmac_f32_e32 v144, v44, v120
	v_mul_f32_e32 v145, v43, v123
	v_fmac_f32_e32 v146, v62, v120
	v_mul_f32_e32 v147, v59, v123
	v_fmac_f32_e32 v121, v120, v22
	v_mul_f32_e32 v120, v123, v21
	v_fmac_f32_e32 v143, v94, v122
	v_fmac_f32_e32 v145, v42, v122
	v_fmac_f32_e32 v147, v58, v122
	v_fmac_f32_e32 v120, v122, v20
	s_waitcnt lgkmcnt(0)
	v_mul_f32_e32 v122, v101, v125
	v_mul_f32_e32 v148, v47, v125
	v_mul_f32_e32 v150, v61, v125
	v_mul_f32_e32 v125, v125, v19
	v_add_f32_e32 v110, v110, v111
	v_fmac_f32_e32 v122, v100, v124
	v_mul_f32_e32 v123, v99, v127
	v_fmac_f32_e32 v148, v46, v124
	v_mul_f32_e32 v149, v41, v127
	v_fmac_f32_e32 v150, v60, v124
	v_mul_f32_e32 v151, v57, v127
	v_fmac_f32_e32 v125, v124, v18
	v_mul_f32_e32 v124, v127, v17
	v_add_f32_e32 v111, v128, v129
	v_add_f32_e32 v128, v134, v135
	v_add_f32_e32 v110, 0, v110
	v_fmac_f32_e32 v123, v98, v126
	v_fmac_f32_e32 v149, v40, v126
	v_fmac_f32_e32 v151, v56, v126
	v_fmac_f32_e32 v124, v126, v16
	v_add_f32_e32 v126, v130, v131
	v_add_f32_e32 v110, v110, v128
	v_add_f32_e32 v128, v136, v137
	v_add_f32_e32 v111, 0, v111
	v_add_f32_e32 v127, v132, v133
	v_add_f32_e32 v111, v111, v128
	v_add_f32_e32 v128, v138, v139
	v_add_f32_e32 v126, 0, v126
	v_add_f32_e32 v126, v126, v128
	v_add_f32_e32 v128, v140, v141
	v_add_f32_e32 v127, 0, v127
	v_add_f32_e32 v127, v128, v127
	v_add_f32_e32 v128, v142, v143
	v_add_f32_e32 v120, v121, v120
	v_add_f32_e32 v110, v110, v128
	v_add_f32_e32 v128, v144, v145
	v_add_f32_e32 v121, v120, v127
	v_add_f32_e32 v120, v122, v123
	v_add_f32_e32 v111, v111, v128
	v_add_f32_e32 v128, v146, v147
	v_add_f32_e32 v122, v110, v120
	v_add_f32_e32 v110, v148, v149
	v_add_f32_e32 v126, v126, v128
	v_add_f32_e32 v120, v111, v110
	v_add_f32_e32 v110, v150, v151
	v_add_f32_e32 v111, v126, v110
	v_add_f32_e32 v110, v125, v124
	v_add_f32_e32 v110, v110, v121
	ds_read_b128 v[124:127], v118 offset:4096
	ds_read_b128 v[128:131], v118 offset:5120
	s_waitcnt lgkmcnt(1)
	v_mul_f32_e32 v121, v109, v125
	v_mul_f32_e32 v123, v107, v127
	v_mul_f32_e32 v132, v39, v125
	v_mul_f32_e32 v133, v37, v127
	v_mul_f32_e32 v134, v55, v125
	v_mul_f32_e32 v135, v53, v127
	v_mul_f32_e32 v136, v125, v31
	v_mul_f32_e32 v137, v127, v29
	v_fmac_f32_e32 v121, v108, v124
	v_fmac_f32_e32 v123, v106, v126
	v_fmac_f32_e32 v132, v38, v124
	v_fmac_f32_e32 v133, v36, v126
	v_fmac_f32_e32 v134, v54, v124
	v_fmac_f32_e32 v135, v52, v126
	v_fmac_f32_e32 v136, v124, v30
	v_fmac_f32_e32 v137, v126, v28
	ds_read_b128 v[124:127], v118 offset:6144
	s_waitcnt lgkmcnt(1)
	v_mul_f32_e32 v138, v105, v129
	v_mul_f32_e32 v139, v103, v131
	v_mul_f32_e32 v140, v35, v129
	v_mul_f32_e32 v141, v33, v131
	v_mul_f32_e32 v142, v51, v129
	v_mul_f32_e32 v143, v49, v131
	v_mul_f32_e32 v144, v27, v129
	v_mul_f32_e32 v145, v25, v131
	v_fmac_f32_e32 v138, v104, v128
	v_fmac_f32_e32 v139, v102, v130
	v_fmac_f32_e32 v140, v34, v128
	v_fmac_f32_e32 v141, v32, v130
	v_fmac_f32_e32 v142, v50, v128
	v_fmac_f32_e32 v143, v48, v130
	v_fmac_f32_e32 v144, v26, v128
	v_fmac_f32_e32 v145, v24, v130
	ds_read_b128 v[128:131], v118 offset:7168
	s_waitcnt lgkmcnt(1)
	v_mul_f32_e32 v146, v97, v125
	v_mul_f32_e32 v148, v45, v125
	v_mul_f32_e32 v150, v63, v125
	v_mul_f32_e32 v125, v23, v125
	v_fmac_f32_e32 v146, v96, v124
	v_mul_f32_e32 v147, v95, v127
	v_fmac_f32_e32 v148, v44, v124
	v_mul_f32_e32 v149, v43, v127
	v_fmac_f32_e32 v150, v62, v124
	v_mul_f32_e32 v151, v59, v127
	v_fmac_f32_e32 v125, v22, v124
	v_mul_f32_e32 v124, v21, v127
	v_fmac_f32_e32 v147, v94, v126
	v_fmac_f32_e32 v149, v42, v126
	v_fmac_f32_e32 v151, v58, v126
	v_fmac_f32_e32 v124, v20, v126
	s_waitcnt lgkmcnt(0)
; #define LAS __attribute__((address_space(3)))
; __device__ __forceinline__ void phase_prologue(const Params& P, LAS unsigned char* lds) {
;     ...
;         for (int r = 0; r < 16; ++r) {
;             float sacc[RP];
; #pragma unroll
;             for (int q = 0; q < RP; ++q) sacc[q] = 0.f;
; #pragma unroll
;             for (int j = 0; j < 4; ++j) { const f32x4 wv = *(const LAS f32x4*)(Wl + r * 1024 + 4 * lane + 256 * j);
; #pragma unroll
;                 for (int q = 0; q < RP; ++q) sacc[q] += (v[q][j][0] * wv[0] + v[q][j][1] * wv[1]) + (v[q][j][2] * wv[2] + v[q][j][3] * wv[3]); }
;             asm volatile("" : "+v"(sacc[0]), "+v"(sacc[1]), "+v"(sacc[2]), "+v"(sacc[3]) :: "memory");
; #pragma unroll
;             for (int q = 0; q < RP; ++q) a[q][r] = sacc[q];
;         }
	v_mul_f32_e32 v126, v101, v129
	v_mul_f32_e32 v152, v47, v129
	v_mul_f32_e32 v154, v61, v129
	v_mul_f32_e32 v129, v19, v129
	v_add_f32_e32 v121, v121, v123
	v_fmac_f32_e32 v126, v100, v128
	v_mul_f32_e32 v127, v99, v131
	v_fmac_f32_e32 v152, v46, v128
	v_mul_f32_e32 v153, v41, v131
	v_fmac_f32_e32 v154, v60, v128
	v_mul_f32_e32 v155, v57, v131
	v_fmac_f32_e32 v129, v18, v128
	v_mul_f32_e32 v128, v17, v131
	v_add_f32_e32 v123, v132, v133
	v_add_f32_e32 v132, v138, v139
	v_add_f32_e32 v121, 0, v121
	v_fmac_f32_e32 v127, v98, v130
	v_fmac_f32_e32 v153, v40, v130
	v_fmac_f32_e32 v155, v56, v130
	v_fmac_f32_e32 v128, v16, v130
	v_add_f32_e32 v130, v134, v135
	v_add_f32_e32 v121, v121, v132
	v_add_f32_e32 v132, v140, v141
	v_add_f32_e32 v123, 0, v123
	v_add_f32_e32 v131, v136, v137
	v_add_f32_e32 v123, v123, v132
	v_add_f32_e32 v132, v142, v143
	v_add_f32_e32 v130, 0, v130
	v_add_f32_e32 v130, v130, v132
	v_add_f32_e32 v132, v144, v145
	v_add_f32_e32 v131, 0, v131
	v_add_f32_e32 v131, v131, v132
	v_add_f32_e32 v132, v146, v147
	v_add_f32_e32 v124, v125, v124
	v_add_f32_e32 v121, v121, v132
	v_add_f32_e32 v132, v148, v149
	v_add_f32_e32 v125, v131, v124
	v_add_f32_e32 v124, v126, v127
	v_add_f32_e32 v123, v123, v132
	v_add_f32_e32 v132, v150, v151
	v_add_f32_e32 v126, v121, v124
	v_add_f32_e32 v121, v152, v153
	v_add_f32_e32 v130, v130, v132
	v_add_f32_e32 v124, v123, v121
	v_add_f32_e32 v121, v154, v155
	v_add_f32_e32 v123, v130, v121
	v_add_f32_e32 v121, v129, v128
	v_add_f32_e32 v121, v125, v121
	ds_read_b128 v[128:131], v118 offset:8192
	ds_read_b128 v[132:135], v118 offset:9216
	s_waitcnt lgkmcnt(1)
	v_mul_f32_e32 v125, v109, v129
	v_mul_f32_e32 v127, v107, v131
	v_mul_f32_e32 v136, v39, v129
	v_mul_f32_e32 v137, v37, v131
	v_mul_f32_e32 v138, v55, v129
	v_mul_f32_e32 v139, v53, v131
	v_mul_f32_e32 v140, v31, v129
	v_mul_f32_e32 v141, v29, v131
	v_fmac_f32_e32 v125, v108, v128
	v_fmac_f32_e32 v127, v106, v130
	v_fmac_f32_e32 v136, v38, v128
	v_fmac_f32_e32 v137, v36, v130
	v_fmac_f32_e32 v138, v54, v128
	v_fmac_f32_e32 v139, v52, v130
	v_fmac_f32_e32 v140, v30, v128
	v_fmac_f32_e32 v141, v28, v130
	ds_read_b128 v[128:131], v118 offset:10240
	s_waitcnt lgkmcnt(1)
	v_mul_f32_e32 v142, v105, v133
	v_mul_f32_e32 v143, v103, v135
	v_mul_f32_e32 v144, v35, v133
	v_mul_f32_e32 v145, v33, v135
	v_mul_f32_e32 v146, v51, v133
	v_mul_f32_e32 v147, v49, v135
	v_mul_f32_e32 v148, v27, v133
	v_mul_f32_e32 v149, v25, v135
	v_fmac_f32_e32 v142, v104, v132
	v_fmac_f32_e32 v143, v102, v134
	v_fmac_f32_e32 v144, v34, v132
	v_fmac_f32_e32 v145, v32, v134
	v_fmac_f32_e32 v146, v50, v132
	v_fmac_f32_e32 v147, v48, v134
	v_fmac_f32_e32 v148, v26, v132
	v_fmac_f32_e32 v149, v24, v134
	ds_read_b128 v[132:135], v118 offset:11264
	s_waitcnt lgkmcnt(1)
	v_mul_f32_e32 v150, v97, v129
	v_mul_f32_e32 v152, v45, v129
	v_mul_f32_e32 v154, v63, v129
	v_mul_f32_e32 v129, v23, v129
	v_fmac_f32_e32 v150, v96, v128
	v_mul_f32_e32 v151, v95, v131
	v_fmac_f32_e32 v152, v44, v128
	v_mul_f32_e32 v153, v43, v131
	v_fmac_f32_e32 v154, v62, v128
	v_mul_f32_e32 v155, v59, v131
	v_fmac_f32_e32 v129, v22, v128
	v_mul_f32_e32 v128, v21, v131
	v_fmac_f32_e32 v151, v94, v130
	v_fmac_f32_e32 v153, v42, v130
	v_fmac_f32_e32 v155, v58, v130
	v_fmac_f32_e32 v128, v20, v130
	s_waitcnt lgkmcnt(0)
	v_mul_f32_e32 v130, v101, v133
	v_mul_f32_e32 v156, v47, v133
	v_mul_f32_e32 v158, v61, v133
	v_mul_f32_e32 v133, v19, v133
	v_add_f32_e32 v125, v125, v127
	v_fmac_f32_e32 v130, v100, v132
	v_mul_f32_e32 v131, v99, v135
	v_fmac_f32_e32 v156, v46, v132
	v_mul_f32_e32 v157, v41, v135
	v_fmac_f32_e32 v158, v60, v132
	v_mul_f32_e32 v159, v57, v135
	v_fmac_f32_e32 v133, v18, v132
	v_mul_f32_e32 v132, v17, v135
	v_add_f32_e32 v127, v136, v137
	v_add_f32_e32 v136, v142, v143
	v_add_f32_e32 v125, 0, v125
	v_fmac_f32_e32 v131, v98, v134
	v_fmac_f32_e32 v157, v40, v134
	v_fmac_f32_e32 v159, v56, v134
	v_fmac_f32_e32 v132, v16, v134
	v_add_f32_e32 v134, v138, v139
	v_add_f32_e32 v125, v125, v136
	v_add_f32_e32 v136, v144, v145
	v_add_f32_e32 v127, 0, v127
	v_add_f32_e32 v135, v140, v141
	v_add_f32_e32 v127, v127, v136
	v_add_f32_e32 v136, v146, v147
	v_add_f32_e32 v134, 0, v134
	v_add_f32_e32 v134, v134, v136
	v_add_f32_e32 v136, v148, v149
	v_add_f32_e32 v135, 0, v135
	v_add_f32_e32 v135, v135, v136
	v_add_f32_e32 v136, v150, v151
	v_add_f32_e32 v128, v129, v128
	v_add_f32_e32 v125, v125, v136
	v_add_f32_e32 v136, v152, v153
	v_add_f32_e32 v129, v135, v128
	v_add_f32_e32 v128, v130, v131
	v_add_f32_e32 v127, v127, v136
	v_add_f32_e32 v136, v154, v155
	v_add_f32_e32 v130, v125, v128
	v_add_f32_e32 v125, v156, v157
	v_add_f32_e32 v134, v134, v136
	v_add_f32_e32 v128, v127, v125
	v_add_f32_e32 v125, v158, v159
	v_add_f32_e32 v127, v134, v125
	v_add_f32_e32 v125, v133, v132
	v_add_f32_e32 v125, v129, v125
	ds_read_b128 v[132:135], v118 offset:12288
	ds_read_b128 v[136:139], v118 offset:13312
	s_waitcnt lgkmcnt(1)
	v_mul_f32_e32 v129, v109, v133
	v_mul_f32_e32 v131, v107, v135
	v_mul_f32_e32 v140, v39, v133
	v_mul_f32_e32 v141, v37, v135
	v_mul_f32_e32 v142, v55, v133
	v_mul_f32_e32 v143, v53, v135
	v_mul_f32_e32 v144, v31, v133
	v_mul_f32_e32 v145, v29, v135
	v_fmac_f32_e32 v129, v108, v132
	v_fmac_f32_e32 v131, v106, v134
	v_fmac_f32_e32 v140, v38, v132
	v_fmac_f32_e32 v141, v36, v134
	v_fmac_f32_e32 v142, v54, v132
	v_fmac_f32_e32 v143, v52, v134
	v_fmac_f32_e32 v144, v30, v132
	v_fmac_f32_e32 v145, v28, v134
	ds_read_b128 v[132:135], v118 offset:14336
	s_waitcnt lgkmcnt(1)
; #define LAS __attribute__((address_space(3)))
; __device__ __forceinline__ void phase_prologue(const Params& P, LAS unsigned char* lds) {
;     ...
;         for (int r = 0; r < 16; ++r) {
;             float sacc[RP];
; #pragma unroll
;             for (int q = 0; q < RP; ++q) sacc[q] = 0.f;
; #pragma unroll
;             for (int j = 0; j < 4; ++j) { const f32x4 wv = *(const LAS f32x4*)(Wl + r * 1024 + 4 * lane + 256 * j);
; #pragma unroll
;                 for (int q = 0; q < RP; ++q) sacc[q] += (v[q][j][0] * wv[0] + v[q][j][1] * wv[1]) + (v[q][j][2] * wv[2] + v[q][j][3] * wv[3]); }
;             asm volatile("" : "+v"(sacc[0]), "+v"(sacc[1]), "+v"(sacc[2]), "+v"(sacc[3]) :: "memory");
; #pragma unroll
;             for (int q = 0; q < RP; ++q) a[q][r] = sacc[q];
;         }
	v_mul_f32_e32 v146, v105, v137
	v_mul_f32_e32 v147, v103, v139
	v_mul_f32_e32 v148, v35, v137
	v_mul_f32_e32 v149, v33, v139
	v_mul_f32_e32 v150, v51, v137
	v_mul_f32_e32 v151, v49, v139
	v_mul_f32_e32 v152, v27, v137
	v_mul_f32_e32 v153, v25, v139
	v_fmac_f32_e32 v146, v104, v136
	v_fmac_f32_e32 v147, v102, v138
	v_fmac_f32_e32 v148, v34, v136
	v_fmac_f32_e32 v149, v32, v138
	v_fmac_f32_e32 v150, v50, v136
	v_fmac_f32_e32 v151, v48, v138
	v_fmac_f32_e32 v152, v26, v136
	v_fmac_f32_e32 v153, v24, v138
	ds_read_b128 v[136:139], v118 offset:15360
	s_waitcnt lgkmcnt(1)
	v_mul_f32_e32 v154, v97, v133
	v_mul_f32_e32 v156, v45, v133
	v_mul_f32_e32 v158, v63, v133
	v_mul_f32_e32 v133, v23, v133
	v_fmac_f32_e32 v154, v96, v132
	v_mul_f32_e32 v155, v95, v135
	v_fmac_f32_e32 v156, v44, v132
	v_mul_f32_e32 v157, v43, v135
	v_fmac_f32_e32 v158, v62, v132
	v_mul_f32_e32 v159, v59, v135
	v_fmac_f32_e32 v133, v22, v132
	v_mul_f32_e32 v132, v21, v135
	v_fmac_f32_e32 v155, v94, v134
	v_fmac_f32_e32 v157, v42, v134
	v_fmac_f32_e32 v159, v58, v134
	v_fmac_f32_e32 v132, v20, v134
	s_waitcnt lgkmcnt(0)
	v_mul_f32_e32 v134, v101, v137
	v_mul_f32_e32 v160, v47, v137
	v_mul_f32_e32 v162, v61, v137
	v_mul_f32_e32 v137, v19, v137
	v_add_f32_e32 v129, v129, v131
	v_fmac_f32_e32 v134, v100, v136
	v_mul_f32_e32 v135, v99, v139
	v_fmac_f32_e32 v160, v46, v136
	v_mul_f32_e32 v161, v41, v139
	v_fmac_f32_e32 v162, v60, v136
	v_mul_f32_e32 v163, v57, v139
	v_fmac_f32_e32 v137, v18, v136
	v_mul_f32_e32 v136, v17, v139
	v_add_f32_e32 v131, v140, v141
	v_add_f32_e32 v140, v146, v147
	v_add_f32_e32 v129, 0, v129
	v_fmac_f32_e32 v135, v98, v138
	v_fmac_f32_e32 v161, v40, v138
	v_fmac_f32_e32 v163, v56, v138
	v_fmac_f32_e32 v136, v16, v138
	v_add_f32_e32 v138, v142, v143
	v_add_f32_e32 v129, v129, v140
	v_add_f32_e32 v140, v148, v149
	v_add_f32_e32 v131, 0, v131
	v_add_f32_e32 v139, v144, v145
	v_add_f32_e32 v131, v131, v140
	v_add_f32_e32 v140, v150, v151
	v_add_f32_e32 v138, 0, v138
	v_add_f32_e32 v138, v138, v140
	v_add_f32_e32 v140, v152, v153
	v_add_f32_e32 v139, 0, v139
	v_add_f32_e32 v139, v139, v140
	v_add_f32_e32 v140, v154, v155
	v_add_f32_e32 v132, v133, v132
	v_add_f32_e32 v129, v129, v140
	v_add_f32_e32 v140, v156, v157
	v_add_f32_e32 v133, v139, v132
	v_add_f32_e32 v132, v134, v135
	v_add_f32_e32 v131, v131, v140
	v_add_f32_e32 v140, v158, v159
	v_add_f32_e32 v134, v129, v132
	v_add_f32_e32 v129, v160, v161
	v_add_f32_e32 v138, v138, v140
	v_add_f32_e32 v132, v131, v129
	v_add_f32_e32 v129, v162, v163
	v_add_f32_e32 v131, v138, v129
	v_add_f32_e32 v129, v137, v136
	v_add_f32_e32 v129, v133, v129
	ds_read_b128 v[136:139], v118 offset:16384
	ds_read_b128 v[140:143], v118 offset:17408
	s_waitcnt lgkmcnt(1)
	v_mul_f32_e32 v133, v109, v137
	v_mul_f32_e32 v135, v107, v139
	v_mul_f32_e32 v144, v39, v137
	v_mul_f32_e32 v145, v37, v139
	v_mul_f32_e32 v146, v55, v137
	v_mul_f32_e32 v147, v53, v139
	v_mul_f32_e32 v148, v31, v137
	v_mul_f32_e32 v149, v29, v139
	v_fmac_f32_e32 v133, v108, v136
	v_fmac_f32_e32 v135, v106, v138
	v_fmac_f32_e32 v144, v38, v136
	v_fmac_f32_e32 v145, v36, v138
	v_fmac_f32_e32 v146, v54, v136
	v_fmac_f32_e32 v147, v52, v138
	v_fmac_f32_e32 v148, v30, v136
	v_fmac_f32_e32 v149, v28, v138
	ds_read_b128 v[136:139], v118 offset:18432
	s_waitcnt lgkmcnt(1)
	v_mul_f32_e32 v150, v105, v141
	v_mul_f32_e32 v151, v103, v143
	v_mul_f32_e32 v152, v35, v141
	v_mul_f32_e32 v153, v33, v143
	v_mul_f32_e32 v154, v51, v141
	v_mul_f32_e32 v155, v49, v143
	v_mul_f32_e32 v156, v27, v141
	v_mul_f32_e32 v157, v25, v143
	v_fmac_f32_e32 v150, v104, v140
	v_fmac_f32_e32 v151, v102, v142
	v_fmac_f32_e32 v152, v34, v140
	v_fmac_f32_e32 v153, v32, v142
	v_fmac_f32_e32 v154, v50, v140
	v_fmac_f32_e32 v155, v48, v142
	v_fmac_f32_e32 v156, v26, v140
	v_fmac_f32_e32 v157, v24, v142
	ds_read_b128 v[140:143], v118 offset:19456
	s_waitcnt lgkmcnt(1)
	v_mul_f32_e32 v158, v97, v137
	v_mul_f32_e32 v160, v45, v137
	v_mul_f32_e32 v162, v63, v137
	v_mul_f32_e32 v137, v23, v137
	v_fmac_f32_e32 v158, v96, v136
	v_mul_f32_e32 v159, v95, v139
	v_fmac_f32_e32 v160, v44, v136
	v_mul_f32_e32 v161, v43, v139
	v_fmac_f32_e32 v162, v62, v136
	v_mul_f32_e32 v163, v59, v139
	v_fmac_f32_e32 v137, v22, v136
	v_mul_f32_e32 v136, v21, v139
	v_fmac_f32_e32 v159, v94, v138
	v_fmac_f32_e32 v161, v42, v138
	v_fmac_f32_e32 v163, v58, v138
	v_fmac_f32_e32 v136, v20, v138
	s_waitcnt lgkmcnt(0)
	v_mul_f32_e32 v138, v101, v141
	v_mul_f32_e32 v164, v47, v141
	v_mul_f32_e32 v166, v61, v141
	v_mul_f32_e32 v141, v19, v141
	v_add_f32_e32 v133, v133, v135
	v_fmac_f32_e32 v138, v100, v140
	v_mul_f32_e32 v139, v99, v143
	v_fmac_f32_e32 v164, v46, v140
	v_mul_f32_e32 v165, v41, v143
	v_fmac_f32_e32 v166, v60, v140
	v_mul_f32_e32 v167, v57, v143
	v_fmac_f32_e32 v141, v18, v140
	v_mul_f32_e32 v140, v17, v143
	v_add_f32_e32 v135, v144, v145
	v_add_f32_e32 v144, v150, v151
	v_add_f32_e32 v133, 0, v133
	v_fmac_f32_e32 v139, v98, v142
	v_fmac_f32_e32 v165, v40, v142
	v_fmac_f32_e32 v167, v56, v142
	v_fmac_f32_e32 v140, v16, v142
	v_add_f32_e32 v142, v146, v147
	v_add_f32_e32 v133, v133, v144
	v_add_f32_e32 v144, v152, v153
	v_add_f32_e32 v135, 0, v135
	v_add_f32_e32 v143, v148, v149
	v_add_f32_e32 v135, v135, v144
	v_add_f32_e32 v144, v154, v155
	v_add_f32_e32 v142, 0, v142
	v_add_f32_e32 v142, v142, v144
	v_add_f32_e32 v144, v156, v157
	v_add_f32_e32 v143, 0, v143
	v_add_f32_e32 v143, v143, v144
	v_add_f32_e32 v144, v158, v159
	v_add_f32_e32 v136, v137, v136
	v_add_f32_e32 v133, v133, v144
	v_add_f32_e32 v144, v160, v161
	v_add_f32_e32 v137, v143, v136
	v_add_f32_e32 v136, v138, v139
	v_add_f32_e32 v135, v135, v144
	v_add_f32_e32 v144, v162, v163
	v_add_f32_e32 v138, v133, v136
	v_add_f32_e32 v133, v164, v165
	v_add_f32_e32 v142, v142, v144
	v_add_f32_e32 v136, v135, v133
	v_add_f32_e32 v133, v166, v167
	v_add_f32_e32 v135, v142, v133
	v_add_f32_e32 v133, v141, v140
	v_add_f32_e32 v133, v137, v133
	ds_read_b128 v[140:143], v118 offset:20480
	ds_read_b128 v[144:147], v118 offset:21504
	s_waitcnt lgkmcnt(1)
; #define LAS __attribute__((address_space(3)))
; __device__ __forceinline__ void phase_prologue(const Params& P, LAS unsigned char* lds) {
;     ...
;         for (int r = 0; r < 16; ++r) {
;             float sacc[RP];
; #pragma unroll
;             for (int q = 0; q < RP; ++q) sacc[q] = 0.f;
; #pragma unroll
;             for (int j = 0; j < 4; ++j) { const f32x4 wv = *(const LAS f32x4*)(Wl + r * 1024 + 4 * lane + 256 * j);
; #pragma unroll
;                 for (int q = 0; q < RP; ++q) sacc[q] += (v[q][j][0] * wv[0] + v[q][j][1] * wv[1]) + (v[q][j][2] * wv[2] + v[q][j][3] * wv[3]); }
;             asm volatile("" : "+v"(sacc[0]), "+v"(sacc[1]), "+v"(sacc[2]), "+v"(sacc[3]) :: "memory");
; #pragma unroll
;             for (int q = 0; q < RP; ++q) a[q][r] = sacc[q];
;         }
	v_mul_f32_e32 v137, v109, v141
	v_mul_f32_e32 v139, v107, v143
	v_mul_f32_e32 v148, v39, v141
	v_mul_f32_e32 v149, v37, v143
	v_mul_f32_e32 v150, v55, v141
	v_mul_f32_e32 v151, v53, v143
	v_mul_f32_e32 v152, v31, v141
	v_mul_f32_e32 v153, v29, v143
	v_fmac_f32_e32 v137, v108, v140
	v_fmac_f32_e32 v139, v106, v142
	v_fmac_f32_e32 v148, v38, v140
	v_fmac_f32_e32 v149, v36, v142
	v_fmac_f32_e32 v150, v54, v140
	v_fmac_f32_e32 v151, v52, v142
	v_fmac_f32_e32 v152, v30, v140
	v_fmac_f32_e32 v153, v28, v142
	ds_read_b128 v[140:143], v118 offset:22528
	s_waitcnt lgkmcnt(1)
	v_mul_f32_e32 v154, v105, v145
	v_mul_f32_e32 v155, v103, v147
	v_mul_f32_e32 v156, v35, v145
	v_mul_f32_e32 v157, v33, v147
	v_mul_f32_e32 v158, v51, v145
	v_mul_f32_e32 v159, v49, v147
	v_mul_f32_e32 v160, v27, v145
	v_mul_f32_e32 v161, v25, v147
	v_fmac_f32_e32 v154, v104, v144
	v_fmac_f32_e32 v155, v102, v146
	v_fmac_f32_e32 v156, v34, v144
	v_fmac_f32_e32 v157, v32, v146
	v_fmac_f32_e32 v158, v50, v144
	v_fmac_f32_e32 v159, v48, v146
	v_fmac_f32_e32 v160, v26, v144
	v_fmac_f32_e32 v161, v24, v146
	ds_read_b128 v[144:147], v118 offset:23552
	s_waitcnt lgkmcnt(1)
	v_mul_f32_e32 v162, v97, v141
	v_mul_f32_e32 v164, v45, v141
	v_mul_f32_e32 v166, v63, v141
	v_mul_f32_e32 v141, v23, v141
	v_fmac_f32_e32 v162, v96, v140
	v_mul_f32_e32 v163, v95, v143
	v_fmac_f32_e32 v164, v44, v140
	v_mul_f32_e32 v165, v43, v143
	v_fmac_f32_e32 v166, v62, v140
	v_mul_f32_e32 v167, v59, v143
	v_fmac_f32_e32 v141, v22, v140
	v_mul_f32_e32 v140, v21, v143
	v_fmac_f32_e32 v163, v94, v142
	v_fmac_f32_e32 v165, v42, v142
	v_fmac_f32_e32 v167, v58, v142
	v_fmac_f32_e32 v140, v20, v142
	s_waitcnt lgkmcnt(0)
	v_mul_f32_e32 v142, v101, v145
	v_mul_f32_e32 v168, v47, v145
	v_mul_f32_e32 v170, v61, v145
	v_mul_f32_e32 v145, v19, v145
	v_add_f32_e32 v137, v137, v139
	v_fmac_f32_e32 v142, v100, v144
	v_mul_f32_e32 v143, v99, v147
	v_fmac_f32_e32 v168, v46, v144
	v_mul_f32_e32 v169, v41, v147
	v_fmac_f32_e32 v170, v60, v144
	v_mul_f32_e32 v171, v57, v147
	v_fmac_f32_e32 v145, v18, v144
	v_mul_f32_e32 v144, v17, v147
	v_add_f32_e32 v139, v148, v149
	v_add_f32_e32 v148, v154, v155
	v_add_f32_e32 v137, 0, v137
	v_fmac_f32_e32 v143, v98, v146
	v_fmac_f32_e32 v169, v40, v146
	v_fmac_f32_e32 v171, v56, v146
	v_fmac_f32_e32 v144, v16, v146
	v_add_f32_e32 v146, v150, v151
	v_add_f32_e32 v137, v137, v148
	v_add_f32_e32 v148, v156, v157
	v_add_f32_e32 v139, 0, v139
	v_add_f32_e32 v147, v152, v153
	v_add_f32_e32 v139, v139, v148
	v_add_f32_e32 v148, v158, v159
	v_add_f32_e32 v146, 0, v146
	v_add_f32_e32 v146, v146, v148
	v_add_f32_e32 v148, v160, v161
	v_add_f32_e32 v147, 0, v147
	v_add_f32_e32 v147, v147, v148
	v_add_f32_e32 v148, v162, v163
	v_add_f32_e32 v140, v141, v140
	v_add_f32_e32 v137, v137, v148
	v_add_f32_e32 v148, v164, v165
	v_add_f32_e32 v141, v147, v140
	v_add_f32_e32 v140, v142, v143
	v_add_f32_e32 v139, v139, v148
	v_add_f32_e32 v148, v166, v167
	v_add_f32_e32 v142, v137, v140
	v_add_f32_e32 v137, v168, v169
	v_add_f32_e32 v146, v146, v148
	v_add_f32_e32 v140, v139, v137
	v_add_f32_e32 v137, v170, v171
	v_add_f32_e32 v139, v146, v137
	v_add_f32_e32 v137, v145, v144
	v_add_f32_e32 v137, v141, v137
	ds_read_b128 v[144:147], v118 offset:24576
	ds_read_b128 v[148:151], v118 offset:25600
	s_waitcnt lgkmcnt(1)
	v_mul_f32_e32 v141, v109, v145
	v_mul_f32_e32 v143, v107, v147
	v_mul_f32_e32 v152, v39, v145
	v_mul_f32_e32 v153, v37, v147
	v_mul_f32_e32 v154, v55, v145
	v_mul_f32_e32 v155, v53, v147
	v_mul_f32_e32 v156, v31, v145
	v_mul_f32_e32 v157, v29, v147
	v_fmac_f32_e32 v141, v108, v144
	v_fmac_f32_e32 v143, v106, v146
	v_fmac_f32_e32 v152, v38, v144
	v_fmac_f32_e32 v153, v36, v146
	v_fmac_f32_e32 v154, v54, v144
	v_fmac_f32_e32 v155, v52, v146
	v_fmac_f32_e32 v156, v30, v144
	v_fmac_f32_e32 v157, v28, v146
	ds_read_b128 v[144:147], v118 offset:26624
	s_waitcnt lgkmcnt(1)
	v_mul_f32_e32 v158, v105, v149
	v_mul_f32_e32 v159, v103, v151
	v_mul_f32_e32 v160, v35, v149
	v_mul_f32_e32 v161, v33, v151
	v_mul_f32_e32 v162, v51, v149
	v_mul_f32_e32 v163, v49, v151
	v_mul_f32_e32 v164, v27, v149
	v_mul_f32_e32 v165, v25, v151
	v_fmac_f32_e32 v158, v104, v148
	v_fmac_f32_e32 v159, v102, v150
	v_fmac_f32_e32 v160, v34, v148
	v_fmac_f32_e32 v161, v32, v150
	v_fmac_f32_e32 v162, v50, v148
	v_fmac_f32_e32 v163, v48, v150
	v_fmac_f32_e32 v164, v26, v148
	v_fmac_f32_e32 v165, v24, v150
	ds_read_b128 v[148:151], v118 offset:27648
	s_waitcnt lgkmcnt(1)
	v_mul_f32_e32 v166, v97, v145
	v_mul_f32_e32 v168, v45, v145
	v_mul_f32_e32 v170, v63, v145
	v_mul_f32_e32 v145, v23, v145
	v_fmac_f32_e32 v166, v96, v144
	v_mul_f32_e32 v167, v95, v147
	v_fmac_f32_e32 v168, v44, v144
	v_mul_f32_e32 v169, v43, v147
	v_fmac_f32_e32 v170, v62, v144
	v_mul_f32_e32 v171, v59, v147
	v_fmac_f32_e32 v145, v22, v144
	v_mul_f32_e32 v144, v21, v147
	v_fmac_f32_e32 v167, v94, v146
	v_fmac_f32_e32 v169, v42, v146
	v_fmac_f32_e32 v171, v58, v146
	v_fmac_f32_e32 v144, v20, v146
	s_waitcnt lgkmcnt(0)
; #define LAS __attribute__((address_space(3)))
; __device__ __forceinline__ void phase_prologue(const Params& P, LAS unsigned char* lds) {
;     ...
;         for (int r = 0; r < 16; ++r) {
;             float sacc[RP];
; #pragma unroll
;             for (int q = 0; q < RP; ++q) sacc[q] = 0.f;
; #pragma unroll
;             for (int j = 0; j < 4; ++j) { const f32x4 wv = *(const LAS f32x4*)(Wl + r * 1024 + 4 * lane + 256 * j);
; #pragma unroll
;                 for (int q = 0; q < RP; ++q) sacc[q] += (v[q][j][0] * wv[0] + v[q][j][1] * wv[1]) + (v[q][j][2] * wv[2] + v[q][j][3] * wv[3]); }
;             asm volatile("" : "+v"(sacc[0]), "+v"(sacc[1]), "+v"(sacc[2]), "+v"(sacc[3]) :: "memory");
; #pragma unroll
;             for (int q = 0; q < RP; ++q) a[q][r] = sacc[q];
;         }
	v_mul_f32_e32 v146, v101, v149
	v_mul_f32_e32 v172, v47, v149
	v_mul_f32_e32 v174, v61, v149
	v_mul_f32_e32 v149, v19, v149
	v_add_f32_e32 v141, v141, v143
	v_fmac_f32_e32 v146, v100, v148
	v_mul_f32_e32 v147, v99, v151
	v_fmac_f32_e32 v172, v46, v148
	v_mul_f32_e32 v173, v41, v151
	v_fmac_f32_e32 v174, v60, v148
	v_mul_f32_e32 v175, v57, v151
	v_fmac_f32_e32 v149, v18, v148
	v_mul_f32_e32 v148, v17, v151
	v_add_f32_e32 v143, v152, v153
	v_add_f32_e32 v152, v158, v159
	v_add_f32_e32 v141, 0, v141
	v_fmac_f32_e32 v147, v98, v150
	v_fmac_f32_e32 v173, v40, v150
	v_fmac_f32_e32 v175, v56, v150
	v_fmac_f32_e32 v148, v16, v150
	v_add_f32_e32 v150, v154, v155
	v_add_f32_e32 v141, v141, v152
	v_add_f32_e32 v152, v160, v161
	v_add_f32_e32 v143, 0, v143
	v_add_f32_e32 v151, v156, v157
	v_add_f32_e32 v143, v143, v152
	v_add_f32_e32 v152, v162, v163
	v_add_f32_e32 v150, 0, v150
	v_add_f32_e32 v150, v150, v152
	v_add_f32_e32 v152, v164, v165
	v_add_f32_e32 v151, 0, v151
	v_add_f32_e32 v151, v151, v152
	v_add_f32_e32 v152, v166, v167
	v_add_f32_e32 v144, v145, v144
	v_add_f32_e32 v141, v141, v152
	v_add_f32_e32 v152, v168, v169
	v_add_f32_e32 v145, v151, v144
	v_add_f32_e32 v144, v146, v147
	v_add_f32_e32 v143, v143, v152
	v_add_f32_e32 v152, v170, v171
	v_add_f32_e32 v146, v141, v144
	v_add_f32_e32 v141, v172, v173
	v_add_f32_e32 v150, v150, v152
	v_add_f32_e32 v144, v143, v141
	v_add_f32_e32 v141, v174, v175
	v_add_f32_e32 v143, v150, v141
	v_add_f32_e32 v141, v149, v148
	v_add_f32_e32 v141, v145, v141
	ds_read_b128 v[148:151], v118 offset:28672
	ds_read_b128 v[152:155], v118 offset:29696
	s_waitcnt lgkmcnt(1)
	v_mul_f32_e32 v145, v109, v149
	v_mul_f32_e32 v147, v107, v151
	v_mul_f32_e32 v156, v39, v149
	v_mul_f32_e32 v157, v37, v151
	v_mul_f32_e32 v158, v55, v149
	v_mul_f32_e32 v159, v53, v151
	v_mul_f32_e32 v160, v31, v149
	v_mul_f32_e32 v161, v29, v151
	v_fmac_f32_e32 v145, v108, v148
	v_fmac_f32_e32 v147, v106, v150
	v_fmac_f32_e32 v156, v38, v148
	v_fmac_f32_e32 v157, v36, v150
	v_fmac_f32_e32 v158, v54, v148
	v_fmac_f32_e32 v159, v52, v150
	v_fmac_f32_e32 v160, v30, v148
	v_fmac_f32_e32 v161, v28, v150
	ds_read_b128 v[148:151], v118 offset:30720
	s_waitcnt lgkmcnt(1)
	v_mul_f32_e32 v162, v105, v153
	v_mul_f32_e32 v163, v103, v155
	v_mul_f32_e32 v164, v35, v153
	v_mul_f32_e32 v165, v33, v155
	v_mul_f32_e32 v166, v51, v153
	v_mul_f32_e32 v167, v49, v155
	v_mul_f32_e32 v168, v27, v153
	v_mul_f32_e32 v169, v25, v155
	v_fmac_f32_e32 v162, v104, v152
	v_fmac_f32_e32 v163, v102, v154
	v_fmac_f32_e32 v164, v34, v152
	v_fmac_f32_e32 v165, v32, v154
	v_fmac_f32_e32 v166, v50, v152
	v_fmac_f32_e32 v167, v48, v154
	v_fmac_f32_e32 v168, v26, v152
	v_fmac_f32_e32 v169, v24, v154
	ds_read_b128 v[152:155], v118 offset:31744
	s_waitcnt lgkmcnt(1)
	v_mul_f32_e32 v170, v97, v149
	v_mul_f32_e32 v172, v45, v149
	v_mul_f32_e32 v174, v63, v149
	v_mul_f32_e32 v149, v23, v149
	v_fmac_f32_e32 v170, v96, v148
	v_mul_f32_e32 v171, v95, v151
	v_fmac_f32_e32 v172, v44, v148
	v_mul_f32_e32 v173, v43, v151
	v_fmac_f32_e32 v174, v62, v148
	v_mul_f32_e32 v175, v59, v151
	v_fmac_f32_e32 v149, v22, v148
	v_mul_f32_e32 v148, v21, v151
	v_fmac_f32_e32 v171, v94, v150
	v_fmac_f32_e32 v173, v42, v150
	v_fmac_f32_e32 v175, v58, v150
	v_fmac_f32_e32 v148, v20, v150
	s_waitcnt lgkmcnt(0)
	v_mul_f32_e32 v150, v101, v153
	v_mul_f32_e32 v176, v47, v153
	v_mul_f32_e32 v178, v61, v153
	v_mul_f32_e32 v153, v19, v153
	v_add_f32_e32 v145, v145, v147
	v_fmac_f32_e32 v150, v100, v152
	v_mul_f32_e32 v151, v99, v155
	v_fmac_f32_e32 v176, v46, v152
	v_mul_f32_e32 v177, v41, v155
	v_fmac_f32_e32 v178, v60, v152
	v_mul_f32_e32 v179, v57, v155
	v_fmac_f32_e32 v153, v18, v152
	v_mul_f32_e32 v152, v17, v155
	v_add_f32_e32 v147, v156, v157
	v_add_f32_e32 v156, v162, v163
	v_add_f32_e32 v145, 0, v145
	v_fmac_f32_e32 v151, v98, v154
	v_fmac_f32_e32 v177, v40, v154
	v_fmac_f32_e32 v179, v56, v154
	v_fmac_f32_e32 v152, v16, v154
	v_add_f32_e32 v154, v158, v159
	v_add_f32_e32 v145, v145, v156
	v_add_f32_e32 v156, v164, v165
	v_add_f32_e32 v147, 0, v147
	v_add_f32_e32 v155, v160, v161
	v_add_f32_e32 v147, v147, v156
	v_add_f32_e32 v156, v166, v167
	v_add_f32_e32 v154, 0, v154
	v_add_f32_e32 v154, v154, v156
	v_add_f32_e32 v156, v168, v169
	v_add_f32_e32 v155, 0, v155
	v_add_f32_e32 v155, v155, v156
	v_add_f32_e32 v156, v170, v171
	v_add_f32_e32 v148, v149, v148
	v_add_f32_e32 v145, v145, v156
	v_add_f32_e32 v156, v172, v173
	v_add_f32_e32 v155, v155, v148
	v_add_f32_e32 v148, v150, v151
	v_add_f32_e32 v147, v147, v156
	v_add_f32_e32 v156, v174, v175
	v_add_f32_e32 v149, v145, v148
	v_add_f32_e32 v145, v176, v177
	v_add_f32_e32 v154, v154, v156
	v_add_f32_e32 v148, v147, v145
	v_add_f32_e32 v145, v178, v179
	v_add_f32_e32 v147, v154, v145
	v_add_f32_e32 v145, v153, v152
	v_add_f32_e32 v145, v155, v145
	ds_read_b128 v[150:153], v118 offset:32768
	ds_read_b128 v[154:157], v118 offset:33792
	s_waitcnt lgkmcnt(1)
	v_mul_f32_e32 v158, v109, v151
	v_mul_f32_e32 v159, v107, v153
	v_mul_f32_e32 v160, v39, v151
	v_mul_f32_e32 v161, v37, v153
	v_mul_f32_e32 v162, v55, v151
	v_mul_f32_e32 v163, v53, v153
	v_mul_f32_e32 v164, v31, v151
	v_mul_f32_e32 v165, v29, v153
	v_fmac_f32_e32 v158, v108, v150
	v_fmac_f32_e32 v159, v106, v152
	v_fmac_f32_e32 v160, v38, v150
	v_fmac_f32_e32 v161, v36, v152
	v_fmac_f32_e32 v162, v54, v150
	v_fmac_f32_e32 v163, v52, v152
	v_fmac_f32_e32 v164, v30, v150
	v_fmac_f32_e32 v165, v28, v152
	ds_read_b128 v[150:153], v118 offset:34816
	s_waitcnt lgkmcnt(1)
; #define LAS __attribute__((address_space(3)))
; __device__ __forceinline__ void phase_prologue(const Params& P, LAS unsigned char* lds) {
;     ...
;         for (int r = 0; r < 16; ++r) {
;             float sacc[RP];
; #pragma unroll
;             for (int q = 0; q < RP; ++q) sacc[q] = 0.f;
; #pragma unroll
;             for (int j = 0; j < 4; ++j) { const f32x4 wv = *(const LAS f32x4*)(Wl + r * 1024 + 4 * lane + 256 * j);
; #pragma unroll
;                 for (int q = 0; q < RP; ++q) sacc[q] += (v[q][j][0] * wv[0] + v[q][j][1] * wv[1]) + (v[q][j][2] * wv[2] + v[q][j][3] * wv[3]); }
;             asm volatile("" : "+v"(sacc[0]), "+v"(sacc[1]), "+v"(sacc[2]), "+v"(sacc[3]) :: "memory");
; #pragma unroll
;             for (int q = 0; q < RP; ++q) a[q][r] = sacc[q];
;         }
	v_mul_f32_e32 v166, v105, v155
	v_mul_f32_e32 v167, v103, v157
	v_mul_f32_e32 v168, v35, v155
	v_mul_f32_e32 v169, v33, v157
	v_mul_f32_e32 v170, v51, v155
	v_mul_f32_e32 v171, v49, v157
	v_mul_f32_e32 v172, v27, v155
	v_mul_f32_e32 v173, v25, v157
	v_fmac_f32_e32 v166, v104, v154
	v_fmac_f32_e32 v167, v102, v156
	v_fmac_f32_e32 v168, v34, v154
	v_fmac_f32_e32 v169, v32, v156
	v_fmac_f32_e32 v170, v50, v154
	v_fmac_f32_e32 v171, v48, v156
	v_fmac_f32_e32 v172, v26, v154
	v_fmac_f32_e32 v173, v24, v156
	ds_read_b128 v[154:157], v118 offset:35840
	s_waitcnt lgkmcnt(1)
	v_mul_f32_e32 v174, v97, v151
	v_mul_f32_e32 v176, v45, v151
	v_mul_f32_e32 v178, v63, v151
	v_mul_f32_e32 v151, v23, v151
	v_fmac_f32_e32 v174, v96, v150
	v_mul_f32_e32 v175, v95, v153
	v_fmac_f32_e32 v176, v44, v150
	v_mul_f32_e32 v177, v43, v153
	v_fmac_f32_e32 v178, v62, v150
	v_mul_f32_e32 v179, v59, v153
	v_fmac_f32_e32 v151, v22, v150
	v_mul_f32_e32 v150, v21, v153
	v_fmac_f32_e32 v175, v94, v152
	v_fmac_f32_e32 v177, v42, v152
	v_fmac_f32_e32 v179, v58, v152
	v_fmac_f32_e32 v150, v20, v152
	s_waitcnt lgkmcnt(0)
	v_mul_f32_e32 v152, v101, v155
	v_mul_f32_e32 v180, v47, v155
	v_mul_f32_e32 v182, v61, v155
	v_mul_f32_e32 v155, v19, v155
	v_fmac_f32_e32 v152, v100, v154
	v_mul_f32_e32 v153, v99, v157
	v_fmac_f32_e32 v180, v46, v154
	v_mul_f32_e32 v181, v41, v157
	v_fmac_f32_e32 v182, v60, v154
	v_mul_f32_e32 v183, v57, v157
	v_fmac_f32_e32 v155, v18, v154
	v_mul_f32_e32 v157, v17, v157
	v_add_f32_e32 v154, v158, v159
	v_fmac_f32_e32 v153, v98, v156
	v_fmac_f32_e32 v181, v40, v156
	v_fmac_f32_e32 v183, v56, v156
	v_fmac_f32_e32 v157, v16, v156
	v_add_f32_e32 v156, v160, v161
	v_add_f32_e32 v160, v166, v167
	v_add_f32_e32 v154, 0, v154
	v_add_f32_e32 v158, v162, v163
	v_add_f32_e32 v154, v154, v160
	v_add_f32_e32 v160, v168, v169
	v_add_f32_e32 v156, 0, v156
	v_add_f32_e32 v159, v164, v165
	v_add_f32_e32 v156, v156, v160
	v_add_f32_e32 v160, v170, v171
	v_add_f32_e32 v158, 0, v158
	v_add_f32_e32 v158, v158, v160
	v_add_f32_e32 v160, v172, v173
	v_add_f32_e32 v159, 0, v159
	v_add_f32_e32 v159, v159, v160
	v_add_f32_e32 v160, v174, v175
	v_add_f32_e32 v154, v154, v160
	v_add_f32_e32 v160, v176, v177
	v_add_f32_e32 v150, v151, v150
	v_add_f32_e32 v151, v152, v153
	v_add_f32_e32 v156, v156, v160
	v_add_f32_e32 v160, v178, v179
	v_add_f32_e32 v154, v154, v151
	v_add_f32_e32 v151, v180, v181
	v_add_f32_e32 v158, v158, v160
	v_add_f32_e32 v150, v159, v150
	v_add_f32_e32 v152, v156, v151
	v_add_f32_e32 v151, v182, v183
	v_add_f32_e32 v153, v155, v157
	v_add_f32_e32 v151, v158, v151
	v_add_f32_e32 v150, v150, v153
	ds_read_b128 v[156:159], v118 offset:36864
	ds_read_b128 v[160:163], v118 offset:37888
	s_waitcnt lgkmcnt(1)
	v_mul_f32_e32 v153, v109, v157
	v_mul_f32_e32 v155, v107, v159
	v_mul_f32_e32 v164, v39, v157
	v_mul_f32_e32 v165, v37, v159
	v_mul_f32_e32 v166, v55, v157
	v_mul_f32_e32 v167, v53, v159
	v_mul_f32_e32 v168, v31, v157
	v_mul_f32_e32 v169, v29, v159
	v_fmac_f32_e32 v153, v108, v156
	v_fmac_f32_e32 v155, v106, v158
	v_fmac_f32_e32 v164, v38, v156
	v_fmac_f32_e32 v165, v36, v158
	v_fmac_f32_e32 v166, v54, v156
	v_fmac_f32_e32 v167, v52, v158
	v_fmac_f32_e32 v168, v30, v156
	v_fmac_f32_e32 v169, v28, v158
	ds_read_b128 v[156:159], v118 offset:38912
	s_waitcnt lgkmcnt(1)
	v_mul_f32_e32 v170, v105, v161
	v_mul_f32_e32 v171, v103, v163
	v_mul_f32_e32 v172, v35, v161
	v_mul_f32_e32 v173, v33, v163
	v_mul_f32_e32 v174, v51, v161
	v_mul_f32_e32 v175, v49, v163
	v_mul_f32_e32 v176, v27, v161
	v_mul_f32_e32 v177, v25, v163
	v_fmac_f32_e32 v170, v104, v160
	v_fmac_f32_e32 v171, v102, v162
	v_fmac_f32_e32 v172, v34, v160
	v_fmac_f32_e32 v173, v32, v162
	v_fmac_f32_e32 v174, v50, v160
	v_fmac_f32_e32 v175, v48, v162
	v_fmac_f32_e32 v176, v26, v160
	v_fmac_f32_e32 v177, v24, v162
	ds_read_b128 v[160:163], v118 offset:39936
	s_waitcnt lgkmcnt(1)
	v_mul_f32_e32 v178, v97, v157
	v_mul_f32_e32 v180, v45, v157
	v_mul_f32_e32 v182, v63, v157
	v_mul_f32_e32 v157, v23, v157
	v_fmac_f32_e32 v178, v96, v156
	v_mul_f32_e32 v179, v95, v159
	v_fmac_f32_e32 v180, v44, v156
	v_mul_f32_e32 v181, v43, v159
	v_fmac_f32_e32 v182, v62, v156
	v_mul_f32_e32 v183, v59, v159
	v_fmac_f32_e32 v157, v22, v156
	v_mul_f32_e32 v156, v21, v159
	v_fmac_f32_e32 v179, v94, v158
	v_fmac_f32_e32 v181, v42, v158
	v_fmac_f32_e32 v183, v58, v158
	v_fmac_f32_e32 v156, v20, v158
	s_waitcnt lgkmcnt(0)
	v_mul_f32_e32 v158, v101, v161
	v_mul_f32_e32 v184, v47, v161
	v_mul_f32_e32 v186, v61, v161
	v_mul_f32_e32 v161, v19, v161
	v_add_f32_e32 v153, v153, v155
	v_fmac_f32_e32 v158, v100, v160
	v_mul_f32_e32 v159, v99, v163
	v_fmac_f32_e32 v184, v46, v160
	v_mul_f32_e32 v185, v41, v163
	v_fmac_f32_e32 v186, v60, v160
	v_mul_f32_e32 v187, v57, v163
	v_fmac_f32_e32 v161, v18, v160
	v_mul_f32_e32 v160, v17, v163
	v_add_f32_e32 v155, v164, v165
	v_add_f32_e32 v164, v170, v171
	v_add_f32_e32 v153, 0, v153
	v_fmac_f32_e32 v159, v98, v162
	v_fmac_f32_e32 v185, v40, v162
	v_fmac_f32_e32 v187, v56, v162
	v_fmac_f32_e32 v160, v16, v162
	v_add_f32_e32 v162, v166, v167
	v_add_f32_e32 v153, v153, v164
	v_add_f32_e32 v164, v172, v173
	v_add_f32_e32 v155, 0, v155
	v_add_f32_e32 v163, v168, v169
	v_add_f32_e32 v155, v155, v164
	v_add_f32_e32 v164, v174, v175
	v_add_f32_e32 v162, 0, v162
	v_add_f32_e32 v162, v162, v164
	v_add_f32_e32 v164, v176, v177
	v_add_f32_e32 v163, 0, v163
	v_add_f32_e32 v163, v163, v164
	v_add_f32_e32 v164, v178, v179
	v_add_f32_e32 v156, v157, v156
	v_add_f32_e32 v153, v153, v164
	v_add_f32_e32 v164, v180, v181
	v_add_f32_e32 v157, v163, v156
	v_add_f32_e32 v156, v158, v159
	v_add_f32_e32 v155, v155, v164
	v_add_f32_e32 v164, v182, v183
	v_add_f32_e32 v158, v153, v156
	v_add_f32_e32 v153, v184, v185
	v_add_f32_e32 v162, v162, v164
	v_add_f32_e32 v156, v155, v153
	v_add_f32_e32 v153, v186, v187
	v_add_f32_e32 v155, v162, v153
	v_add_f32_e32 v153, v161, v160
	v_add_f32_e32 v153, v157, v153
	ds_read_b128 v[160:163], v118 offset:40960
	ds_read_b128 v[164:167], v118 offset:41984
	s_waitcnt lgkmcnt(1)
; #define LAS __attribute__((address_space(3)))
; __device__ __forceinline__ void phase_prologue(const Params& P, LAS unsigned char* lds) {
;     ...
;         for (int r = 0; r < 16; ++r) {
;             float sacc[RP];
; #pragma unroll
;             for (int q = 0; q < RP; ++q) sacc[q] = 0.f;
; #pragma unroll
;             for (int j = 0; j < 4; ++j) { const f32x4 wv = *(const LAS f32x4*)(Wl + r * 1024 + 4 * lane + 256 * j);
; #pragma unroll
;                 for (int q = 0; q < RP; ++q) sacc[q] += (v[q][j][0] * wv[0] + v[q][j][1] * wv[1]) + (v[q][j][2] * wv[2] + v[q][j][3] * wv[3]); }
;             asm volatile("" : "+v"(sacc[0]), "+v"(sacc[1]), "+v"(sacc[2]), "+v"(sacc[3]) :: "memory");
; #pragma unroll
;             for (int q = 0; q < RP; ++q) a[q][r] = sacc[q];
;         }
	v_mul_f32_e32 v157, v109, v161
	v_mul_f32_e32 v159, v107, v163
	v_mul_f32_e32 v168, v39, v161
	v_mul_f32_e32 v169, v37, v163
	v_mul_f32_e32 v170, v55, v161
	v_mul_f32_e32 v171, v53, v163
	v_mul_f32_e32 v172, v31, v161
	v_mul_f32_e32 v173, v29, v163
	v_fmac_f32_e32 v157, v108, v160
	v_fmac_f32_e32 v159, v106, v162
	v_fmac_f32_e32 v168, v38, v160
	v_fmac_f32_e32 v169, v36, v162
	v_fmac_f32_e32 v170, v54, v160
	v_fmac_f32_e32 v171, v52, v162
	v_fmac_f32_e32 v172, v30, v160
	v_fmac_f32_e32 v173, v28, v162
	ds_read_b128 v[160:163], v118 offset:43008
	s_waitcnt lgkmcnt(1)
	v_mul_f32_e32 v174, v105, v165
	v_mul_f32_e32 v175, v103, v167
	v_mul_f32_e32 v176, v35, v165
	v_mul_f32_e32 v177, v33, v167
	v_mul_f32_e32 v178, v51, v165
	v_mul_f32_e32 v179, v49, v167
	v_mul_f32_e32 v180, v27, v165
	v_mul_f32_e32 v181, v25, v167
	v_fmac_f32_e32 v174, v104, v164
	v_fmac_f32_e32 v175, v102, v166
	v_fmac_f32_e32 v176, v34, v164
	v_fmac_f32_e32 v177, v32, v166
	v_fmac_f32_e32 v178, v50, v164
	v_fmac_f32_e32 v179, v48, v166
	v_fmac_f32_e32 v180, v26, v164
	v_fmac_f32_e32 v181, v24, v166
	ds_read_b128 v[164:167], v118 offset:44032
	s_waitcnt lgkmcnt(1)
	v_mul_f32_e32 v182, v97, v161
	v_mul_f32_e32 v184, v45, v161
	v_mul_f32_e32 v186, v63, v161
	v_mul_f32_e32 v161, v23, v161
	v_fmac_f32_e32 v182, v96, v160
	v_mul_f32_e32 v183, v95, v163
	v_fmac_f32_e32 v184, v44, v160
	v_mul_f32_e32 v185, v43, v163
	v_fmac_f32_e32 v186, v62, v160
	v_mul_f32_e32 v187, v59, v163
	v_fmac_f32_e32 v161, v22, v160
	v_mul_f32_e32 v160, v21, v163
	v_fmac_f32_e32 v183, v94, v162
	v_fmac_f32_e32 v185, v42, v162
	v_fmac_f32_e32 v187, v58, v162
	v_fmac_f32_e32 v160, v20, v162
	s_waitcnt lgkmcnt(0)
	v_mul_f32_e32 v162, v101, v165
	v_mul_f32_e32 v188, v47, v165
	v_mul_f32_e32 v190, v61, v165
	v_mul_f32_e32 v165, v19, v165
	v_add_f32_e32 v157, v157, v159
	v_fmac_f32_e32 v162, v100, v164
	v_mul_f32_e32 v163, v99, v167
	v_fmac_f32_e32 v188, v46, v164
	v_mul_f32_e32 v189, v41, v167
	v_fmac_f32_e32 v190, v60, v164
	v_mul_f32_e32 v191, v57, v167
	v_fmac_f32_e32 v165, v18, v164
	v_mul_f32_e32 v164, v17, v167
	v_add_f32_e32 v159, v168, v169
	v_add_f32_e32 v168, v174, v175
	v_add_f32_e32 v157, 0, v157
	v_fmac_f32_e32 v163, v98, v166
	v_fmac_f32_e32 v189, v40, v166
	v_fmac_f32_e32 v191, v56, v166
	v_fmac_f32_e32 v164, v16, v166
	v_add_f32_e32 v166, v170, v171
	v_add_f32_e32 v157, v157, v168
	v_add_f32_e32 v168, v176, v177
	v_add_f32_e32 v159, 0, v159
	v_add_f32_e32 v167, v172, v173
	v_add_f32_e32 v159, v159, v168
	v_add_f32_e32 v168, v178, v179
	v_add_f32_e32 v166, 0, v166
	v_add_f32_e32 v166, v166, v168
	v_add_f32_e32 v168, v180, v181
	v_add_f32_e32 v167, 0, v167
	v_add_f32_e32 v167, v167, v168
	v_add_f32_e32 v168, v182, v183
	v_add_f32_e32 v160, v161, v160
	v_add_f32_e32 v157, v157, v168
	v_add_f32_e32 v168, v184, v185
	v_add_f32_e32 v161, v167, v160
	v_add_f32_e32 v160, v162, v163
	v_add_f32_e32 v159, v159, v168
	v_add_f32_e32 v168, v186, v187
	v_add_f32_e32 v162, v157, v160
	v_add_f32_e32 v157, v188, v189
	v_add_f32_e32 v166, v166, v168
	v_add_f32_e32 v160, v159, v157
	v_add_f32_e32 v157, v190, v191
	v_add_f32_e32 v159, v166, v157
	v_add_f32_e32 v157, v165, v164
	v_add_f32_e32 v157, v161, v157
	ds_read_b128 v[164:167], v118 offset:45056
	ds_read_b128 v[168:171], v118 offset:46080
	s_waitcnt lgkmcnt(1)
	v_mul_f32_e32 v161, v109, v165
	v_mul_f32_e32 v163, v107, v167
	v_mul_f32_e32 v172, v39, v165
	v_mul_f32_e32 v173, v37, v167
	v_mul_f32_e32 v174, v55, v165
	v_mul_f32_e32 v175, v53, v167
	v_mul_f32_e32 v176, v31, v165
	v_mul_f32_e32 v177, v29, v167
	v_fmac_f32_e32 v161, v108, v164
	v_fmac_f32_e32 v163, v106, v166
	v_fmac_f32_e32 v172, v38, v164
	v_fmac_f32_e32 v173, v36, v166
	v_fmac_f32_e32 v174, v54, v164
	v_fmac_f32_e32 v175, v52, v166
	v_fmac_f32_e32 v176, v30, v164
	v_fmac_f32_e32 v177, v28, v166
	ds_read_b128 v[164:167], v118 offset:47104
	s_waitcnt lgkmcnt(1)
	v_mul_f32_e32 v178, v105, v169
	v_mul_f32_e32 v179, v103, v171
	v_mul_f32_e32 v180, v35, v169
	v_mul_f32_e32 v181, v33, v171
	v_mul_f32_e32 v182, v51, v169
	v_mul_f32_e32 v183, v49, v171
	v_mul_f32_e32 v184, v27, v169
	v_mul_f32_e32 v185, v25, v171
	v_fmac_f32_e32 v178, v104, v168
	v_fmac_f32_e32 v179, v102, v170
	v_fmac_f32_e32 v180, v34, v168
	v_fmac_f32_e32 v181, v32, v170
	v_fmac_f32_e32 v182, v50, v168
	v_fmac_f32_e32 v183, v48, v170
	v_fmac_f32_e32 v184, v26, v168
	v_fmac_f32_e32 v185, v24, v170
	ds_read_b128 v[168:171], v118 offset:48128
	s_waitcnt lgkmcnt(1)
	v_mul_f32_e32 v186, v97, v165
	v_mul_f32_e32 v188, v45, v165
	v_mul_f32_e32 v190, v63, v165
	v_mul_f32_e32 v165, v23, v165
	v_fmac_f32_e32 v186, v96, v164
	v_mul_f32_e32 v187, v95, v167
	v_fmac_f32_e32 v188, v44, v164
	v_mul_f32_e32 v189, v43, v167
	v_fmac_f32_e32 v190, v62, v164
	v_mul_f32_e32 v191, v59, v167
	v_fmac_f32_e32 v165, v22, v164
	v_mul_f32_e32 v164, v21, v167
	v_fmac_f32_e32 v187, v94, v166
	v_fmac_f32_e32 v189, v42, v166
	v_fmac_f32_e32 v191, v58, v166
	v_fmac_f32_e32 v164, v20, v166
	s_waitcnt lgkmcnt(0)
; #define LAS __attribute__((address_space(3)))
; __device__ __forceinline__ void phase_prologue(const Params& P, LAS unsigned char* lds) {
;     ...
;         for (int r = 0; r < 16; ++r) {
;             float sacc[RP];
; #pragma unroll
;             for (int q = 0; q < RP; ++q) sacc[q] = 0.f;
; #pragma unroll
;             for (int j = 0; j < 4; ++j) { const f32x4 wv = *(const LAS f32x4*)(Wl + r * 1024 + 4 * lane + 256 * j);
; #pragma unroll
;                 for (int q = 0; q < RP; ++q) sacc[q] += (v[q][j][0] * wv[0] + v[q][j][1] * wv[1]) + (v[q][j][2] * wv[2] + v[q][j][3] * wv[3]); }
;             asm volatile("" : "+v"(sacc[0]), "+v"(sacc[1]), "+v"(sacc[2]), "+v"(sacc[3]) :: "memory");
; #pragma unroll
;             for (int q = 0; q < RP; ++q) a[q][r] = sacc[q];
;         }
	v_mul_f32_e32 v166, v101, v169
	v_mul_f32_e32 v192, v47, v169
	v_mul_f32_e32 v196, v61, v169
	v_mul_f32_e32 v169, v19, v169
	v_add_f32_e32 v161, v161, v163
	v_fmac_f32_e32 v166, v100, v168
	v_mul_f32_e32 v167, v99, v171
	v_fmac_f32_e32 v192, v46, v168
	v_mul_f32_e32 v193, v41, v171
	v_fmac_f32_e32 v196, v60, v168
	v_mul_f32_e32 v197, v57, v171
	v_fmac_f32_e32 v169, v18, v168
	v_mul_f32_e32 v168, v17, v171
	v_add_f32_e32 v163, v172, v173
	v_add_f32_e32 v172, v178, v179
	v_add_f32_e32 v161, 0, v161
	v_fmac_f32_e32 v167, v98, v170
	v_fmac_f32_e32 v193, v40, v170
	v_fmac_f32_e32 v197, v56, v170
	v_fmac_f32_e32 v168, v16, v170
	v_add_f32_e32 v170, v174, v175
	v_add_f32_e32 v161, v161, v172
	v_add_f32_e32 v172, v180, v181
	v_add_f32_e32 v163, 0, v163
	v_add_f32_e32 v171, v176, v177
	v_add_f32_e32 v163, v163, v172
	v_add_f32_e32 v172, v182, v183
	v_add_f32_e32 v170, 0, v170
	v_add_f32_e32 v170, v170, v172
	v_add_f32_e32 v172, v184, v185
	v_add_f32_e32 v171, 0, v171
	v_add_f32_e32 v171, v171, v172
	v_add_f32_e32 v172, v186, v187
	v_add_f32_e32 v164, v165, v164
	v_add_f32_e32 v161, v161, v172
	v_add_f32_e32 v172, v188, v189
	v_add_f32_e32 v165, v171, v164
	v_add_f32_e32 v164, v166, v167
	v_add_f32_e32 v163, v163, v172
	v_add_f32_e32 v172, v190, v191
	v_add_f32_e32 v166, v161, v164
	v_add_f32_e32 v161, v192, v193
	v_add_f32_e32 v170, v170, v172
	v_add_f32_e32 v164, v163, v161
	v_add_f32_e32 v161, v196, v197
	v_add_f32_e32 v163, v170, v161
	v_add_f32_e32 v161, v169, v168
	v_add_f32_e32 v161, v165, v161
	ds_read_b128 v[168:171], v118 offset:49152
	ds_read_b128 v[172:175], v118 offset:50176
	s_waitcnt lgkmcnt(1)
	v_mul_f32_e32 v165, v109, v169
	v_mul_f32_e32 v167, v107, v171
	v_mul_f32_e32 v176, v39, v169
	v_mul_f32_e32 v177, v37, v171
	v_mul_f32_e32 v178, v55, v169
	v_mul_f32_e32 v179, v53, v171
	v_mul_f32_e32 v180, v31, v169
	v_mul_f32_e32 v181, v29, v171
	v_fmac_f32_e32 v165, v108, v168
	v_fmac_f32_e32 v167, v106, v170
	v_fmac_f32_e32 v176, v38, v168
	v_fmac_f32_e32 v177, v36, v170
	v_fmac_f32_e32 v178, v54, v168
	v_fmac_f32_e32 v179, v52, v170
	v_fmac_f32_e32 v180, v30, v168
	v_fmac_f32_e32 v181, v28, v170
	ds_read_b128 v[168:171], v118 offset:51200
	s_waitcnt lgkmcnt(1)
	v_mul_f32_e32 v182, v105, v173
	v_mul_f32_e32 v183, v103, v175
	v_mul_f32_e32 v184, v35, v173
	v_mul_f32_e32 v185, v33, v175
	v_mul_f32_e32 v186, v51, v173
	v_mul_f32_e32 v187, v49, v175
	v_mul_f32_e32 v188, v27, v173
	v_mul_f32_e32 v189, v25, v175
	v_fmac_f32_e32 v182, v104, v172
	v_fmac_f32_e32 v183, v102, v174
	v_fmac_f32_e32 v184, v34, v172
	v_fmac_f32_e32 v185, v32, v174
	v_fmac_f32_e32 v186, v50, v172
	v_fmac_f32_e32 v187, v48, v174
	v_fmac_f32_e32 v188, v26, v172
	v_fmac_f32_e32 v189, v24, v174
	ds_read_b128 v[172:175], v118 offset:52224
	s_waitcnt lgkmcnt(1)
	v_mul_f32_e32 v190, v97, v169
	v_mul_f32_e32 v192, v45, v169
	v_mul_f32_e32 v196, v63, v169
	v_mul_f32_e32 v169, v23, v169
	v_fmac_f32_e32 v190, v96, v168
	v_mul_f32_e32 v191, v95, v171
	v_fmac_f32_e32 v192, v44, v168
	v_mul_f32_e32 v193, v43, v171
	v_fmac_f32_e32 v196, v62, v168
	v_mul_f32_e32 v197, v59, v171
	v_fmac_f32_e32 v169, v22, v168
	v_mul_f32_e32 v168, v21, v171
	v_fmac_f32_e32 v191, v94, v170
	v_fmac_f32_e32 v193, v42, v170
	v_fmac_f32_e32 v197, v58, v170
	v_fmac_f32_e32 v168, v20, v170
	s_waitcnt lgkmcnt(0)
	v_mul_f32_e32 v170, v101, v173
	v_mul_f32_e32 v198, v47, v173
	v_mul_f32_e32 v200, v61, v173
	v_mul_f32_e32 v173, v19, v173
	v_add_f32_e32 v165, v165, v167
	v_fmac_f32_e32 v170, v100, v172
	v_mul_f32_e32 v171, v99, v175
	v_fmac_f32_e32 v198, v46, v172
	v_mul_f32_e32 v199, v41, v175
	v_fmac_f32_e32 v200, v60, v172
	v_mul_f32_e32 v201, v57, v175
	v_fmac_f32_e32 v173, v18, v172
	v_mul_f32_e32 v172, v17, v175
	v_add_f32_e32 v167, v176, v177
	v_add_f32_e32 v176, v182, v183
	v_add_f32_e32 v165, 0, v165
	v_fmac_f32_e32 v171, v98, v174
	v_fmac_f32_e32 v199, v40, v174
	v_fmac_f32_e32 v201, v56, v174
	v_fmac_f32_e32 v172, v16, v174
	v_add_f32_e32 v174, v178, v179
	v_add_f32_e32 v165, v165, v176
	v_add_f32_e32 v176, v184, v185
	v_add_f32_e32 v167, 0, v167
	v_add_f32_e32 v175, v180, v181
	v_add_f32_e32 v167, v167, v176
	v_add_f32_e32 v176, v186, v187
	v_add_f32_e32 v174, 0, v174
	v_add_f32_e32 v174, v174, v176
	v_add_f32_e32 v176, v188, v189
	v_add_f32_e32 v175, 0, v175
	v_add_f32_e32 v175, v175, v176
	v_add_f32_e32 v176, v190, v191
	v_add_f32_e32 v168, v169, v168
	v_add_f32_e32 v165, v165, v176
	v_add_f32_e32 v176, v192, v193
	v_add_f32_e32 v169, v175, v168
	v_add_f32_e32 v168, v170, v171
	v_add_f32_e32 v167, v167, v176
	v_add_f32_e32 v176, v196, v197
	v_add_f32_e32 v170, v165, v168
	v_add_f32_e32 v165, v198, v199
	v_add_f32_e32 v174, v174, v176
	v_add_f32_e32 v168, v167, v165
	v_add_f32_e32 v165, v200, v201
	v_add_f32_e32 v167, v174, v165
	v_add_f32_e32 v165, v173, v172
	v_add_f32_e32 v165, v169, v165
	ds_read_b128 v[172:175], v118 offset:53248
	ds_read_b128 v[176:179], v118 offset:54272
	s_waitcnt lgkmcnt(1)
	v_mul_f32_e32 v169, v109, v173
	v_mul_f32_e32 v171, v107, v175
	v_mul_f32_e32 v180, v39, v173
	v_mul_f32_e32 v181, v37, v175
	v_mul_f32_e32 v182, v55, v173
	v_mul_f32_e32 v183, v53, v175
	v_mul_f32_e32 v184, v31, v173
	v_mul_f32_e32 v185, v29, v175
	v_fmac_f32_e32 v169, v108, v172
	v_fmac_f32_e32 v171, v106, v174
	v_fmac_f32_e32 v180, v38, v172
	v_fmac_f32_e32 v181, v36, v174
	v_fmac_f32_e32 v182, v54, v172
	v_fmac_f32_e32 v183, v52, v174
	v_fmac_f32_e32 v184, v30, v172
	v_fmac_f32_e32 v185, v28, v174
	ds_read_b128 v[172:175], v118 offset:55296
	s_waitcnt lgkmcnt(1)
; #define LAS __attribute__((address_space(3)))
; __device__ __forceinline__ void phase_prologue(const Params& P, LAS unsigned char* lds) {
;     ...
;         for (int r = 0; r < 16; ++r) {
;             float sacc[RP];
; #pragma unroll
;             for (int q = 0; q < RP; ++q) sacc[q] = 0.f;
; #pragma unroll
;             for (int j = 0; j < 4; ++j) { const f32x4 wv = *(const LAS f32x4*)(Wl + r * 1024 + 4 * lane + 256 * j);
; #pragma unroll
;                 for (int q = 0; q < RP; ++q) sacc[q] += (v[q][j][0] * wv[0] + v[q][j][1] * wv[1]) + (v[q][j][2] * wv[2] + v[q][j][3] * wv[3]); }
;             asm volatile("" : "+v"(sacc[0]), "+v"(sacc[1]), "+v"(sacc[2]), "+v"(sacc[3]) :: "memory");
; #pragma unroll
;             for (int q = 0; q < RP; ++q) a[q][r] = sacc[q];
;         }
	v_mul_f32_e32 v186, v105, v177
	v_mul_f32_e32 v187, v103, v179
	v_mul_f32_e32 v188, v35, v177
	v_mul_f32_e32 v189, v33, v179
	v_mul_f32_e32 v190, v51, v177
	v_mul_f32_e32 v191, v49, v179
	v_mul_f32_e32 v192, v27, v177
	v_mul_f32_e32 v193, v25, v179
	v_fmac_f32_e32 v186, v104, v176
	v_fmac_f32_e32 v187, v102, v178
	v_fmac_f32_e32 v188, v34, v176
	v_fmac_f32_e32 v189, v32, v178
	v_fmac_f32_e32 v190, v50, v176
	v_fmac_f32_e32 v191, v48, v178
	v_fmac_f32_e32 v192, v26, v176
	v_fmac_f32_e32 v193, v24, v178
	ds_read_b128 v[176:179], v118 offset:56320
	s_waitcnt lgkmcnt(1)
	v_mul_f32_e32 v196, v97, v173
	v_mul_f32_e32 v198, v45, v173
	v_mul_f32_e32 v200, v63, v173
	v_mul_f32_e32 v173, v23, v173
	v_fmac_f32_e32 v196, v96, v172
	v_mul_f32_e32 v197, v95, v175
	v_fmac_f32_e32 v198, v44, v172
	v_mul_f32_e32 v199, v43, v175
	v_fmac_f32_e32 v200, v62, v172
	v_mul_f32_e32 v201, v59, v175
	v_fmac_f32_e32 v173, v22, v172
	v_mul_f32_e32 v172, v21, v175
	v_fmac_f32_e32 v197, v94, v174
	v_fmac_f32_e32 v199, v42, v174
	v_fmac_f32_e32 v201, v58, v174
	v_fmac_f32_e32 v172, v20, v174
	s_waitcnt lgkmcnt(0)
	v_mul_f32_e32 v174, v101, v177
	v_mul_f32_e32 v202, v47, v177
	v_mul_f32_e32 v204, v61, v177
	v_mul_f32_e32 v177, v19, v177
	v_add_f32_e32 v169, v169, v171
	v_fmac_f32_e32 v174, v100, v176
	v_mul_f32_e32 v175, v99, v179
	v_fmac_f32_e32 v202, v46, v176
	v_mul_f32_e32 v203, v41, v179
	v_fmac_f32_e32 v204, v60, v176
	v_mul_f32_e32 v205, v57, v179
	v_fmac_f32_e32 v177, v18, v176
	v_mul_f32_e32 v176, v17, v179
	v_add_f32_e32 v171, v180, v181
	v_add_f32_e32 v180, v186, v187
	v_add_f32_e32 v169, 0, v169
	v_fmac_f32_e32 v175, v98, v178
	v_fmac_f32_e32 v203, v40, v178
	v_fmac_f32_e32 v205, v56, v178
	v_fmac_f32_e32 v176, v16, v178
	v_add_f32_e32 v178, v182, v183
	v_add_f32_e32 v169, v169, v180
	v_add_f32_e32 v180, v188, v189
	v_add_f32_e32 v171, 0, v171
	v_add_f32_e32 v179, v184, v185
	v_add_f32_e32 v171, v171, v180
	v_add_f32_e32 v180, v190, v191
	v_add_f32_e32 v178, 0, v178
	v_add_f32_e32 v178, v178, v180
	v_add_f32_e32 v180, v192, v193
	v_add_f32_e32 v179, 0, v179
	v_add_f32_e32 v179, v179, v180
	v_add_f32_e32 v180, v196, v197
	v_add_f32_e32 v172, v173, v172
	v_add_f32_e32 v169, v169, v180
	v_add_f32_e32 v180, v198, v199
	v_add_f32_e32 v173, v179, v172
	v_add_f32_e32 v172, v174, v175
	v_add_f32_e32 v171, v171, v180
	v_add_f32_e32 v180, v200, v201
	v_add_f32_e32 v174, v169, v172
	v_add_f32_e32 v169, v202, v203
	v_add_f32_e32 v178, v178, v180
	v_add_f32_e32 v172, v171, v169
	v_add_f32_e32 v169, v204, v205
	v_add_f32_e32 v171, v178, v169
	v_add_f32_e32 v169, v177, v176
	v_add_f32_e32 v169, v173, v169
	ds_read_b128 v[176:179], v118 offset:57344
	ds_read_b128 v[180:183], v118 offset:58368
	s_waitcnt lgkmcnt(1)
	v_mul_f32_e32 v173, v109, v177
	v_mul_f32_e32 v175, v107, v179
	v_mul_f32_e32 v184, v39, v177
	v_mul_f32_e32 v185, v37, v179
	v_mul_f32_e32 v186, v55, v177
	v_mul_f32_e32 v187, v53, v179
	v_mul_f32_e32 v188, v31, v177
	v_mul_f32_e32 v189, v29, v179
	v_fmac_f32_e32 v173, v108, v176
	v_fmac_f32_e32 v175, v106, v178
	v_fmac_f32_e32 v184, v38, v176
	v_fmac_f32_e32 v185, v36, v178
	v_fmac_f32_e32 v186, v54, v176
	v_fmac_f32_e32 v187, v52, v178
	v_fmac_f32_e32 v188, v30, v176
	v_fmac_f32_e32 v189, v28, v178
	ds_read_b128 v[176:179], v118 offset:59392
	s_waitcnt lgkmcnt(1)
	v_mul_f32_e32 v190, v105, v181
	v_mul_f32_e32 v191, v103, v183
	v_mul_f32_e32 v192, v35, v181
	v_mul_f32_e32 v193, v33, v183
	v_mul_f32_e32 v196, v51, v181
	v_mul_f32_e32 v197, v49, v183
	v_mul_f32_e32 v198, v27, v181
	v_mul_f32_e32 v199, v25, v183
	v_fmac_f32_e32 v190, v104, v180
	v_fmac_f32_e32 v191, v102, v182
	v_fmac_f32_e32 v192, v34, v180
	v_fmac_f32_e32 v193, v32, v182
	v_fmac_f32_e32 v196, v50, v180
	v_fmac_f32_e32 v197, v48, v182
	v_fmac_f32_e32 v198, v26, v180
	v_fmac_f32_e32 v199, v24, v182
	ds_read_b128 v[180:183], v118 offset:60416
	s_waitcnt lgkmcnt(1)
	v_mul_f32_e32 v200, v97, v177
	v_mul_f32_e32 v202, v45, v177
	v_mul_f32_e32 v204, v63, v177
	v_mul_f32_e32 v177, v23, v177
	v_fmac_f32_e32 v200, v96, v176
	v_mul_f32_e32 v201, v95, v179
	v_fmac_f32_e32 v202, v44, v176
	v_mul_f32_e32 v203, v43, v179
	v_fmac_f32_e32 v204, v62, v176
	v_mul_f32_e32 v205, v59, v179
	v_fmac_f32_e32 v177, v22, v176
	v_mul_f32_e32 v176, v21, v179
	v_fmac_f32_e32 v201, v94, v178
	v_fmac_f32_e32 v203, v42, v178
	v_fmac_f32_e32 v205, v58, v178
	v_fmac_f32_e32 v176, v20, v178
	s_waitcnt lgkmcnt(0)
	v_mul_f32_e32 v178, v101, v181
	v_mul_f32_e32 v206, v47, v181
	v_mul_f32_e32 v208, v61, v181
	v_mul_f32_e32 v181, v19, v181
	v_add_f32_e32 v173, v173, v175
	v_fmac_f32_e32 v178, v100, v180
	v_mul_f32_e32 v179, v99, v183
	v_fmac_f32_e32 v206, v46, v180
	v_mul_f32_e32 v207, v41, v183
	v_fmac_f32_e32 v208, v60, v180
	v_mul_f32_e32 v209, v57, v183
	v_fmac_f32_e32 v181, v18, v180
	v_mul_f32_e32 v180, v17, v183
	v_add_f32_e32 v175, v184, v185
	v_add_f32_e32 v184, v190, v191
	v_add_f32_e32 v173, 0, v173
	v_fmac_f32_e32 v179, v98, v182
	v_fmac_f32_e32 v207, v40, v182
	v_fmac_f32_e32 v209, v56, v182
	v_fmac_f32_e32 v180, v16, v182
	v_add_f32_e32 v182, v186, v187
	v_add_f32_e32 v173, v173, v184
	v_add_f32_e32 v184, v192, v193
	v_add_f32_e32 v175, 0, v175
	v_add_f32_e32 v183, v188, v189
	v_add_f32_e32 v175, v175, v184
	v_add_f32_e32 v184, v196, v197
	v_add_f32_e32 v182, 0, v182
	v_add_f32_e32 v182, v182, v184
	v_add_f32_e32 v184, v198, v199
	v_add_f32_e32 v183, 0, v183
	v_add_f32_e32 v183, v183, v184
	v_add_f32_e32 v184, v200, v201
	v_add_f32_e32 v176, v177, v176
	v_add_f32_e32 v173, v173, v184
	v_add_f32_e32 v184, v202, v203
	v_add_f32_e32 v177, v183, v176
	v_add_f32_e32 v176, v178, v179
	v_add_f32_e32 v175, v175, v184
	v_add_f32_e32 v184, v204, v205
	v_add_f32_e32 v186, v173, v176
	v_add_f32_e32 v173, v206, v207
	v_add_f32_e32 v182, v182, v184
	v_add_f32_e32 v176, v175, v173
	v_add_f32_e32 v173, v208, v209
	v_add_f32_e32 v175, v182, v173
	v_add_f32_e32 v173, v181, v180
	v_add_f32_e32 v173, v177, v173
	ds_read_b128 v[178:181], v118 offset:61440
	ds_read_b128 v[182:185], v118 offset:62464
	s_waitcnt lgkmcnt(1)
; #define LAS __attribute__((address_space(3)))
; __device__ __forceinline__ void phase_prologue(const Params& P, LAS unsigned char* lds) {
;     ...
;         for (int r = 0; r < 16; ++r) {
;             float sacc[RP];
; #pragma unroll
;             for (int q = 0; q < RP; ++q) sacc[q] = 0.f;
; #pragma unroll
;             for (int j = 0; j < 4; ++j) { const f32x4 wv = *(const LAS f32x4*)(Wl + r * 1024 + 4 * lane + 256 * j);
; #pragma unroll
;                 for (int q = 0; q < RP; ++q) sacc[q] += (v[q][j][0] * wv[0] + v[q][j][1] * wv[1]) + (v[q][j][2] * wv[2] + v[q][j][3] * wv[3]); }
;             asm volatile("" : "+v"(sacc[0]), "+v"(sacc[1]), "+v"(sacc[2]), "+v"(sacc[3]) :: "memory");
; #pragma unroll
;             for (int q = 0; q < RP; ++q) a[q][r] = sacc[q];
;         }
; #pragma unroll
;         for (int q = 0; q < RP; ++q) {
;             float r8[8], r4[4], r2[2], r1;
;             const bool h5 = lane & 32, h4 = lane & 16, h3 = lane & 8, h2 = lane & 4;
; #pragma unroll
;             for (int i = 0; i < 8; ++i) r8[i] = (h5 ? a[q][i + 8] : a[q][i]) + __shfl_xor(h5 ? a[q][i] : a[q][i + 8], 32);
; #pragma unroll
;             for (int i = 0; i < 4; ++i) r4[i] = (h4 ? r8[i + 4] : r8[i]) + __shfl_xor(h4 ? r8[i] : r8[i + 4], 16);
; #pragma unroll
;             for (int i = 0; i < 2; ++i) r2[i] = (h3 ? r4[i + 2] : r4[i]) + __shfl_xor(h3 ? r4[i] : r4[i + 2], 8);
;             r1 = (h2 ? r2[1] : r2[0]) + __shfl_xor(h2 ? r2[0] : r2[1], 4);
;             r1 += __shfl_xor(r1, 2); r1 += __shfl_xor(r1, 1);
;             if ((lane & 3) == 0) LR[(size_t)(m0 + q * NGW) * 16 + (lane >> 2)] = r1;
	v_mul_f32_e32 v39, v39, v179
	v_fmac_f32_e32 v39, v38, v178
	v_mul_f32_e32 v38, v53, v181
	v_fmac_f32_e32 v38, v52, v180
	v_mul_f32_e32 v52, v31, v179
	v_mul_f32_e32 v53, v29, v181
	s_waitcnt lgkmcnt(0)
	v_mul_f32_e32 v35, v35, v183
	v_fmac_f32_e32 v52, v30, v178
	v_fmac_f32_e32 v53, v28, v180
	v_fmac_f32_e32 v35, v34, v182
	v_mul_f32_e32 v34, v49, v185
	ds_read_b128 v[28:31], v118 offset:63488
	v_fmac_f32_e32 v34, v48, v184
	v_mul_f32_e32 v48, v27, v183
	v_mul_f32_e32 v49, v25, v185
	v_fmac_f32_e32 v48, v26, v182
	v_fmac_f32_e32 v49, v24, v184
	ds_read_b128 v[24:27], v118 offset:64512
	v_mul_f32_e32 v33, v33, v185
	v_fmac_f32_e32 v33, v32, v184
	v_mul_f32_e32 v32, v51, v183
	s_waitcnt lgkmcnt(1)
	v_mul_f32_e32 v45, v45, v29
	v_mul_f32_e32 v43, v43, v31
	v_mul_f32_e32 v37, v37, v181
	v_fmac_f32_e32 v32, v50, v182
	v_mul_f32_e32 v50, v97, v29
	v_mul_f32_e32 v51, v95, v31
	v_fmac_f32_e32 v45, v44, v28
	v_fmac_f32_e32 v43, v42, v30
	v_mul_f32_e32 v42, v63, v29
	v_mul_f32_e32 v44, v59, v31
	v_mul_f32_e32 v23, v23, v29
	v_mul_f32_e32 v21, v21, v31
	v_mul_f32_e32 v109, v109, v179
	v_mul_f32_e32 v107, v107, v181
	v_fmac_f32_e32 v37, v36, v180
	v_mul_f32_e32 v36, v55, v179
	v_fmac_f32_e32 v50, v96, v28
	v_fmac_f32_e32 v51, v94, v30
	v_fmac_f32_e32 v42, v62, v28
	v_fmac_f32_e32 v44, v58, v30
	v_fmac_f32_e32 v23, v22, v28
	v_fmac_f32_e32 v21, v20, v30
	s_waitcnt lgkmcnt(0)
	v_mul_f32_e32 v20, v101, v25
	v_mul_f32_e32 v28, v47, v25
	v_mul_f32_e32 v30, v61, v25
	v_mul_f32_e32 v19, v19, v25
	v_fmac_f32_e32 v109, v108, v178
	v_fmac_f32_e32 v107, v106, v180
	v_fmac_f32_e32 v36, v54, v178
	v_mul_f32_e32 v54, v105, v183
	v_mul_f32_e32 v55, v103, v185
	v_fmac_f32_e32 v20, v100, v24
	v_fmac_f32_e32 v28, v46, v24
	v_fmac_f32_e32 v30, v60, v24
	v_fmac_f32_e32 v19, v18, v24
	v_mul_f32_e32 v24, v17, v27
	v_fmac_f32_e32 v54, v104, v182
	v_fmac_f32_e32 v55, v102, v184
	v_mul_f32_e32 v22, v99, v27
	v_mul_f32_e32 v29, v41, v27
	v_mul_f32_e32 v31, v57, v27
	v_fmac_f32_e32 v24, v16, v26
	v_add_f32_e32 v16, v109, v107
	v_fmac_f32_e32 v22, v98, v26
	v_fmac_f32_e32 v29, v40, v26
	v_fmac_f32_e32 v31, v56, v26
	v_add_f32_e32 v17, v39, v37
	v_add_f32_e32 v26, v54, v55
	v_add_f32_e32 v16, 0, v16
	v_add_f32_e32 v18, v36, v38
	v_add_f32_e32 v16, v16, v26
	v_add_f32_e32 v26, v35, v33
	v_add_f32_e32 v17, 0, v17
	v_add_f32_e32 v25, v52, v53
	v_add_f32_e32 v17, v17, v26
	v_add_f32_e32 v26, v32, v34
	v_add_f32_e32 v18, 0, v18
	v_add_f32_e32 v18, v18, v26
	v_add_f32_e32 v26, v48, v49
	v_add_f32_e32 v25, 0, v25
	v_add_f32_e32 v25, v25, v26
	v_add_f32_e32 v26, v50, v51
	v_add_f32_e32 v16, v16, v26
	v_add_f32_e32 v26, v45, v43
	v_add_f32_e32 v17, v17, v26
	v_add_f32_e32 v26, v42, v44
	v_add_f32_e32 v26, v18, v26
	v_add_f32_e32 v18, v23, v21
	v_add_f32_e32 v21, v25, v18
	v_add_f32_e32 v18, v20, v22
	v_add_f32_e32 v20, v16, v18
	v_add_f32_e32 v16, v28, v29
	v_add_f32_e32 v18, v17, v16
	v_add_f32_e32 v16, v30, v31
	v_add_f32_e32 v17, v26, v16
	v_add_f32_e32 v16, v19, v24
	v_add_f32_e32 v16, v21, v16
	v_cndmask_b32_e64 v21, v122, v154, s[4:5]
	ds_bpermute_b32 v21, v117, v21
	v_cndmask_b32_e64 v22, v126, v158, s[4:5]
	ds_bpermute_b32 v22, v117, v22
	v_cndmask_b32_e64 v23, v130, v162, s[4:5]
	ds_bpermute_b32 v23, v117, v23
	v_cndmask_b32_e64 v24, v134, v166, s[4:5]
	ds_bpermute_b32 v24, v117, v24
	v_cndmask_b32_e64 v25, v138, v170, s[4:5]
	v_cndmask_b32_e64 v19, v154, v122, s[4:5]
	ds_bpermute_b32 v25, v117, v25
	v_cndmask_b32_e64 v26, v142, v174, s[4:5]
	s_waitcnt lgkmcnt(4)
	v_add_f32_e32 v19, v19, v21
	v_cndmask_b32_e64 v21, v158, v126, s[4:5]
	ds_bpermute_b32 v26, v117, v26
	v_cndmask_b32_e64 v27, v146, v186, s[4:5]
	s_waitcnt lgkmcnt(4)
	v_add_f32_e32 v21, v21, v22
	v_cndmask_b32_e64 v28, v149, v20, s[4:5]
	v_cndmask_b32_e64 v22, v162, v130, s[4:5]
	ds_bpermute_b32 v27, v117, v27
	ds_bpermute_b32 v28, v117, v28
	s_waitcnt lgkmcnt(5)
	v_add_f32_e32 v22, v22, v23
	v_cndmask_b32_e64 v23, v166, v134, s[4:5]
	s_waitcnt lgkmcnt(4)
	v_add_f32_e32 v23, v23, v24
	v_cndmask_b32_e64 v24, v170, v138, s[4:5]
	s_waitcnt lgkmcnt(3)
	v_add_f32_e32 v24, v24, v25
	v_cndmask_b32_e64 v25, v174, v142, s[4:5]
	s_waitcnt lgkmcnt(2)
	v_add_f32_e32 v25, v25, v26
	v_cndmask_b32_e64 v26, v186, v146, s[4:5]
	v_cndmask_b32_e64 v20, v20, v149, s[4:5]
	s_waitcnt lgkmcnt(1)
	v_add_f32_e32 v26, v26, v27
	s_waitcnt lgkmcnt(0)
	v_add_f32_e32 v20, v20, v28
	v_cndmask_b32_e64 v29, v19, v24, s[6:7]
	v_cndmask_b32_e64 v19, v24, v19, s[6:7]
	v_cndmask_b32_e64 v24, v25, v21, s[6:7]
	v_cndmask_b32_e64 v21, v21, v25, s[6:7]
	v_cndmask_b32_e64 v25, v22, v26, s[6:7]
	v_cndmask_b32_e64 v27, v23, v20, s[6:7]
	ds_bpermute_b32 v29, v116, v29
	ds_bpermute_b32 v21, v116, v21
	ds_bpermute_b32 v25, v116, v25
	ds_bpermute_b32 v27, v116, v27
	v_cndmask_b32_e64 v22, v26, v22, s[6:7]
	v_cndmask_b32_e64 v20, v20, v23, s[6:7]
	s_waitcnt lgkmcnt(3)
	v_add_f32_e32 v19, v19, v29
	s_waitcnt lgkmcnt(2)
	v_add_f32_e32 v21, v24, v21
	s_waitcnt lgkmcnt(1)
	v_add_f32_e32 v22, v22, v25
	s_waitcnt lgkmcnt(0)
	v_add_f32_e32 v20, v20, v27
	v_cndmask_b32_e64 v23, v19, v22, s[8:9]
	v_cndmask_b32_e64 v24, v21, v20, s[8:9]
	ds_bpermute_b32 v23, v115, v23
	ds_bpermute_b32 v24, v115, v24
	v_cndmask_b32_e64 v19, v22, v19, s[8:9]
	v_cndmask_b32_e64 v20, v20, v21, s[8:9]
	s_waitcnt lgkmcnt(1)
	v_add_f32_e32 v19, v19, v23
	s_waitcnt lgkmcnt(0)
	v_add_f32_e32 v20, v20, v24
	v_cndmask_b32_e64 v21, v19, v20, s[10:11]
	ds_bpermute_b32 v21, v114, v21
	v_cndmask_b32_e64 v19, v20, v19, s[10:11]
	s_waitcnt lgkmcnt(0)
	v_add_f32_e32 v19, v19, v21
	ds_bpermute_b32 v20, v113, v19
	s_waitcnt lgkmcnt(0)
	v_add_f32_e32 v19, v19, v20
	ds_bpermute_b32 v20, v112, v19
	s_and_saveexec_b64 s[14:15], s[12:13]
	s_cbranch_execz .LBB0_102
	s_waitcnt lgkmcnt(0)
	v_add_f32_e32 v19, v19, v20
	v_lshl_add_u64 v[20:21], v[88:89], 0, v[86:87]
	global_store_dword v[20:21], v19, off

; #define LAS __attribute__((address_space(3)))
; __device__ __forceinline__ float bf2f(unsigned b) { return __uint_as_float(b << 16); }
; __device__ __forceinline__ unsigned f2bf(float f) { unsigned u = __float_as_uint(f); return (u + 0x7fffu + ((u >> 16) & 1u)) >> 16; }
; __device__ __forceinline__ void split8(const f32x4 x0, const f32x4 x1, bf16x8& hi, bf16x8& lo) {
; #pragma unroll
;     for (int j = 0; j < 8; ++j) { const float x = j < 4 ? x0[j & 3] : x1[j & 3]; const unsigned h = f2bf(x); const unsigned l = f2bf(x - bf2f(h)); hi[j] = (short)h; lo[j] = (short)l; }
; }
; __device__ __forceinline__ void phase_gla_pre(const Params& P, LAS unsigned char* lds, bool dry) {
;     ...
;         bf16x8 bhi = (bf16x8){0, 0, 0, 0, 0, 0, 0, 0}, blo = bhi;
;         if (g < 2) { f32x4 w0, w1;
; #pragma unroll
;             for (int j = 0; j < 4; ++j) { w0[j] = P.w_gate_up[(8 * g + j) * 512 + h * 128 + 16 * w + fr]; w1[j] = P.w_gate_up[(8 * g + 4 + j) * 512 + h * 128 + 16 * w + fr]; }
;             split8(w0, w1, bhi, blo); }
;         const float bg = P.b_gate_up[h * 128 + 16 * w + fr];
;         __syncthreads();
;         float run = 0.f;
; #pragma unroll
;         for (int tt = 0; tt < 4; ++tt) {
;             bf16x8 ahi = (bf16x8){0, 0, 0, 0, 0, 0, 0, 0}, alo = ahi;
;             if (g < 2) { const f32x4 l0 = *(const LAS f32x4*)(Llr + (16 * tt + fr) * 16 + 8 * g), l1 = *(const LAS f32x4*)(Llr + (16 * tt + fr) * 16 + 8 * g + 4); split8(l0, l1, ahi, alo); }
.Lp2_join:
	v_mov_b32_e32 v33, 0
	v_mov_b32_e32 v34, 0
	v_mov_b32_e32 v35, 0
	v_mov_b32_e32 v36, 0
	v_mov_b32_e32 v37, 0
	v_mov_b32_e32 v38, 0
	v_mov_b32_e32 v39, 0
	s_waitcnt lgkmcnt(0)
	s_barrier
	s_and_saveexec_b64 s[36:37], s[6:7]
	s_cbranch_execz .LBB0_486
	ds_read_b128 v[30:33], v96
	ds_read_b128 v[34:37], v96 offset:16
	s_waitcnt lgkmcnt(1)
	v_and_b32_sdwa v29, v31, v95 dst_sel:DWORD dst_unused:UNUSED_PAD src0_sel:WORD_1 src1_sel:DWORD
	v_and_b32_sdwa v38, v30, v95 dst_sel:DWORD dst_unused:UNUSED_PAD src0_sel:WORD_1 src1_sel:DWORD
	v_add3_u32 v29, v31, v29, s86
	v_add3_u32 v40, v30, v38, s86
	v_and_b32_e32 v39, 0xffff0000, v29
	v_and_b32_e32 v38, 0xffff0000, v40
	v_cvt_pk_bf16_f32 v186, v30, v31
	v_pk_add_f32 v[30:31], v[30:31], v[38:39] neg_lo:[0,1] neg_hi:[0,1]
	v_and_b32_sdwa v38, v33, v95 dst_sel:DWORD dst_unused:UNUSED_PAD src0_sel:WORD_1 src1_sel:DWORD
	v_and_b32_sdwa v39, v32, v95 dst_sel:DWORD dst_unused:UNUSED_PAD src0_sel:WORD_1 src1_sel:DWORD
	v_add3_u32 v41, v33, v38, s86
	v_add3_u32 v42, v32, v39, s86
	v_and_b32_e32 v39, 0xffff0000, v41
	v_and_b32_e32 v38, 0xffff0000, v42
	v_cvt_pk_bf16_f32 v187, v32, v33
	v_pk_add_f32 v[32:33], v[32:33], v[38:39] neg_lo:[0,1] neg_hi:[0,1]
	s_waitcnt lgkmcnt(0)
	v_and_b32_sdwa v38, v35, v95 dst_sel:DWORD dst_unused:UNUSED_PAD src0_sel:WORD_1 src1_sel:DWORD
	v_and_b32_sdwa v39, v34, v95 dst_sel:DWORD dst_unused:UNUSED_PAD src0_sel:WORD_1 src1_sel:DWORD
	v_add3_u32 v43, v35, v38, s86
	v_add3_u32 v44, v34, v39, s86
	v_and_b32_e32 v39, 0xffff0000, v43
	v_and_b32_e32 v38, 0xffff0000, v44
	v_cvt_pk_bf16_f32 v188, v34, v35
	v_pk_add_f32 v[34:35], v[34:35], v[38:39] neg_lo:[0,1] neg_hi:[0,1]
	v_and_b32_sdwa v38, v37, v95 dst_sel:DWORD dst_unused:UNUSED_PAD src0_sel:WORD_1 src1_sel:DWORD
	v_and_b32_sdwa v39, v36, v95 dst_sel:DWORD dst_unused:UNUSED_PAD src0_sel:WORD_1 src1_sel:DWORD
	v_add3_u32 v45, v37, v38, s86
	v_add3_u32 v46, v36, v39, s86
	v_and_b32_e32 v39, 0xffff0000, v45
	v_and_b32_e32 v38, 0xffff0000, v46
	v_cvt_pk_bf16_f32 v189, v36, v37
	v_pk_add_f32 v[36:37], v[36:37], v[38:39] neg_lo:[0,1] neg_hi:[0,1]
	s_nop 0
	v_cvt_pk_bf16_f32 v185, v36, v37
	v_cvt_pk_bf16_f32 v184, v34, v35
	v_cvt_pk_bf16_f32 v183, v32, v33
	v_cvt_pk_bf16_f32 v182, v30, v31
	v_mov_b32_e32 v32, v182
	v_mov_b32_e32 v33, v183
	v_mov_b32_e32 v34, v184
	v_mov_b32_e32 v35, v185
	v_mov_b32_e32 v36, v186
	v_mov_b32_e32 v37, v187
	v_mov_b32_e32 v38, v188
	v_mov_b32_e32 v39, v189

; #define LAS __attribute__((address_space(3)))
; __device__ __forceinline__ float bf2f(unsigned b) { return __uint_as_float(b << 16); }
; __device__ __forceinline__ unsigned f2bf(float f) { unsigned u = __float_as_uint(f); return (u + 0x7fffu + ((u >> 16) & 1u)) >> 16; }
; __device__ __forceinline__ void split8(const f32x4 x0, const f32x4 x1, bf16x8& hi, bf16x8& lo) {
; #pragma unroll
;     for (int j = 0; j < 8; ++j) { const float x = j < 4 ? x0[j & 3] : x1[j & 3]; const unsigned h = f2bf(x); const unsigned l = f2bf(x - bf2f(h)); hi[j] = (short)h; lo[j] = (short)l; }
; }
; __device__ __forceinline__ void phase_gla_pre(const Params& P, LAS unsigned char* lds, bool dry) {
;     ...
;         for (int tt = 0; tt < 4; ++tt) {
;             bf16x8 ahi = (bf16x8){0, 0, 0, 0, 0, 0, 0, 0}, alo = ahi;
;             if (g < 2) { const f32x4 l0 = *(const LAS f32x4*)(Llr + (16 * tt + fr) * 16 + 8 * g), l1 = *(const LAS f32x4*)(Llr + (16 * tt + fr) * 16 + 8 * g + 4); split8(l0, l1, ahi, alo); }
;             f32x4 acc = (f32x4){bg, bg, bg, bg};
;             acc = __builtin_amdgcn_mfma_f32_16x16x32_bf16(alo, bhi, acc, 0, 0, 0); acc = __builtin_amdgcn_mfma_f32_16x16x32_bf16(ahi, blo, acc, 0, 0, 0); acc = __builtin_amdgcn_mfma_f32_16x16x32_bf16(ahi, bhi, acc, 0, 0, 0);
;             float pr[4];
; #pragma unroll
;             for (int r = 0; r < 4; ++r) { const float lg = acc[r]; const float ls = fminf(lg, 0.f) - __logf(1.0f + __expf(-fabsf(lg))); pr[r] = ls * (1.0f / 16.0f) + (r ? pr[r - 1] : 0.f); }
;             const float T = pr[3];
;             const float u1 = __shfl_up(T, 16), s1 = T + (g >= 1 ? u1 : 0.f);
;             const float u2 = __shfl_up(s1, 32), s2 = s1 + (g >= 2 ? u2 : 0.f);
;             const float base = run + (s2 - T); run += __shfl(s2, 48 + fr);
; #pragma unroll
;             for (int r = 0; r < 4; ++r) *(LAS float*)(Lb + (16 * tt + 4 * g + r) * BP + (16 * w + fr) * 4) = base + pr[r];
.Lp2_nowait1:
	v_mov_b32_e32 v140, v20
	v_mov_b32_e32 v141, v21
	v_mov_b32_e32 v142, v22
	v_mov_b32_e32 v143, v23
	v_mov_b32_e32 v144, v24
	v_mov_b32_e32 v145, v25
	v_mov_b32_e32 v146, v26
	v_mov_b32_e32 v147, v27
	v_mov_b32_e32 v148, v28
	s_and_b32 s98, s38, 0xff
	s_cselect_b32 s98, 0, 1
	v_mov_b32_e32 v29, v28
	v_mov_b32_e32 v30, v28
	v_mov_b32_e32 v31, v28
	v_mov_b32_e32 v40, 0
	v_mov_b32_e32 v41, 0
	v_mfma_f32_16x16x32_bf16 v[32:35], v[32:35], v[20:23], v[28:31]
	v_mfma_f32_16x16x32_bf16 v[32:35], v[36:39], v[24:27], v[32:35]
	v_mfma_f32_16x16x32_bf16 v[32:35], v[36:39], v[20:23], v[32:35]
	s_nop 7
	v_max_f32_e32 v36, v32, v32
	v_mul_f32_e64 v32, |v32|, s89
	v_exp_f32_e32 v32, v32
	v_mul_f32_e64 v37, |v33|, s89
	v_exp_f32_e32 v37, v37
	v_min_f32_e32 v36, 0, v36
	v_add_f32_e32 v32, 1.0, v32
	v_cmp_gt_f32_e32 vcc, s90, v32
	v_add_f32_e32 v37, 1.0, v37
	v_cmp_gt_f32_e64 s[36:37], s90, v37
	v_cndmask_b32_e64 v38, 0, 32, vcc
	v_ldexp_f32 v32, v32, v38
	v_log_f32_e32 v32, v32
	v_cndmask_b32_e64 v39, 0, 32, s[36:37]
	v_ldexp_f32 v37, v37, v39
	v_log_f32_e32 v37, v37
	v_mul_f32_e32 v39, 0x3f317217, v32
	v_fma_f32 v39, v32, s91, -v39
	v_fmac_f32_e32 v39, 0x3377d1cf, v32
	v_cndmask_b32_e32 v38, 0, v97, vcc
	v_fmac_f32_e32 v39, 0x3f317217, v32
	v_cmp_lt_f32_e64 vcc, |v32|, s92
	v_max_f32_e32 v33, v33, v33
	v_min_f32_e32 v33, 0, v33
	v_cndmask_b32_e32 v32, v32, v39, vcc
	v_sub_f32_e32 v32, v32, v38
	v_sub_f32_e32 v32, v36, v32
	v_mul_f32_e32 v36, 0x3f317217, v37
	v_fma_f32 v36, v37, s91, -v36
	v_fmac_f32_e32 v36, 0x3377d1cf, v37
	v_fmac_f32_e32 v36, 0x3f317217, v37
	v_cmp_lt_f32_e64 vcc, |v37|, s92
	v_cndmask_b32_e64 v38, 0, v97, s[36:37]
	v_fma_f32 v32, v32, s93, 0
	v_cndmask_b32_e32 v36, v37, v36, vcc
	v_mul_f32_e64 v37, |v34|, s89
	v_exp_f32_e32 v37, v37
	v_sub_f32_e32 v36, v36, v38
	v_sub_f32_e32 v33, v33, v36
	v_mov_b32_e32 v39, 0
	v_add_f32_e32 v36, 1.0, v37
	v_cmp_gt_f32_e32 vcc, s90, v36
	s_nop 1
	v_cndmask_b32_e64 v37, 0, 32, vcc
	v_ldexp_f32 v36, v36, v37
	v_log_f32_e32 v36, v36
	v_fmamk_f32 v37, v33, 0x3d800000, v32
	v_max_f32_e32 v33, v34, v34
	v_cndmask_b32_e32 v38, 0, v97, vcc
	v_mul_f32_e32 v34, 0x3f317217, v36
	v_fma_f32 v34, v36, s91, -v34
	v_fmac_f32_e32 v34, 0x3377d1cf, v36
	v_fmac_f32_e32 v34, 0x3f317217, v36
	v_cmp_lt_f32_e64 s[36:37], |v36|, s92
	v_min_f32_e32 v33, 0, v33
	s_nop 0
	v_cndmask_b32_e64 v34, v36, v34, s[36:37]
	v_mul_f32_e64 v36, |v35|, s89
	v_exp_f32_e32 v36, v36
	v_sub_f32_e32 v34, v34, v38
	v_sub_f32_e32 v33, v33, v34
	v_add_u32_e32 v38, 0x8800, v98
	v_add_f32_e32 v34, 1.0, v36
	v_cmp_gt_f32_e32 vcc, s90, v34
	s_nop 1
	v_cndmask_b32_e64 v36, 0, 32, vcc
	v_ldexp_f32 v34, v34, v36
	v_log_f32_e32 v34, v34
	v_fmamk_f32 v36, v33, 0x3d800000, v37
	v_max_f32_e32 v33, v35, v35
	v_min_f32_e32 v33, 0, v33
	v_mul_f32_e32 v35, 0x3f317217, v34
	v_fma_f32 v35, v34, s91, -v35
	v_fmac_f32_e32 v35, 0x3377d1cf, v34
	v_fmac_f32_e32 v35, 0x3f317217, v34
	v_cmp_lt_f32_e64 s[36:37], |v34|, s92
	s_nop 1
	v_cndmask_b32_e64 v34, v34, v35, s[36:37]
	v_cndmask_b32_e32 v35, 0, v97, vcc
	v_sub_f32_e32 v34, v34, v35
	v_sub_f32_e32 v33, v33, v34
	v_fmamk_f32 v34, v33, 0x3d800000, v36
	ds_bpermute_b32 v33, v83, v34
	s_waitcnt lgkmcnt(0)
	v_cndmask_b32_e64 v33, v33, 0, s[8:9]
	v_add_f32_e32 v33, v33, v34
	ds_bpermute_b32 v35, v84, v33
	s_waitcnt lgkmcnt(0)
	v_cndmask_b32_e64 v35, 0, v35, s[10:11]
	v_add_f32_e32 v33, v35, v33
	v_sub_f32_e32 v35, v33, v34
	ds_bpermute_b32 v33, v85, v33
	v_add_f32_e32 v35, 0, v35
	v_add_f32_e32 v32, v32, v35
	v_add_f32_e32 v37, v37, v35
	ds_write2_b32 v38, v32, v37 offset1:132
	v_add_f32_e32 v32, v36, v35
	v_add_f32_e32 v34, v34, v35
	v_add_u32_e32 v35, 0x8c00, v98
	ds_write2_b32 v35, v32, v34 offset0:8 offset1:140
	v_mov_b32_e32 v32, 0
	v_mov_b32_e32 v34, 0
	v_mov_b32_e32 v35, 0
	v_mov_b32_e32 v36, 0
	v_mov_b32_e32 v37, 0
	v_mov_b32_e32 v38, 0
	s_and_saveexec_b64 s[36:37], s[6:7]
	s_cbranch_execz .LBB0_488
	ds_read_b128 v[34:37], v96 offset:1024
	ds_read_b128 v[38:41], v96 offset:1040
	s_waitcnt lgkmcnt(1)
	v_and_b32_sdwa v42, v35, v95 dst_sel:DWORD dst_unused:UNUSED_PAD src0_sel:WORD_1 src1_sel:DWORD
	v_and_b32_sdwa v43, v34, v95 dst_sel:DWORD dst_unused:UNUSED_PAD src0_sel:WORD_1 src1_sel:DWORD
	v_add3_u32 v44, v35, v42, s86
	v_add3_u32 v45, v34, v43, s86
	v_and_b32_e32 v43, 0xffff0000, v44
	v_and_b32_e32 v42, 0xffff0000, v45
	v_cvt_pk_bf16_f32 v196, v34, v35
	v_pk_add_f32 v[34:35], v[34:35], v[42:43] neg_lo:[0,1] neg_hi:[0,1]
	v_and_b32_sdwa v42, v37, v95 dst_sel:DWORD dst_unused:UNUSED_PAD src0_sel:WORD_1 src1_sel:DWORD
	v_and_b32_sdwa v43, v36, v95 dst_sel:DWORD dst_unused:UNUSED_PAD src0_sel:WORD_1 src1_sel:DWORD
	v_add3_u32 v46, v37, v42, s86
	v_add3_u32 v47, v36, v43, s86
	v_and_b32_e32 v43, 0xffff0000, v46
	v_and_b32_e32 v42, 0xffff0000, v47
	v_cvt_pk_bf16_f32 v197, v36, v37
	v_pk_add_f32 v[36:37], v[36:37], v[42:43] neg_lo:[0,1] neg_hi:[0,1]
	s_waitcnt lgkmcnt(0)
	v_and_b32_sdwa v42, v39, v95 dst_sel:DWORD dst_unused:UNUSED_PAD src0_sel:WORD_1 src1_sel:DWORD
	v_and_b32_sdwa v43, v38, v95 dst_sel:DWORD dst_unused:UNUSED_PAD src0_sel:WORD_1 src1_sel:DWORD
	v_add3_u32 v60, v39, v42, s86
	v_add3_u32 v61, v38, v43, s86
	v_and_b32_e32 v43, 0xffff0000, v60
	v_and_b32_e32 v42, 0xffff0000, v61
	v_cvt_pk_bf16_f32 v198, v38, v39
	v_pk_add_f32 v[38:39], v[38:39], v[42:43] neg_lo:[0,1] neg_hi:[0,1]
	v_and_b32_sdwa v42, v41, v95 dst_sel:DWORD dst_unused:UNUSED_PAD src0_sel:WORD_1 src1_sel:DWORD
	v_and_b32_sdwa v43, v40, v95 dst_sel:DWORD dst_unused:UNUSED_PAD src0_sel:WORD_1 src1_sel:DWORD
	v_add3_u32 v62, v41, v42, s86
	v_add3_u32 v63, v40, v43, s86
	v_and_b32_e32 v43, 0xffff0000, v62
	v_and_b32_e32 v42, 0xffff0000, v63
	v_cvt_pk_bf16_f32 v199, v40, v41
	v_pk_add_f32 v[40:41], v[40:41], v[42:43] neg_lo:[0,1] neg_hi:[0,1]
	s_nop 0
	v_cvt_pk_bf16_f32 v193, v40, v41
	v_cvt_pk_bf16_f32 v192, v38, v39
	v_cvt_pk_bf16_f32 v191, v36, v37
	v_cvt_pk_bf16_f32 v190, v34, v35
	v_mov_b32_e32 v34, v190
	v_mov_b32_e32 v35, v191
	v_mov_b32_e32 v36, v192
	v_mov_b32_e32 v37, v193
	v_mov_b32_e32 v38, v196
	v_mov_b32_e32 v39, v197
	v_mov_b32_e32 v40, v198
	v_mov_b32_e32 v41, v199
; #define LAS __attribute__((address_space(3)))
; __device__ __forceinline__ float bf2f(unsigned b) { return __uint_as_float(b << 16); }
; __device__ __forceinline__ unsigned f2bf(float f) { unsigned u = __float_as_uint(f); return (u + 0x7fffu + ((u >> 16) & 1u)) >> 16; }
; __device__ __forceinline__ void split8(const f32x4 x0, const f32x4 x1, bf16x8& hi, bf16x8& lo) {
; #pragma unroll
;     for (int j = 0; j < 8; ++j) { const float x = j < 4 ? x0[j & 3] : x1[j & 3]; const unsigned h = f2bf(x); const unsigned l = f2bf(x - bf2f(h)); hi[j] = (short)h; lo[j] = (short)l; }
; }
; __device__ __forceinline__ void phase_gla_pre(const Params& P, LAS unsigned char* lds, bool dry) {
;     ...
;         for (int tt = 0; tt < 4; ++tt) {
;             bf16x8 ahi = (bf16x8){0, 0, 0, 0, 0, 0, 0, 0}, alo = ahi;
;             if (g < 2) { const f32x4 l0 = *(const LAS f32x4*)(Llr + (16 * tt + fr) * 16 + 8 * g), l1 = *(const LAS f32x4*)(Llr + (16 * tt + fr) * 16 + 8 * g + 4); split8(l0, l1, ahi, alo); }
;             f32x4 acc = (f32x4){bg, bg, bg, bg};
;             acc = __builtin_amdgcn_mfma_f32_16x16x32_bf16(alo, bhi, acc, 0, 0, 0); acc = __builtin_amdgcn_mfma_f32_16x16x32_bf16(ahi, blo, acc, 0, 0, 0); acc = __builtin_amdgcn_mfma_f32_16x16x32_bf16(ahi, bhi, acc, 0, 0, 0);
;             float pr[4];
; #pragma unroll
;             for (int r = 0; r < 4; ++r) { const float lg = acc[r]; const float ls = fminf(lg, 0.f) - __logf(1.0f + __expf(-fabsf(lg))); pr[r] = ls * (1.0f / 16.0f) + (r ? pr[r - 1] : 0.f); }
;             const float T = pr[3];
;             const float u1 = __shfl_up(T, 16), s1 = T + (g >= 1 ? u1 : 0.f);
;             const float u2 = __shfl_up(s1, 32), s2 = s1 + (g >= 2 ? u2 : 0.f);
;             const float base = run + (s2 - T); run += __shfl(s2, 48 + fr);
; #pragma unroll
;             for (int r = 0; r < 4; ++r) *(LAS float*)(Lb + (16 * tt + 4 * g + r) * BP + (16 * w + fr) * 4) = base + pr[r];
.LBB0_488:
	s_or_b64 exec, exec, s[36:37]
	v_mfma_f32_16x16x32_bf16 v[34:37], v[34:37], v[20:23], v[28:31]
	v_mfma_f32_16x16x32_bf16 v[34:37], v[38:41], v[24:27], v[34:37]
	v_mfma_f32_16x16x32_bf16 v[34:37], v[38:41], v[20:23], v[34:37]
	s_nop 7
	v_max_f32_e32 v38, v34, v34
	v_mul_f32_e64 v34, |v34|, s89
	v_exp_f32_e32 v34, v34
	v_mul_f32_e64 v39, |v35|, s89
	v_exp_f32_e32 v39, v39
	v_min_f32_e32 v38, 0, v38
	v_add_f32_e32 v34, 1.0, v34
	v_cmp_gt_f32_e32 vcc, s90, v34
	v_add_f32_e32 v39, 1.0, v39
	v_cmp_gt_f32_e64 s[36:37], s90, v39
	v_cndmask_b32_e64 v40, 0, 32, vcc
	v_ldexp_f32 v34, v34, v40
	v_log_f32_e32 v34, v34
	v_cndmask_b32_e64 v41, 0, 32, s[36:37]
	v_ldexp_f32 v39, v39, v41
	v_log_f32_e32 v39, v39
	v_mul_f32_e32 v41, 0x3f317217, v34
	v_fma_f32 v41, v34, s91, -v41
	v_fmac_f32_e32 v41, 0x3377d1cf, v34
	v_cndmask_b32_e32 v40, 0, v97, vcc
	v_fmac_f32_e32 v41, 0x3f317217, v34
	v_cmp_lt_f32_e64 vcc, |v34|, s92
	v_mul_f32_e32 v42, 0x3f317217, v39
	v_max_f32_e32 v35, v35, v35
	v_cndmask_b32_e32 v34, v34, v41, vcc
	v_sub_f32_e32 v34, v34, v40
	v_sub_f32_e32 v34, v38, v34
	v_fma_f32 v38, v39, s91, -v42
	v_fmac_f32_e32 v38, 0x3377d1cf, v39
	v_fmac_f32_e32 v38, 0x3f317217, v39
	v_cmp_lt_f32_e64 vcc, |v39|, s92
	v_cndmask_b32_e64 v40, 0, v97, s[36:37]
	v_min_f32_e32 v35, 0, v35
	v_cndmask_b32_e32 v38, v39, v38, vcc
	v_mul_f32_e64 v39, |v36|, s89
	v_exp_f32_e32 v39, v39
	v_sub_f32_e32 v38, v38, v40
	v_sub_f32_e32 v35, v35, v38
	v_max_f32_e32 v36, v36, v36
	v_add_f32_e32 v38, 1.0, v39
	v_cmp_gt_f32_e32 vcc, s90, v38
	v_min_f32_e32 v36, 0, v36
	v_fma_f32 v34, v34, s93, 0
	v_cndmask_b32_e64 v39, 0, 32, vcc
	v_ldexp_f32 v38, v38, v39
	v_log_f32_e32 v38, v38
	v_cndmask_b32_e32 v40, 0, v97, vcc
	v_fmamk_f32 v35, v35, 0x3d800000, v34
	v_mul_f32_e32 v39, 0x3f317217, v38
	v_fma_f32 v39, v38, s91, -v39
	v_fmac_f32_e32 v39, 0x3377d1cf, v38
	v_fmac_f32_e32 v39, 0x3f317217, v38
	v_cmp_lt_f32_e64 s[36:37], |v38|, s92
	s_nop 1
	v_cndmask_b32_e64 v38, v38, v39, s[36:37]
	v_mul_f32_e64 v39, |v37|, s89
	v_exp_f32_e32 v39, v39
	v_sub_f32_e32 v38, v38, v40
	v_sub_f32_e32 v36, v36, v38
	v_max_f32_e32 v37, v37, v37
	v_add_f32_e32 v38, 1.0, v39
	v_cmp_gt_f32_e32 vcc, s90, v38
	v_min_f32_e32 v37, 0, v37
	v_fmamk_f32 v36, v36, 0x3d800000, v35
	v_cndmask_b32_e64 v39, 0, 32, vcc
	v_ldexp_f32 v38, v38, v39
	v_log_f32_e32 v38, v38
	s_waitcnt lgkmcnt(2)
	v_add_f32_e32 v40, 0, v33
	v_mul_f32_e32 v39, 0x3f317217, v38
	v_fma_f32 v39, v38, s91, -v39
	v_fmac_f32_e32 v39, 0x3377d1cf, v38
	v_fmac_f32_e32 v39, 0x3f317217, v38
	v_cmp_lt_f32_e64 s[36:37], |v38|, s92
	s_nop 1
	v_cndmask_b32_e64 v38, v38, v39, s[36:37]
	v_cndmask_b32_e32 v39, 0, v97, vcc
	v_sub_f32_e32 v38, v38, v39
	v_sub_f32_e32 v37, v37, v38
	v_fmamk_f32 v37, v37, 0x3d800000, v36
	ds_bpermute_b32 v38, v83, v37
	s_waitcnt lgkmcnt(0)
	v_cndmask_b32_e64 v38, v38, 0, s[8:9]
	v_add_f32_e32 v38, v38, v37
	ds_bpermute_b32 v39, v84, v38
	s_waitcnt lgkmcnt(0)
	v_cndmask_b32_e64 v33, 0, v39, s[10:11]
	v_add_f32_e32 v33, v33, v38
	v_sub_f32_e32 v38, v33, v37
	ds_bpermute_b32 v41, v85, v33
	v_add_f32_e32 v38, v40, v38
	v_add_f32_e32 v33, v34, v38
	v_add_f32_e32 v34, v35, v38
	v_add_u32_e32 v35, 0xa800, v98
	ds_write2_b32 v35, v33, v34 offset0:64 offset1:196
	v_add_f32_e32 v33, v36, v38
	v_add_f32_e32 v34, v37, v38
	v_add_u32_e32 v35, 0xac00, v98
	ds_write2_b32 v35, v33, v34 offset0:72 offset1:204
	v_mov_b32_e32 v33, 0
	v_mov_b32_e32 v34, 0
	v_mov_b32_e32 v35, 0
	v_mov_b32_e32 v36, 0
	v_mov_b32_e32 v37, 0
	v_mov_b32_e32 v38, 0
	v_mov_b32_e32 v39, 0
	s_and_saveexec_b64 s[36:37], s[6:7]
	s_cbranch_execz .LBB0_490
	ds_read_b128 v[32:35], v96 offset:2048
	ds_read_b128 v[36:39], v96 offset:2064
	s_waitcnt lgkmcnt(1)
	v_and_b32_sdwa v42, v33, v95 dst_sel:DWORD dst_unused:UNUSED_PAD src0_sel:WORD_1 src1_sel:DWORD
	v_and_b32_sdwa v43, v32, v95 dst_sel:DWORD dst_unused:UNUSED_PAD src0_sel:WORD_1 src1_sel:DWORD
	v_add3_u32 v44, v33, v42, s86
	v_add3_u32 v45, v32, v43, s86
	v_and_b32_e32 v43, 0xffff0000, v44
	v_and_b32_e32 v42, 0xffff0000, v45
	v_cvt_pk_bf16_f32 v204, v32, v33
	v_pk_add_f32 v[32:33], v[32:33], v[42:43] neg_lo:[0,1] neg_hi:[0,1]
	v_and_b32_sdwa v42, v35, v95 dst_sel:DWORD dst_unused:UNUSED_PAD src0_sel:WORD_1 src1_sel:DWORD
	v_and_b32_sdwa v43, v34, v95 dst_sel:DWORD dst_unused:UNUSED_PAD src0_sel:WORD_1 src1_sel:DWORD
	v_add3_u32 v46, v35, v42, s86
	v_add3_u32 v47, v34, v43, s86
	v_and_b32_e32 v43, 0xffff0000, v46
	v_and_b32_e32 v42, 0xffff0000, v47
	v_cvt_pk_bf16_f32 v205, v34, v35
	v_pk_add_f32 v[34:35], v[34:35], v[42:43] neg_lo:[0,1] neg_hi:[0,1]
	s_waitcnt lgkmcnt(0)
	v_and_b32_sdwa v42, v37, v95 dst_sel:DWORD dst_unused:UNUSED_PAD src0_sel:WORD_1 src1_sel:DWORD
	v_and_b32_sdwa v43, v36, v95 dst_sel:DWORD dst_unused:UNUSED_PAD src0_sel:WORD_1 src1_sel:DWORD
	v_add3_u32 v60, v37, v42, s86
	v_add3_u32 v61, v36, v43, s86
	v_and_b32_e32 v43, 0xffff0000, v60
	v_and_b32_e32 v42, 0xffff0000, v61
	v_cvt_pk_bf16_f32 v206, v36, v37
	v_pk_add_f32 v[36:37], v[36:37], v[42:43] neg_lo:[0,1] neg_hi:[0,1]
	v_and_b32_sdwa v42, v39, v95 dst_sel:DWORD dst_unused:UNUSED_PAD src0_sel:WORD_1 src1_sel:DWORD
	v_and_b32_sdwa v43, v38, v95 dst_sel:DWORD dst_unused:UNUSED_PAD src0_sel:WORD_1 src1_sel:DWORD
	v_add3_u32 v62, v39, v42, s86
	v_add3_u32 v63, v38, v43, s86
	v_and_b32_e32 v43, 0xffff0000, v62
	v_and_b32_e32 v42, 0xffff0000, v63
	v_cvt_pk_bf16_f32 v208, v38, v39
	v_pk_add_f32 v[38:39], v[38:39], v[42:43] neg_lo:[0,1] neg_hi:[0,1]
	s_nop 0
	v_cvt_pk_bf16_f32 v203, v38, v39
	v_cvt_pk_bf16_f32 v202, v36, v37
	v_cvt_pk_bf16_f32 v201, v34, v35
	v_cvt_pk_bf16_f32 v200, v32, v33
	v_mov_b32_e32 v32, v200
	v_mov_b32_e32 v33, v201
	v_mov_b32_e32 v34, v202
	v_mov_b32_e32 v35, v203
	v_mov_b32_e32 v36, v204
	v_mov_b32_e32 v37, v205
	v_mov_b32_e32 v38, v206
	v_mov_b32_e32 v39, v208
; #define LAS __attribute__((address_space(3)))
; __device__ __forceinline__ float bf2f(unsigned b) { return __uint_as_float(b << 16); }
; __device__ __forceinline__ unsigned f2bf(float f) { unsigned u = __float_as_uint(f); return (u + 0x7fffu + ((u >> 16) & 1u)) >> 16; }
; __device__ __forceinline__ void split8(const f32x4 x0, const f32x4 x1, bf16x8& hi, bf16x8& lo) {
; #pragma unroll
;     for (int j = 0; j < 8; ++j) { const float x = j < 4 ? x0[j & 3] : x1[j & 3]; const unsigned h = f2bf(x); const unsigned l = f2bf(x - bf2f(h)); hi[j] = (short)h; lo[j] = (short)l; }
; }
; __device__ __forceinline__ void phase_gla_pre(const Params& P, LAS unsigned char* lds, bool dry) {
;     ...
;         for (int tt = 0; tt < 4; ++tt) {
;             bf16x8 ahi = (bf16x8){0, 0, 0, 0, 0, 0, 0, 0}, alo = ahi;
;             if (g < 2) { const f32x4 l0 = *(const LAS f32x4*)(Llr + (16 * tt + fr) * 16 + 8 * g), l1 = *(const LAS f32x4*)(Llr + (16 * tt + fr) * 16 + 8 * g + 4); split8(l0, l1, ahi, alo); }
;             f32x4 acc = (f32x4){bg, bg, bg, bg};
;             acc = __builtin_amdgcn_mfma_f32_16x16x32_bf16(alo, bhi, acc, 0, 0, 0); acc = __builtin_amdgcn_mfma_f32_16x16x32_bf16(ahi, blo, acc, 0, 0, 0); acc = __builtin_amdgcn_mfma_f32_16x16x32_bf16(ahi, bhi, acc, 0, 0, 0);
;             float pr[4];
; #pragma unroll
;             for (int r = 0; r < 4; ++r) { const float lg = acc[r]; const float ls = fminf(lg, 0.f) - __logf(1.0f + __expf(-fabsf(lg))); pr[r] = ls * (1.0f / 16.0f) + (r ? pr[r - 1] : 0.f); }
;             const float T = pr[3];
;             const float u1 = __shfl_up(T, 16), s1 = T + (g >= 1 ? u1 : 0.f);
;             const float u2 = __shfl_up(s1, 32), s2 = s1 + (g >= 2 ? u2 : 0.f);
;             const float base = run + (s2 - T); run += __shfl(s2, 48 + fr);
; #pragma unroll
;             for (int r = 0; r < 4; ++r) *(LAS float*)(Lb + (16 * tt + 4 * g + r) * BP + (16 * w + fr) * 4) = base + pr[r];
.LBB0_490:
	s_or_b64 exec, exec, s[36:37]
	v_mfma_f32_16x16x32_bf16 v[32:35], v[32:35], v[20:23], v[28:31]
	s_waitcnt lgkmcnt(2)
	v_add_f32_e32 v40, v40, v41
	v_mfma_f32_16x16x32_bf16 v[32:35], v[36:39], v[24:27], v[32:35]
	v_mfma_f32_16x16x32_bf16 v[32:35], v[36:39], v[20:23], v[32:35]
	s_nop 7
	v_max_f32_e32 v36, v32, v32
	v_mul_f32_e64 v32, |v32|, s89
	v_exp_f32_e32 v32, v32
	v_mul_f32_e64 v37, |v33|, s89
	v_exp_f32_e32 v37, v37
	v_min_f32_e32 v36, 0, v36
	v_add_f32_e32 v32, 1.0, v32
	v_cmp_gt_f32_e32 vcc, s90, v32
	v_add_f32_e32 v37, 1.0, v37
	v_cmp_gt_f32_e64 s[36:37], s90, v37
	v_cndmask_b32_e64 v38, 0, 32, vcc
	v_ldexp_f32 v32, v32, v38
	v_log_f32_e32 v32, v32
	v_cndmask_b32_e64 v39, 0, 32, s[36:37]
	v_ldexp_f32 v37, v37, v39
	v_log_f32_e32 v37, v37
	v_mul_f32_e32 v39, 0x3f317217, v32
	v_fma_f32 v39, v32, s91, -v39
	v_fmac_f32_e32 v39, 0x3377d1cf, v32
	v_cndmask_b32_e32 v38, 0, v97, vcc
	v_fmac_f32_e32 v39, 0x3f317217, v32
	v_cmp_lt_f32_e64 vcc, |v32|, s92
	v_mul_f32_e32 v42, 0x3f317217, v37
	v_max_f32_e32 v33, v33, v33
	v_cndmask_b32_e32 v32, v32, v39, vcc
	v_sub_f32_e32 v32, v32, v38
	v_sub_f32_e32 v32, v36, v32
	v_fma_f32 v36, v37, s91, -v42
	v_fmac_f32_e32 v36, 0x3377d1cf, v37
	v_fmac_f32_e32 v36, 0x3f317217, v37
	v_cmp_lt_f32_e64 vcc, |v37|, s92
	v_cndmask_b32_e64 v38, 0, v97, s[36:37]
	v_min_f32_e32 v33, 0, v33
	v_cndmask_b32_e32 v36, v37, v36, vcc
	v_mul_f32_e64 v37, |v34|, s89
	v_exp_f32_e32 v37, v37
	v_sub_f32_e32 v36, v36, v38
	v_sub_f32_e32 v33, v33, v36
	v_max_f32_e32 v34, v34, v34
	v_add_f32_e32 v36, 1.0, v37
	v_cmp_gt_f32_e32 vcc, s90, v36
	v_min_f32_e32 v34, 0, v34
	v_fma_f32 v32, v32, s93, 0
	v_cndmask_b32_e64 v37, 0, 32, vcc
	v_ldexp_f32 v36, v36, v37
	v_log_f32_e32 v36, v36
	v_cndmask_b32_e32 v38, 0, v97, vcc
	v_fmamk_f32 v33, v33, 0x3d800000, v32
	v_mov_b32_e32 v39, 0
	v_mul_f32_e32 v37, 0x3f317217, v36
	v_fma_f32 v37, v36, s91, -v37
	v_fmac_f32_e32 v37, 0x3377d1cf, v36
	v_fmac_f32_e32 v37, 0x3f317217, v36
	v_cmp_lt_f32_e64 s[36:37], |v36|, s92
	s_nop 1
	v_cndmask_b32_e64 v36, v36, v37, s[36:37]
	v_mul_f32_e64 v37, |v35|, s89
	v_exp_f32_e32 v37, v37
	v_sub_f32_e32 v36, v36, v38
	v_sub_f32_e32 v34, v34, v36
	v_max_f32_e32 v35, v35, v35
	v_add_f32_e32 v36, 1.0, v37
	v_cmp_gt_f32_e32 vcc, s90, v36
	v_min_f32_e32 v35, 0, v35
	v_fmamk_f32 v34, v34, 0x3d800000, v33
	v_cndmask_b32_e64 v37, 0, 32, vcc
	v_ldexp_f32 v36, v36, v37
	v_log_f32_e32 v36, v36
	v_mov_b32_e32 v38, 0
	v_mul_f32_e32 v37, 0x3f317217, v36
	v_fma_f32 v37, v36, s91, -v37
	v_fmac_f32_e32 v37, 0x3377d1cf, v36
	v_fmac_f32_e32 v37, 0x3f317217, v36
	v_cmp_lt_f32_e64 s[36:37], |v36|, s92
	s_nop 1
	v_cndmask_b32_e64 v36, v36, v37, s[36:37]
	v_cndmask_b32_e32 v37, 0, v97, vcc
	v_sub_f32_e32 v36, v36, v37
	v_sub_f32_e32 v35, v35, v36
	v_fmamk_f32 v35, v35, 0x3d800000, v34
	ds_bpermute_b32 v36, v83, v35
	s_waitcnt lgkmcnt(0)
	v_cndmask_b32_e64 v36, v36, 0, s[8:9]
	v_add_f32_e32 v36, v36, v35
	ds_bpermute_b32 v37, v84, v36
	s_waitcnt lgkmcnt(0)
	v_cndmask_b32_e64 v37, 0, v37, s[10:11]
	v_add_f32_e32 v36, v37, v36
	v_sub_f32_e32 v37, v36, v35
	ds_bpermute_b32 v41, v85, v36
	v_add_f32_e32 v37, v40, v37
	v_add_f32_e32 v32, v32, v37
	v_add_f32_e32 v33, v33, v37
	v_add_u32_e32 v36, 0xca00, v98
	ds_write2_b32 v36, v32, v33 offset1:132
	v_add_f32_e32 v32, v34, v37
	v_add_f32_e32 v33, v35, v37
	v_add_u32_e32 v34, 0xce00, v98
	ds_write2_b32 v34, v32, v33 offset0:8 offset1:140
	v_mov_b32_e32 v32, 0
	v_mov_b32_e32 v33, 0
	v_mov_b32_e32 v34, 0
	v_mov_b32_e32 v35, 0
	v_mov_b32_e32 v36, 0
	v_mov_b32_e32 v37, 0
	s_and_saveexec_b64 s[36:37], s[6:7]
	s_cbranch_execz .LBB0_492
	ds_read_b128 v[32:35], v96 offset:3072
	ds_read_b128 v[36:39], v96 offset:3088
	s_waitcnt lgkmcnt(1)
	v_and_b32_sdwa v42, v33, v95 dst_sel:DWORD dst_unused:UNUSED_PAD src0_sel:WORD_1 src1_sel:DWORD
	v_and_b32_sdwa v43, v32, v95 dst_sel:DWORD dst_unused:UNUSED_PAD src0_sel:WORD_1 src1_sel:DWORD
	v_add3_u32 v44, v33, v42, s86
	v_add3_u32 v45, v32, v43, s86
	v_and_b32_e32 v43, 0xffff0000, v44
	v_and_b32_e32 v42, 0xffff0000, v45
	v_cvt_pk_bf16_f32 v214, v32, v33
	v_pk_add_f32 v[32:33], v[32:33], v[42:43] neg_lo:[0,1] neg_hi:[0,1]
	v_and_b32_sdwa v42, v35, v95 dst_sel:DWORD dst_unused:UNUSED_PAD src0_sel:WORD_1 src1_sel:DWORD
	v_and_b32_sdwa v43, v34, v95 dst_sel:DWORD dst_unused:UNUSED_PAD src0_sel:WORD_1 src1_sel:DWORD
	v_add3_u32 v46, v35, v42, s86
	v_add3_u32 v47, v34, v43, s86
	v_and_b32_e32 v43, 0xffff0000, v46
	v_and_b32_e32 v42, 0xffff0000, v47
	v_cvt_pk_bf16_f32 v216, v34, v35
	v_pk_add_f32 v[34:35], v[34:35], v[42:43] neg_lo:[0,1] neg_hi:[0,1]
	s_waitcnt lgkmcnt(0)
	v_and_b32_sdwa v42, v37, v95 dst_sel:DWORD dst_unused:UNUSED_PAD src0_sel:WORD_1 src1_sel:DWORD
	v_and_b32_sdwa v43, v36, v95 dst_sel:DWORD dst_unused:UNUSED_PAD src0_sel:WORD_1 src1_sel:DWORD
	v_add3_u32 v60, v37, v42, s86
	v_add3_u32 v61, v36, v43, s86
	v_and_b32_e32 v43, 0xffff0000, v60
	v_and_b32_e32 v42, 0xffff0000, v61
	v_cvt_pk_bf16_f32 v217, v36, v37
	v_pk_add_f32 v[36:37], v[36:37], v[42:43] neg_lo:[0,1] neg_hi:[0,1]
	v_and_b32_sdwa v42, v39, v95 dst_sel:DWORD dst_unused:UNUSED_PAD src0_sel:WORD_1 src1_sel:DWORD
	v_and_b32_sdwa v43, v38, v95 dst_sel:DWORD dst_unused:UNUSED_PAD src0_sel:WORD_1 src1_sel:DWORD
	v_add3_u32 v62, v39, v42, s86
	v_add3_u32 v63, v38, v43, s86
	v_and_b32_e32 v43, 0xffff0000, v62
	v_and_b32_e32 v42, 0xffff0000, v63
	v_cvt_pk_bf16_f32 v218, v38, v39
	v_pk_add_f32 v[38:39], v[38:39], v[42:43] neg_lo:[0,1] neg_hi:[0,1]
	s_nop 0
	v_cvt_pk_bf16_f32 v213, v38, v39
	v_cvt_pk_bf16_f32 v212, v36, v37
	v_cvt_pk_bf16_f32 v210, v34, v35
	v_cvt_pk_bf16_f32 v209, v32, v33
	v_mov_b32_e32 v32, v209
	v_mov_b32_e32 v33, v210
	v_mov_b32_e32 v34, v212
	v_mov_b32_e32 v35, v213
	v_mov_b32_e32 v36, v214
	v_mov_b32_e32 v37, v216
	v_mov_b32_e32 v38, v217
	v_mov_b32_e32 v39, v218
; #define LAS __attribute__((address_space(3)))
; __device__ __forceinline__ void phase_gla_pre(const Params& P, LAS unsigned char* lds, bool dry) {
;     ...
;         for (int tt = 0; tt < 4; ++tt) {
;             bf16x8 ahi = (bf16x8){0, 0, 0, 0, 0, 0, 0, 0}, alo = ahi;
;             if (g < 2) { const f32x4 l0 = *(const LAS f32x4*)(Llr + (16 * tt + fr) * 16 + 8 * g), l1 = *(const LAS f32x4*)(Llr + (16 * tt + fr) * 16 + 8 * g + 4); split8(l0, l1, ahi, alo); }
;             f32x4 acc = (f32x4){bg, bg, bg, bg};
;             acc = __builtin_amdgcn_mfma_f32_16x16x32_bf16(alo, bhi, acc, 0, 0, 0); acc = __builtin_amdgcn_mfma_f32_16x16x32_bf16(ahi, blo, acc, 0, 0, 0); acc = __builtin_amdgcn_mfma_f32_16x16x32_bf16(ahi, bhi, acc, 0, 0, 0);
;             float pr[4];
; #pragma unroll
;             for (int r = 0; r < 4; ++r) { const float lg = acc[r]; const float ls = fminf(lg, 0.f) - __logf(1.0f + __expf(-fabsf(lg))); pr[r] = ls * (1.0f / 16.0f) + (r ? pr[r - 1] : 0.f); }
;             const float T = pr[3];
;             const float u1 = __shfl_up(T, 16), s1 = T + (g >= 1 ? u1 : 0.f);
;             const float u2 = __shfl_up(s1, 32), s2 = s1 + (g >= 2 ? u2 : 0.f);
;             const float base = run + (s2 - T); run += __shfl(s2, 48 + fr);
; #pragma unroll
;             for (int r = 0; r < 4; ++r) *(LAS float*)(Lb + (16 * tt + 4 * g + r) * BP + (16 * w + fr) * 4) = base + pr[r];
;         }
;         __syncthreads();
;         {
;             f32x4 bb[4], bm[4], bl[4];
; #pragma unroll
;             for (int i = 0; i < 4; ++i) { bb[i] = *(const LAS f32x4*)(Lb + te * BP + (16 * kc + 4 * i) * 4); bm[i] = *(const LAS f32x4*)(Lb + 31 * BP + (16 * kc + 4 * i) * 4); bl[i] = *(const LAS f32x4*)(Lb + 63 * BP + (16 * kc + 4 * i) * 4); }
;             unsigned oqi[8], oki[8], oqd[8], oks[8];
; #pragma unroll
;             for (int e2 = 0; e2 < 8; ++e2) {
;                 const unsigned qw = e2 < 4 ? rq[0][e2] : rq[1][e2 - 4], kw = e2 < 4 ? rk[0][e2] : rk[1][e2 - 4];
;                 float vqi[2], vki[2], vqd[2], vks[2];
; #pragma unroll
;                 for (int hh = 0; hh < 2; ++hh) {
;                     const int e = 2 * e2 + hh; const float bv = bb[e >> 2][e & 3], bmv = bm[e >> 2][e & 3], blv = bl[e >> 2][e & 3];
;                     const float qv = hh ? bfhi(qw) : bflo(qw), kv = hh ? bfhi(kw) : bflo(kw);
;                     const float e1 = __expf(bv - bmv);
.LBB0_492:
	s_or_b64 exec, exec, s[36:37]
	v_mfma_f32_16x16x32_bf16 v[28:31], v[32:35], v[20:23], v[28:31]
	v_and_b32_e32 v111, 0xffff0000, v5
	v_and_b32_e32 v110, 0xffff0000, v4
	v_and_b32_e32 v117, 0xffff0000, v13
	v_mfma_f32_16x16x32_bf16 v[24:27], v[36:39], v[24:27], v[28:31]
	v_and_b32_e32 v116, 0xffff0000, v12
	v_and_b32_e32 v121, 0xffff0000, v7
	v_and_b32_e32 v120, 0xffff0000, v6
	v_mfma_f32_16x16x32_bf16 v[20:23], v[36:39], v[20:23], v[24:27]
	v_and_b32_e32 v127, 0xffff0000, v17
	v_and_b32_e32 v126, 0xffff0000, v16
	v_lshlrev_b32_e32 v125, 16, v17
	v_lshlrev_b32_e32 v124, 16, v16
	v_lshlrev_b32_e32 v133, 16, v11
	s_nop 2
	v_max_f32_e32 v24, v20, v20
	v_mul_f32_e64 v20, |v20|, s89
	v_exp_f32_e32 v20, v20
	v_mul_f32_e64 v25, |v21|, s89
	v_exp_f32_e32 v25, v25
	v_min_f32_e32 v24, 0, v24
	v_add_f32_e32 v20, 1.0, v20
	v_cmp_gt_f32_e32 vcc, s90, v20
	v_add_f32_e32 v25, 1.0, v25
	v_cmp_gt_f32_e64 s[36:37], s90, v25
	v_cndmask_b32_e64 v26, 0, 32, vcc
	v_ldexp_f32 v20, v20, v26
	v_log_f32_e32 v20, v20
	v_cndmask_b32_e64 v27, 0, 32, s[36:37]
	v_ldexp_f32 v25, v25, v27
	v_log_f32_e32 v25, v25
	v_mul_f32_e32 v27, 0x3f317217, v20
	v_fma_f32 v27, v20, s91, -v27
	v_fmac_f32_e32 v27, 0x3377d1cf, v20
	v_cndmask_b32_e32 v26, 0, v97, vcc
	v_fmac_f32_e32 v27, 0x3f317217, v20
	v_cmp_lt_f32_e64 vcc, |v20|, s92
	v_mul_f32_e32 v28, 0x3f317217, v25
	v_max_f32_e32 v21, v21, v21
	v_cndmask_b32_e32 v20, v20, v27, vcc
	v_sub_f32_e32 v20, v20, v26
	v_sub_f32_e32 v20, v24, v20
	v_fma_f32 v24, v25, s91, -v28
	v_fmac_f32_e32 v24, 0x3377d1cf, v25
	v_fmac_f32_e32 v24, 0x3f317217, v25
	v_cmp_lt_f32_e64 vcc, |v25|, s92
	v_cndmask_b32_e64 v26, 0, v97, s[36:37]
	v_min_f32_e32 v21, 0, v21
	v_cndmask_b32_e32 v24, v25, v24, vcc
	v_mul_f32_e64 v25, |v22|, s89
	v_exp_f32_e32 v25, v25
	v_sub_f32_e32 v24, v24, v26
	v_sub_f32_e32 v21, v21, v24
	v_max_f32_e32 v22, v22, v22
	v_add_f32_e32 v24, 1.0, v25
	v_cmp_gt_f32_e32 vcc, s90, v24
	v_min_f32_e32 v22, 0, v22
	v_fma_f32 v20, v20, s93, 0
	v_cndmask_b32_e64 v25, 0, 32, vcc
	v_ldexp_f32 v24, v24, v25
	v_log_f32_e32 v24, v24
	v_cndmask_b32_e32 v26, 0, v97, vcc
	v_fmamk_f32 v21, v21, 0x3d800000, v20
	v_lshlrev_b32_e32 v132, 16, v10
	v_mul_f32_e32 v25, 0x3f317217, v24
	v_fma_f32 v25, v24, s91, -v25
	v_fmac_f32_e32 v25, 0x3377d1cf, v24
	v_fmac_f32_e32 v25, 0x3f317217, v24
	v_cmp_lt_f32_e64 s[36:37], |v24|, s92
	v_and_b32_e32 v135, 0xffff0000, v11
	v_and_b32_e32 v134, 0xffff0000, v10
	v_cndmask_b32_e64 v24, v24, v25, s[36:37]
	v_mul_f32_e64 v25, |v23|, s89
	v_exp_f32_e32 v25, v25
	v_sub_f32_e32 v24, v24, v26
	v_sub_f32_e32 v22, v22, v24
	v_max_f32_e32 v23, v23, v23
	v_add_f32_e32 v24, 1.0, v25
	v_cmp_gt_f32_e32 vcc, s90, v24
	v_min_f32_e32 v23, 0, v23
	v_fmamk_f32 v22, v22, 0x3d800000, v21
	v_cndmask_b32_e64 v25, 0, 32, vcc
	v_ldexp_f32 v24, v24, v25
	v_log_f32_e32 v24, v24
	s_waitcnt lgkmcnt(2)
	v_add_f32_e32 v26, v40, v41
	s_and_b32 s74, s1, 0xfc0
	s_ashr_i32 s83, s82, 31
	v_mul_f32_e32 v25, 0x3f317217, v24
	v_fma_f32 v25, v24, s91, -v25
	v_fmac_f32_e32 v25, 0x3377d1cf, v24
	v_fmac_f32_e32 v25, 0x3f317217, v24
	v_cmp_lt_f32_e64 s[36:37], |v24|, s92
	s_nop 1
	v_cndmask_b32_e64 v24, v24, v25, s[36:37]
	v_cndmask_b32_e32 v25, 0, v97, vcc
	v_sub_f32_e32 v24, v24, v25
	v_sub_f32_e32 v23, v23, v24
	v_fmamk_f32 v23, v23, 0x3d800000, v22
	ds_bpermute_b32 v24, v83, v23
	s_lshl_b64 s[36:37], s[82:83], 20
	s_waitcnt lgkmcnt(0)
	v_cndmask_b32_e64 v24, v24, 0, s[8:9]
	v_add_f32_e32 v24, v24, v23
	ds_bpermute_b32 v25, v84, v24
	s_waitcnt lgkmcnt(0)
	v_cndmask_b32_e64 v25, 0, v25, s[10:11]
	v_add_f32_e32 v24, v25, v24
	v_sub_f32_e32 v24, v24, v23
	v_add_f32_e32 v24, v26, v24
	v_add_f32_e32 v20, v20, v24
	v_add_f32_e32 v21, v21, v24
	v_add_u32_e32 v25, 0xea00, v98
	ds_write2_b32 v25, v20, v21 offset0:64 offset1:196
	v_add_f32_e32 v20, v22, v24
	v_add_f32_e32 v21, v23, v24
	v_add_u32_e32 v22, 0xee00, v98
	ds_write2_b32 v22, v20, v21 offset0:72 offset1:204
	v_add_u32_e32 v22, s94, v87
	s_waitcnt lgkmcnt(0)
	s_barrier
	v_add_u32_e32 v20, v86, v87
	v_add_u32_e32 v21, 0, v87
	ds_read_b128 v[32:35], v22
	ds_read_b128 v[24:27], v89
	ds_read_b128 v[60:63], v21 offset:51184
	ds_read_b128 v[64:67], v20 offset:34816
	ds_read_b128 v[74:77], v20 offset:34832
	ds_read_b128 v[44:47], v20 offset:34848
	ds_read_b128 v[36:39], v20 offset:34864
	ds_read_b128 v[100:103], v21 offset:51200
	s_waitcnt lgkmcnt(4)
	v_sub_f32_e32 v61, v65, v61
	v_mul_f32_e32 v61, 0x3fb8aa3b, v61
	v_sub_f32_e32 v63, v67, v63
	v_exp_f32_e32 v72, v61
	v_sub_f32_e32 v61, v32, v64
	v_mul_f32_e32 v63, 0x3fb8aa3b, v63
	v_mul_f32_e32 v61, 0x3fb8aa3b, v61
	v_exp_f32_e32 v73, v63
	v_exp_f32_e32 v78, v61
	v_mul_f32_e32 v61, 0x3fb8aa3b, v65
	v_sub_f32_e32 v20, v64, v60
	v_exp_f32_e32 v108, v61
	v_sub_f32_e32 v61, v66, v62
	v_mul_f32_e32 v20, 0x3fb8aa3b, v20
	v_mul_f32_e32 v69, 0x3fb8aa3b, v64
	v_mul_f32_e32 v61, 0x3fb8aa3b, v61
	v_sub_f32_e32 v62, v33, v65
	v_mul_f32_e32 v65, 0x3fb8aa3b, v66
	v_sub_f32_e32 v63, v34, v66
	v_exp_f32_e32 v60, v20
	v_exp_f32_e32 v70, v69
	v_rcp_f32_e32 v64, v72
	v_exp_f32_e32 v61, v61
	v_exp_f32_e32 v71, v65
	v_mul_f32_e32 v63, 0x3fb8aa3b, v63
	v_rcp_f32_e32 v65, v73
	v_exp_f32_e32 v79, v63
	v_mul_f32_e32 v63, 0x3fb8aa3b, v67
	v_exp_f32_e32 v109, v63
	v_sub_f32_e32 v63, v35, v67
	v_lshlrev_b32_e32 v67, 16, v5
	v_lshlrev_b32_e32 v66, 16, v4
	v_pk_mul_f32 v[112:113], v[60:61], v[66:67]
	v_pk_mul_f32 v[114:115], v[72:73], v[110:111]
	v_pk_mul_f32 v[72:73], v[64:65], v[116:117]
	v_pk_mul_f32 v[64:65], v[70:71], v[66:67]
	s_waitcnt lgkmcnt(0)
; #define LAS __attribute__((address_space(3)))
; __device__ __forceinline__ float bflo(unsigned w) { return __uint_as_float(w << 16); }
; __device__ __forceinline__ float bfhi(unsigned w) { return __uint_as_float(w & 0xffff0000u); }
; __device__ __forceinline__ unsigned pk2(float lo, float hi) { return f2bf(lo) | (f2bf(hi) << 16); }
; __device__ __forceinline__ void phase_gla_pre(const Params& P, LAS unsigned char* lds, bool dry) {
;     ...
;             for (int i = 0; i < 4; ++i) { bb[i] = *(const LAS f32x4*)(Lb + te * BP + (16 * kc + 4 * i) * 4); bm[i] = *(const LAS f32x4*)(Lb + 31 * BP + (16 * kc + 4 * i) * 4); bl[i] = *(const LAS f32x4*)(Lb + 63 * BP + (16 * kc + 4 * i) * 4); }
;             unsigned oqi[8], oki[8], oqd[8], oks[8];
; #pragma unroll
;             for (int e2 = 0; e2 < 8; ++e2) {
;                 const unsigned qw = e2 < 4 ? rq[0][e2] : rq[1][e2 - 4], kw = e2 < 4 ? rk[0][e2] : rk[1][e2 - 4];
;                 float vqi[2], vki[2], vqd[2], vks[2];
; #pragma unroll
;                 for (int hh = 0; hh < 2; ++hh) {
;                     const int e = 2 * e2 + hh; const float bv = bb[e >> 2][e & 3], bmv = bm[e >> 2][e & 3], blv = bl[e >> 2][e & 3];
;                     const float qv = hh ? bfhi(qw) : bflo(qw), kv = hh ? bfhi(kw) : bflo(kw);
;                     const float e1 = __expf(bv - bmv);
;                     vqi[hh] = qv * e1; vki[hh] = kv * __builtin_amdgcn_rcpf(e1); vqd[hh] = qv * __expf(bv); vks[hh] = kv * __expf(blv - bv);
;                 }
;                 oqi[e2] = pk2(vqi[0], vqi[1]); oki[e2] = pk2(vki[0], vki[1]); oqd[e2] = pk2(vqd[0], vqd[1]); oks[e2] = pk2(vks[0], vks[1]);
;             }
;             *(LAS u32x4*)(Lqi + te * QP + 32 * kc) = (u32x4){oqi[0], oqi[1], oqi[2], oqi[3]}; *(LAS u32x4*)(Lqi + te * QP + 32 * kc + 16) = (u32x4){oqi[4], oqi[5], oqi[6], oqi[7]};
;             *(LAS u32x4*)(Lki + te * QP + 32 * kc) = (u32x4){oki[0], oki[1], oki[2], oki[3]}; *(LAS u32x4*)(Lki + te * QP + 32 * kc + 16) = (u32x4){oki[4], oki[5], oki[6], oki[7]};
	v_sub_f32_e32 v66, v74, v100
	v_mul_f32_e32 v66, 0x3fb8aa3b, v66
	v_mul_f32_e32 v71, 0x3fb8aa3b, v74
	v_exp_f32_e32 v70, v66
	v_pk_mul_f32 v[66:67], v[108:109], v[110:111]
	v_exp_f32_e32 v108, v71
	v_sub_f32_e32 v71, v75, v101
	v_mul_f32_e32 v71, 0x3fb8aa3b, v71
	v_mul_f32_e32 v62, 0x3fb8aa3b, v62
	v_mul_f32_e32 v63, 0x3fb8aa3b, v63
	v_exp_f32_e32 v100, v71
	v_sub_f32_e32 v71, v24, v74
	v_exp_f32_e32 v62, v62
	v_exp_f32_e32 v63, v63
	v_mul_f32_e32 v71, 0x3fb8aa3b, v71
	v_exp_f32_e32 v74, v71
	v_mul_f32_e32 v71, 0x3fb8aa3b, v75
	v_sub_f32_e32 v75, v25, v75
	v_mul_f32_e32 v75, 0x3fb8aa3b, v75
	v_exp_f32_e32 v118, v75
	v_mul_f32_e32 v75, 0x3fb8aa3b, v76
	v_pk_mul_f32 v[62:63], v[62:63], v[116:117]
	v_exp_f32_e32 v116, v71
	v_sub_f32_e32 v71, v76, v102
	v_exp_f32_e32 v109, v75
	v_sub_f32_e32 v75, v77, v103
	v_mul_f32_e32 v71, 0x3fb8aa3b, v71
	v_mul_f32_e32 v75, 0x3fb8aa3b, v75
	v_rcp_f32_e32 v68, v60
	v_rcp_f32_e32 v69, v61
	v_exp_f32_e32 v71, v71
	v_exp_f32_e32 v101, v75
	v_sub_f32_e32 v75, v26, v76
	v_mul_f32_e32 v76, 0x3fb8aa3b, v77
	v_exp_f32_e32 v117, v76
	v_sub_f32_e32 v76, v27, v77
	v_mul_f32_e32 v76, 0x3fb8aa3b, v76
	v_lshlrev_b32_e32 v61, 16, v13
	v_lshlrev_b32_e32 v60, 16, v12
	v_exp_f32_e32 v119, v76
	v_lshlrev_b32_e32 v77, 16, v7
	v_lshlrev_b32_e32 v76, 16, v6
	v_pk_mul_f32 v[68:69], v[68:69], v[60:61]
	v_pk_mul_f32 v[60:61], v[78:79], v[60:61]
	v_rcp_f32_e32 v78, v70
	v_rcp_f32_e32 v110, v100
	v_rcp_f32_e32 v79, v71
	v_rcp_f32_e32 v111, v101
	v_pk_mul_f32 v[70:71], v[70:71], v[76:77]
	v_pk_mul_f32 v[100:101], v[100:101], v[120:121]
	v_cvt_pk_bf16_f32 v224, v112, v114
	v_cvt_pk_bf16_f32 v222, v113, v115
	v_cvt_pk_bf16_f32 v221, v70, v100
	v_cvt_pk_bf16_f32 v220, v71, v101
	ds_read_b128 v[104:107], v21 offset:51216
	ds_read_b128 v[40:43], v21 offset:51232
	ds_read_b128 v[28:31], v90
	ds_read_b128 v[20:23], v91
	v_mov_b32_e32 v103, v220
	v_mov_b32_e32 v102, v221
	v_lshlrev_b32_e32 v71, 16, v15
	v_lshlrev_b32_e32 v70, 16, v14
	v_mul_f32_e32 v75, 0x3fb8aa3b, v75
	v_mov_b32_e32 v101, v222
	v_mov_b32_e32 v100, v224
	v_pk_mul_f32 v[114:115], v[78:79], v[70:71]
	s_waitcnt lgkmcnt(3)
	v_sub_f32_e32 v78, v44, v104
	v_sub_f32_e32 v105, v45, v105
	v_exp_f32_e32 v75, v75
	v_mul_f32_e32 v78, 0x3fb8aa3b, v78
	v_mul_f32_e32 v105, 0x3fb8aa3b, v105
	v_exp_f32_e32 v104, v78
	v_pk_mul_f32 v[78:79], v[116:117], v[120:121]
	v_exp_f32_e32 v116, v105
	v_mul_f32_e32 v105, 0x3fb8aa3b, v45
	s_waitcnt lgkmcnt(1)
	v_sub_f32_e32 v45, v29, v45
	v_mul_f32_e32 v45, 0x3fb8aa3b, v45
	v_and_b32_e32 v113, 0xffff0000, v15
	v_and_b32_e32 v112, 0xffff0000, v14
	v_exp_f32_e32 v120, v105
	v_sub_f32_e32 v105, v46, v106
	v_exp_f32_e32 v106, v45
	v_mul_f32_e32 v45, 0x3fb8aa3b, v46
	v_pk_mul_f32 v[110:111], v[110:111], v[112:113]
	v_pk_mul_f32 v[70:71], v[74:75], v[70:71]
	v_pk_mul_f32 v[74:75], v[118:119], v[112:113]
	v_exp_f32_e32 v113, v45
	v_sub_f32_e32 v45, v47, v107
	v_mul_f32_e32 v45, 0x3fb8aa3b, v45
	v_exp_f32_e32 v117, v45
	v_sub_f32_e32 v45, v30, v46
	v_mul_f32_e32 v46, 0x3fb8aa3b, v47
	v_exp_f32_e32 v121, v46
	v_sub_f32_e32 v46, v31, v47
	v_pk_mul_f32 v[76:77], v[108:109], v[76:77]
	v_mul_f32_e32 v109, 0x3fb8aa3b, v44
	v_mul_f32_e32 v105, 0x3fb8aa3b, v105
	v_mul_f32_e32 v46, 0x3fb8aa3b, v46
	v_exp_f32_e32 v112, v109
	v_exp_f32_e32 v105, v105
	v_exp_f32_e32 v107, v46
	v_rcp_f32_e32 v118, v116
	v_rcp_f32_e32 v119, v117
	v_sub_f32_e32 v44, v28, v44
	v_lshlrev_b32_e32 v47, 16, v9
	v_lshlrev_b32_e32 v46, 16, v8
	v_rcp_f32_e32 v108, v104
	v_mul_f32_e32 v44, 0x3fb8aa3b, v44
	v_rcp_f32_e32 v109, v105
	v_mul_f32_e32 v45, 0x3fb8aa3b, v45
	v_pk_mul_f32 v[104:105], v[104:105], v[46:47]
	v_pk_mul_f32 v[112:113], v[112:113], v[46:47]
	v_sub_f32_e32 v40, v36, v40
	v_pk_mul_f32 v[46:47], v[106:107], v[126:127]
	v_mul_f32_e32 v107, 0x3fb8aa3b, v36
	s_waitcnt lgkmcnt(0)
; #define LAS __attribute__((address_space(3)))
; __device__ __forceinline__ void phase_gla_pre(const Params& P, LAS unsigned char* lds, bool dry) {
;     ...
;             for (int i = 0; i < 4; ++i) { bb[i] = *(const LAS f32x4*)(Lb + te * BP + (16 * kc + 4 * i) * 4); bm[i] = *(const LAS f32x4*)(Lb + 31 * BP + (16 * kc + 4 * i) * 4); bl[i] = *(const LAS f32x4*)(Lb + 63 * BP + (16 * kc + 4 * i) * 4); }
;             unsigned oqi[8], oki[8], oqd[8], oks[8];
; #pragma unroll
;             for (int e2 = 0; e2 < 8; ++e2) {
;                 const unsigned qw = e2 < 4 ? rq[0][e2] : rq[1][e2 - 4], kw = e2 < 4 ? rk[0][e2] : rk[1][e2 - 4];
;                 float vqi[2], vki[2], vqd[2], vks[2];
; #pragma unroll
;                 for (int hh = 0; hh < 2; ++hh) {
;                     const int e = 2 * e2 + hh; const float bv = bb[e >> 2][e & 3], bmv = bm[e >> 2][e & 3], blv = bl[e >> 2][e & 3];
;                     const float qv = hh ? bfhi(qw) : bflo(qw), kv = hh ? bfhi(kw) : bflo(kw);
;                     const float e1 = __expf(bv - bmv);
;                     vqi[hh] = qv * e1; vki[hh] = kv * __builtin_amdgcn_rcpf(e1); vqd[hh] = qv * __expf(bv); vks[hh] = kv * __expf(blv - bv);
;                 }
;                 oqi[e2] = pk2(vqi[0], vqi[1]); oki[e2] = pk2(vki[0], vki[1]); oqd[e2] = pk2(vqd[0], vqd[1]); oks[e2] = pk2(vks[0], vks[1]);
;             }
;             *(LAS u32x4*)(Lqi + te * QP + 32 * kc) = (u32x4){oqi[0], oqi[1], oqi[2], oqi[3]}; *(LAS u32x4*)(Lqi + te * QP + 32 * kc + 16) = (u32x4){oqi[4], oqi[5], oqi[6], oqi[7]};
;             *(LAS u32x4*)(Lki + te * QP + 32 * kc) = (u32x4){oki[0], oki[1], oki[2], oki[3]}; *(LAS u32x4*)(Lki + te * QP + 32 * kc + 16) = (u32x4){oki[4], oki[5], oki[6], oki[7]};
;             if (!dry) {
;                 bf16_t* p_ = PJ + ((size_t)bh * SEQ + c * 64 + te) * 128 + 16 * kc;
;                 *(u32x4*)(p_ + T_Q) = (u32x4){oqd[0], oqd[1], oqd[2], oqd[3]}; *(u32x4*)(p_ + T_Q + 8) = (u32x4){oqd[4], oqd[5], oqd[6], oqd[7]};
;                 *(u32x4*)(p_ + T_K) = (u32x4){oks[0], oks[1], oks[2], oks[3]}; *(u32x4*)(p_ + T_K + 8) = (u32x4){oks[4], oks[5], oks[6], oks[7]};
;                 if (te == 63) {
; #pragma unroll
;                     for (int i = 0; i < 4; ++i) *(f32x4*)(DEC + (size_t)item * 128 + 16 * kc + 4 * i) = (f32x4){__expf(bl[i][0]), __expf(bl[i][1]), __expf(bl[i][2]), __expf(bl[i][3])};
;                 }
	v_sub_f32_e32 v36, v20, v36
	v_exp_f32_e32 v44, v44
	v_exp_f32_e32 v45, v45
	v_mul_f32_e32 v36, 0x3fb8aa3b, v36
	v_pk_mul_f32 v[118:119], v[118:119], v[126:127]
	v_exp_f32_e32 v126, v36
	v_mul_f32_e32 v36, 0x3fb8aa3b, v37
	v_sub_f32_e32 v41, v37, v41
	v_exp_f32_e32 v130, v36
	v_sub_f32_e32 v36, v38, v42
	v_mul_f32_e32 v41, 0x3fb8aa3b, v41
	v_mul_f32_e32 v36, 0x3fb8aa3b, v36
	v_pk_mul_f32 v[108:109], v[108:109], v[124:125]
	v_pk_mul_f32 v[44:45], v[44:45], v[124:125]
	v_exp_f32_e32 v124, v41
	v_exp_f32_e32 v41, v36
	v_sub_f32_e32 v36, v21, v37
	v_mul_f32_e32 v36, 0x3fb8aa3b, v36
	v_and_b32_e32 v123, 0xffff0000, v9
	v_and_b32_e32 v122, 0xffff0000, v8
	v_exp_f32_e32 v42, v36
	v_mul_f32_e32 v36, 0x3fb8aa3b, v38
	v_pk_mul_f32 v[116:117], v[116:117], v[122:123]
	v_pk_mul_f32 v[120:121], v[120:121], v[122:123]
	v_exp_f32_e32 v123, v36
	v_sub_f32_e32 v36, v39, v43
	v_mul_f32_e32 v36, 0x3fb8aa3b, v36
	v_mul_f32_e32 v40, 0x3fb8aa3b, v40
	v_exp_f32_e32 v125, v36
	v_sub_f32_e32 v36, v22, v38
	v_exp_f32_e32 v40, v40
	v_mul_f32_e32 v36, 0x3fb8aa3b, v36
	v_exp_f32_e32 v127, v36
	v_mul_f32_e32 v36, 0x3fb8aa3b, v39
	v_exp_f32_e32 v131, v36
	v_sub_f32_e32 v36, v23, v39
	v_mul_f32_e32 v36, 0x3fb8aa3b, v36
	v_rcp_f32_e32 v128, v124
	v_rcp_f32_e32 v129, v125
	v_exp_f32_e32 v43, v36
	v_pk_mul_f32 v[36:37], v[40:41], v[132:133]
	v_pk_mul_f32 v[38:39], v[124:125], v[134:135]
	v_rcp_f32_e32 v106, v40
	v_exp_f32_e32 v122, v107
	v_rcp_f32_e32 v107, v41
	v_cvt_pk_bf16_f32 v228, v104, v116
	v_cvt_pk_bf16_f32 v227, v105, v117
	v_cvt_pk_bf16_f32 v226, v36, v38
	v_cvt_pk_bf16_f32 v225, v37, v39
	v_mov_b32_e32 v39, v225
	v_mov_b32_e32 v38, v226
	v_mov_b32_e32 v37, v227
	v_mov_b32_e32 v36, v228
	ds_write_b128 v92, v[100:103]
	ds_write_b128 v92, v[36:39] offset:16
	v_cvt_pk_bf16_f32 v230, v68, v72
	v_cvt_pk_bf16_f32 v229, v69, v73
	v_lshlrev_b32_e32 v41, 16, v19
	v_lshlrev_b32_e32 v40, 16, v18
	v_cvt_pk_bf16_f32 v39, v115, v111
	v_cvt_pk_bf16_f32 v38, v114, v110
	v_mov_b32_e32 v37, v229
	v_mov_b32_e32 v36, v230
	v_and_b32_e32 v105, 0xffff0000, v19
	v_and_b32_e32 v104, 0xffff0000, v18
	v_pk_mul_f32 v[106:107], v[106:107], v[40:41]
	ds_write_b128 v92, v[36:39] offset:17408
	v_pk_mul_f32 v[116:117], v[128:129], v[104:105]
	s_nop 0
	v_cvt_pk_bf16_f32 v39, v107, v117
	v_cvt_pk_bf16_f32 v38, v106, v116
	v_cvt_pk_bf16_f32 v37, v109, v119
	v_cvt_pk_bf16_f32 v36, v108, v118
	ds_write_b128 v92, v[36:39] offset:17424
	v_lshl_add_u64 v[36:37], s[74:75], 0, v[48:49]
	v_lshlrev_b64 v[36:37], 8, v[36:37]
	v_lshl_add_u64 v[38:39], v[52:53], 0, s[36:37]
	v_lshl_add_u64 v[68:69], v[38:39], 0, v[36:37]
	v_cvt_pk_bf16_f32 v232, v64, v66
	v_cvt_pk_bf16_f32 v233, v65, v67
	s_brev_b32 s36, 16
	v_cvt_pk_bf16_f32 v39, v77, v79
	v_mov_b32_e32 v36, v232
	v_add_co_u32_e32 v64, vcc, s36, v68
	v_cvt_pk_bf16_f32 v38, v76, v78
	v_mov_b32_e32 v37, v233
	v_addc_co_u32_e32 v65, vcc, 0, v69, vcc
	v_pk_mul_f32 v[122:123], v[122:123], v[132:133]
	global_store_dwordx4 v[64:65], v[36:39], off
	v_pk_mul_f32 v[124:125], v[130:131], v[134:135]
	s_nop 0
	v_cvt_pk_bf16_f32 v39, v123, v125
	v_cvt_pk_bf16_f32 v38, v122, v124
	v_cvt_pk_bf16_f32 v37, v113, v121
	v_cvt_pk_bf16_f32 v36, v112, v120
	global_store_dwordx4 v[64:65], v[36:39], off offset:16
	s_nop 1
	s_nop 0
	v_cvt_pk_bf16_f32 v234, v60, v62
	v_cvt_pk_bf16_f32 v235, v61, v63
	v_cvt_pk_bf16_f32 v39, v71, v75
	v_mov_b32_e32 v36, v234
	v_add_co_u32_e32 v60, vcc, s95, v68
	v_pk_mul_f32 v[42:43], v[42:43], v[104:105]
	v_cvt_pk_bf16_f32 v38, v70, v74
	v_mov_b32_e32 v37, v235
	v_addc_co_u32_e32 v61, vcc, 0, v69, vcc
	v_pk_mul_f32 v[40:41], v[126:127], v[40:41]
	global_store_dwordx4 v[60:61], v[36:39], off
	s_nop 1
	v_cvt_pk_bf16_f32 v240, v44, v46
	v_cvt_pk_bf16_f32 v239, v45, v47
	v_cvt_pk_bf16_f32 v238, v40, v42
	v_cvt_pk_bf16_f32 v237, v41, v43
	v_mov_b32_e32 v39, v237
	v_mov_b32_e32 v38, v238
	v_mov_b32_e32 v37, v239
	v_mov_b32_e32 v36, v240
	global_store_dwordx4 v[60:61], v[36:39], off offset:16
	s_and_saveexec_b64 s[36:37], s[12:13]
	s_cbranch_execz .LBB0_494
	v_mul_f32_e32 v32, 0x3fb8aa3b, v32
	v_mul_f32_e32 v33, 0x3fb8aa3b, v33
	v_mul_f32_e32 v34, 0x3fb8aa3b, v34
	v_mul_f32_e32 v35, 0x3fb8aa3b, v35
	v_exp_f32_e32 v32, v32
	v_exp_f32_e32 v33, v33
	v_exp_f32_e32 v34, v34
	v_exp_f32_e32 v35, v35
	v_mul_f32_e32 v24, 0x3fb8aa3b, v24
	v_mul_f32_e32 v25, 0x3fb8aa3b, v25
	v_mul_f32_e32 v26, 0x3fb8aa3b, v26
	v_mul_f32_e32 v27, 0x3fb8aa3b, v27
	s_ashr_i32 s81, s80, 31
	v_exp_f32_e32 v24, v24
	v_exp_f32_e32 v25, v25
	v_exp_f32_e32 v26, v26
	v_exp_f32_e32 v27, v27
	v_mul_f32_e32 v28, 0x3fb8aa3b, v28
	v_mul_f32_e32 v29, 0x3fb8aa3b, v29
	v_mul_f32_e32 v30, 0x3fb8aa3b, v30
	v_mul_f32_e32 v31, 0x3fb8aa3b, v31
	s_lshl_b64 s[42:43], s[80:81], 9
	v_exp_f32_e32 v28, v28
	v_exp_f32_e32 v29, v29
	v_exp_f32_e32 v30, v30
	v_exp_f32_e32 v31, v31
	v_mul_f32_e32 v20, 0x3fb8aa3b, v20
	v_mul_f32_e32 v21, 0x3fb8aa3b, v21
	v_mul_f32_e32 v22, 0x3fb8aa3b, v22
	v_mul_f32_e32 v23, 0x3fb8aa3b, v23
	v_lshl_add_u64 v[36:37], v[54:55], 0, s[42:43]
	v_exp_f32_e32 v20, v20
	v_exp_f32_e32 v21, v21
	v_exp_f32_e32 v22, v22
	v_exp_f32_e32 v23, v23
	global_store_dwordx4 v[36:37], v[32:35], off
	global_store_dwordx4 v[36:37], v[24:27], off offset:16
	global_store_dwordx4 v[36:37], v[28:31], off offset:32
	global_store_dwordx4 v[36:37], v[20:23], off offset:48

; #define LAS __attribute__((address_space(3)))
; __device__ __forceinline__ float bflo(unsigned w) { return __uint_as_float(w << 16); }
; __device__ __forceinline__ float bfhi(unsigned w) { return __uint_as_float(w & 0xffff0000u); }
; __device__ __forceinline__ unsigned pk2(float lo, float hi) { return f2bf(lo) | (f2bf(hi) << 16); }
; template <bool FULL>
; __device__ __forceinline__ void gla_pass(const Params& P, LAS unsigned char* lds, f32x4 (&S)[8][2], int bh, int c0, int L, bool dry) {
;     ...
;         if (FULL) {
;             f32x4 gn[2];
; #pragma unroll
;             for (int vt = 0; vt < 2; ++vt) gn[vt] = *(const f32x4*)(P.gla_norm_g + 32 * w + 4 * g + 16 * vt);
; #pragma unroll
;             for (int tt = 0; tt < 4; ++tt) {
;                 const int t = 16 * tt + fr;
;                 const f32x4 r0 = *(const LAS f32x4*)(red + t * 8), r1 = *(const LAS f32x4*)(red + t * 8 + 4);
;                 const float rstd = 1.0f / sqrtf(((r0[0] + r0[1]) + (r0[2] + r0[3]) + (r1[0] + r1[1]) + (r1[2] + r1[3])) * (1.0f / 256.0f) + RMS_EPS);
; #pragma unroll
;                 for (int vt = 0; vt < 2; ++vt) {
;                     bf16_t* op = (bf16_t*)P.out + (row0 + t) * 2048 + 1024 + h * 256 + 32 * w + 16 * vt + 4 * g;
;                     const u32x2 z = zb[vt][tt]; const f32x4 ov = o[vt][tt] * rstd * gn[vt];
;                     u32x2 r; r.x = pk2(ov[0] * bflo(z.x), ov[1] * bfhi(z.x)); r.y = pk2(ov[2] * bflo(z.y), ov[3] * bfhi(z.y));
;                     if (!dry) *(u32x2*)op = r;
;                 }
;             }
.LBB0_564:
	global_load_dwordx4 v[140:143], v[162:163], off
	global_load_dwordx4 v[136:139], v[162:163], off offset:64
	ds_read_b128 v[212:215], v200
	ds_read_b128 v[216:219], v200 offset:16
	s_waitcnt vmcnt(9)
	v_lshlrev_b32_e32 v221, 16, v185
	v_lshlrev_b32_e32 v220, 16, v184
	v_and_b32_e32 v223, 0xffff0000, v185
	s_waitcnt lgkmcnt(1)
	v_mov_b32_e32 v224, v213
	v_mov_b32_e32 v225, v214
	v_mov_b32_e32 v213, v215
	s_waitcnt lgkmcnt(0)
	v_mov_b32_e32 v214, v218
	v_mov_b32_e32 v215, v216
	v_mov_b32_e32 v216, v219
	v_pk_add_f32 v[212:213], v[224:225], v[212:213]
	v_pk_add_f32 v[214:215], v[214:215], v[216:217]
	v_add_f32_e32 v211, v212, v213
	v_add_f32_e32 v211, v211, v215
	v_add_f32_e32 v211, v214, v211
	v_fmamk_f32 v211, v211, 0x3b800000, v186
	v_mul_f32_e32 v212, 0x4f800000, v211
	v_cmp_gt_f32_e32 vcc, s91, v211
	v_and_b32_e32 v222, 0xffff0000, v184
	s_waitcnt vmcnt(6)
	v_lshlrev_b32_e32 v213, 16, v183
	v_cndmask_b32_e32 v211, v211, v212, vcc
	v_sqrt_f32_e32 v214, v211
	v_lshlrev_b32_e32 v212, 16, v182
	v_and_b32_e32 v183, 0xffff0000, v183
	v_and_b32_e32 v182, 0xffff0000, v182
	v_add_u32_e32 v215, -1, v214
	v_add_u32_e32 v216, 1, v214
	v_fma_f32 v217, -v215, v214, v211
	v_fma_f32 v218, -v216, v214, v211
	v_cmp_ge_f32_e64 s[8:9], 0, v217
	v_lshl_add_u64 v[184:185], v[176:177], 0, v[172:173]
	s_add_u32 s28, s28, 0x8000
	v_cndmask_b32_e64 v214, v214, v215, s[8:9]
	v_cmp_lt_f32_e64 s[8:9], 0, v218
	s_addc_u32 s29, s29, 0
	s_add_u32 s30, s30, 0x4000
	v_cndmask_b32_e64 v214, v214, v216, s[8:9]
	v_mul_f32_e32 v215, 0x37800000, v214
	v_cndmask_b32_e32 v214, v214, v215, vcc
	v_cmp_class_f32_e32 vcc, v211, v187
	s_addc_u32 s31, s31, 0
	s_add_i32 s27, s27, 1
	v_cndmask_b32_e32 v211, v214, v211, vcc
	v_div_scale_f32 v214, s[8:9], v211, v211, 1.0
	v_rcp_f32_e32 v215, v214
	v_div_scale_f32 v216, vcc, 1.0, v211, 1.0
	v_lshl_add_u64 v[174:175], v[174:175], 0, s[22:23]
	v_fma_f32 v217, -v214, v215, 1.0
	v_fmac_f32_e32 v215, v217, v215
	v_mul_f32_e32 v217, v216, v215
	v_fma_f32 v218, -v214, v217, v216
	v_fmac_f32_e32 v217, v218, v215
	v_fma_f32 v214, -v214, v217, v216
	v_div_fmas_f32 v214, v214, v215, v217
	v_div_fixup_f32 v214, v214, v211, 1.0
	v_pk_mul_f32 v[134:135], v[134:135], v[214:215] op_sel_hi:[1,0]
	v_pk_mul_f32 v[132:133], v[132:133], v[214:215] op_sel_hi:[1,0]
	v_pk_mul_f32 v[130:131], v[130:131], v[214:215] op_sel_hi:[1,0]
	v_pk_mul_f32 v[128:129], v[128:129], v[214:215] op_sel_hi:[1,0]
	s_cmp_lg_u32 s28, 0x200000
	v_lshl_add_u64 v[176:177], v[176:177], 0, s[24:25]
	s_waitcnt vmcnt(1)
	v_pk_mul_f32 v[132:133], v[140:141], v[132:133]
	v_pk_mul_f32 v[134:135], v[142:143], v[134:135]
	s_waitcnt vmcnt(0)
	v_pk_mul_f32 v[128:129], v[136:137], v[128:129]
	v_pk_mul_f32 v[130:131], v[138:139], v[130:131]
	v_mov_b32_e32 v214, v132
	v_mov_b32_e32 v215, v134
	v_mov_b32_e32 v134, v133
	v_mov_b32_e32 v132, v128
	v_mov_b32_e32 v133, v130
	v_mov_b32_e32 v130, v129
	v_pk_mul_f32 v[128:129], v[214:215], v[220:221]
	v_pk_mul_f32 v[134:135], v[134:135], v[222:223]
	v_pk_mul_f32 v[132:133], v[132:133], v[212:213]
	v_pk_mul_f32 v[182:183], v[130:131], v[182:183]
	v_cvt_pk_bf16_f32 v238, v128, v134
	v_cvt_pk_bf16_f32 v237, v129, v135
	v_and_b32_sdwa v214, v132, v189 dst_sel:DWORD dst_unused:UNUSED_PAD src0_sel:WORD_1 src1_sel:DWORD
	v_mov_b32_e32 v129, v237
	v_mov_b32_e32 v128, v238
	global_store_dwordx2 v[184:185], v[128:129], off offset:2048
	v_add3_u32 v211, v132, v214, s89
	ds_read_b128 v[128:131], v208
	v_cvt_pk_bf16_f32 v240, v132, v182
	v_cvt_pk_bf16_f32 v239, v133, v183
	ds_read_b128 v[132:135], v208 offset:16
	s_waitcnt lgkmcnt(1)
	v_mov_b32_e32 v212, v129
	v_mov_b32_e32 v213, v130
	v_mov_b32_e32 v129, v131
	v_pk_add_f32 v[128:129], v[212:213], v[128:129]
	s_waitcnt lgkmcnt(0)
	v_mov_b32_e32 v130, v134
	v_mov_b32_e32 v131, v132
	v_mov_b32_e32 v132, v135
	v_pk_add_f32 v[130:131], v[130:131], v[132:133]
	v_add_f32_e32 v128, v128, v129
	v_add_f32_e32 v128, v128, v131
	v_add_f32_e32 v128, v130, v128
	v_fmamk_f32 v128, v128, 0x3b800000, v186
	v_mul_f32_e32 v129, 0x4f800000, v128
	v_cmp_gt_f32_e32 vcc, s91, v128
	v_and_b32_sdwa v215, v182, v189 dst_sel:DWORD dst_unused:UNUSED_PAD src0_sel:WORD_1 src1_sel:DWORD
	s_nop 0
	v_cndmask_b32_e32 v128, v128, v129, vcc
	v_sqrt_f32_e32 v129, v128
	s_nop 0
	v_add_u32_e32 v132, -1, v129
	v_fma_f32 v133, -v132, v129, v128
	v_cmp_ge_f32_e64 s[8:9], 0, v133
	v_add_u32_e32 v133, 1, v129
	s_nop 0
	v_cndmask_b32_e64 v132, v129, v132, s[8:9]
	v_fma_f32 v129, -v133, v129, v128
	v_cmp_lt_f32_e64 s[8:9], 0, v129
	s_nop 1
	v_cndmask_b32_e64 v129, v132, v133, s[8:9]
	v_mul_f32_e32 v132, 0x37800000, v129
	v_cndmask_b32_e32 v129, v129, v132, vcc
	v_cmp_class_f32_e32 vcc, v128, v187
	s_nop 1
	v_cndmask_b32_e32 v132, v129, v128, vcc
	v_div_scale_f32 v133, s[8:9], v132, v132, 1.0
	v_rcp_f32_e32 v134, v133
	v_mov_b32_e32 v129, v239
	v_mov_b32_e32 v128, v240
	global_store_dwordx2 v[184:185], v[128:129], off offset:2080
	v_fma_f32 v128, -v133, v134, 1.0
	v_fmac_f32_e32 v134, v128, v134
	v_div_scale_f32 v128, vcc, 1.0, v132, 1.0
	v_mul_f32_e32 v129, v128, v134
	v_fma_f32 v130, -v133, v129, v128
	v_fmac_f32_e32 v129, v130, v134
	v_fma_f32 v128, -v133, v129, v128
	v_div_fmas_f32 v128, v128, v134, v129
	v_div_fixup_f32 v128, v128, v132, 1.0
	v_pk_mul_f32 v[126:127], v[126:127], v[128:129] op_sel_hi:[1,0]
	v_pk_mul_f32 v[124:125], v[124:125], v[128:129] op_sel_hi:[1,0]
	v_pk_mul_f32 v[126:127], v[142:143], v[126:127]
	v_pk_mul_f32 v[124:125], v[140:141], v[124:125]
	v_lshlrev_b32_e32 v131, 16, v181
	v_lshlrev_b32_e32 v130, 16, v180
	v_mov_b32_e32 v132, v124
	v_mov_b32_e32 v133, v126
	v_pk_mul_f32 v[130:131], v[132:133], v[130:131]
	v_and_b32_e32 v133, 0xffff0000, v181
	v_and_b32_e32 v132, 0xffff0000, v180
	v_mov_b32_e32 v126, v125
	v_pk_mul_f32 v[124:125], v[126:127], v[132:133]
	s_nop 0
	v_and_b32_sdwa v129, v125, v189 dst_sel:DWORD dst_unused:UNUSED_PAD src0_sel:WORD_1 src1_sel:DWORD
	v_cvt_pk_bf16_f32 v242, v130, v124
	v_cvt_pk_bf16_f32 v241, v131, v125
	v_add_co_u32_e32 v130, vcc, s92, v184
	v_pk_mul_f32 v[122:123], v[122:123], v[128:129] op_sel_hi:[1,0]
	v_pk_mul_f32 v[120:121], v[120:121], v[128:129] op_sel_hi:[1,0]
	v_mov_b32_e32 v125, v241
	v_mov_b32_e32 v124, v242
	v_addc_co_u32_e32 v131, vcc, 0, v185, vcc
	v_pk_mul_f32 v[120:121], v[136:137], v[120:121]
	v_pk_mul_f32 v[122:123], v[138:139], v[122:123]
	global_store_dwordx2 v[130:131], v[124:125], off offset:2048
	v_lshlrev_b32_e32 v125, 16, v179
	v_lshlrev_b32_e32 v124, 16, v178
	v_mov_b32_e32 v126, v120
	v_mov_b32_e32 v127, v122
	v_pk_mul_f32 v[124:125], v[126:127], v[124:125]
	v_and_b32_e32 v127, 0xffff0000, v179
	v_and_b32_e32 v126, 0xffff0000, v178
	v_mov_b32_e32 v122, v121
	v_pk_mul_f32 v[128:129], v[122:123], v[126:127]
	ds_read_b128 v[120:123], v209
	v_cvt_pk_bf16_f32 v244, v124, v128
	v_cvt_pk_bf16_f32 v243, v125, v129
	ds_read_b128 v[124:127], v209 offset:16
	s_waitcnt lgkmcnt(1)
; #define LAS __attribute__((address_space(3)))
; __device__ __forceinline__ float bflo(unsigned w) { return __uint_as_float(w << 16); }
; __device__ __forceinline__ float bfhi(unsigned w) { return __uint_as_float(w & 0xffff0000u); }
; __device__ __forceinline__ unsigned pk2(float lo, float hi) { return f2bf(lo) | (f2bf(hi) << 16); }
; template <bool FULL>
; __device__ __forceinline__ void gla_pass(const Params& P, LAS unsigned char* lds, f32x4 (&S)[8][2], int bh, int c0, int L, bool dry) {
;     ...
;         if (FULL) {
;             f32x4 gn[2];
; #pragma unroll
;             for (int vt = 0; vt < 2; ++vt) gn[vt] = *(const f32x4*)(P.gla_norm_g + 32 * w + 4 * g + 16 * vt);
; #pragma unroll
;             for (int tt = 0; tt < 4; ++tt) {
;                 const int t = 16 * tt + fr;
;                 const f32x4 r0 = *(const LAS f32x4*)(red + t * 8), r1 = *(const LAS f32x4*)(red + t * 8 + 4);
;                 const float rstd = 1.0f / sqrtf(((r0[0] + r0[1]) + (r0[2] + r0[3]) + (r1[0] + r1[1]) + (r1[2] + r1[3])) * (1.0f / 256.0f) + RMS_EPS);
; #pragma unroll
;                 for (int vt = 0; vt < 2; ++vt) {
;                     bf16_t* op = (bf16_t*)P.out + (row0 + t) * 2048 + 1024 + h * 256 + 32 * w + 16 * vt + 4 * g;
;                     const u32x2 z = zb[vt][tt]; const f32x4 ov = o[vt][tt] * rstd * gn[vt];
;                     u32x2 r; r.x = pk2(ov[0] * bflo(z.x), ov[1] * bfhi(z.x)); r.y = pk2(ov[2] * bflo(z.y), ov[3] * bfhi(z.y));
;                     if (!dry) *(u32x2*)op = r;
;                 }
;             }
;         }
;         __syncthreads();
	v_mov_b32_e32 v132, v121
	v_mov_b32_e32 v133, v122
	v_mov_b32_e32 v121, v123
	v_pk_add_f32 v[120:121], v[132:133], v[120:121]
	s_waitcnt lgkmcnt(0)
	v_mov_b32_e32 v122, v126
	v_mov_b32_e32 v123, v124
	v_mov_b32_e32 v124, v127
	v_pk_add_f32 v[122:123], v[122:123], v[124:125]
	v_add_f32_e32 v120, v120, v121
	v_add_f32_e32 v120, v120, v123
	v_add_f32_e32 v120, v122, v120
	v_fmamk_f32 v120, v120, 0x3b800000, v186
	v_mul_f32_e32 v121, 0x4f800000, v120
	v_cmp_gt_f32_e32 vcc, s91, v120
	s_nop 1
	v_cndmask_b32_e32 v120, v120, v121, vcc
	v_sqrt_f32_e32 v121, v120
	s_nop 0
	v_add_u32_e32 v124, -1, v121
	v_fma_f32 v125, -v124, v121, v120
	v_cmp_ge_f32_e64 s[8:9], 0, v125
	v_add_u32_e32 v125, 1, v121
	s_nop 0
	v_cndmask_b32_e64 v124, v121, v124, s[8:9]
	v_fma_f32 v121, -v125, v121, v120
	v_cmp_lt_f32_e64 s[8:9], 0, v121
	s_nop 1
	v_cndmask_b32_e64 v121, v124, v125, s[8:9]
	v_mul_f32_e32 v124, 0x37800000, v121
	v_cndmask_b32_e32 v121, v121, v124, vcc
	v_cmp_class_f32_e32 vcc, v120, v187
	s_nop 1
	v_cndmask_b32_e32 v124, v121, v120, vcc
	v_div_scale_f32 v125, s[8:9], v124, v124, 1.0
	v_rcp_f32_e32 v126, v125
	v_mov_b32_e32 v121, v243
	v_mov_b32_e32 v120, v244
	global_store_dwordx2 v[130:131], v[120:121], off offset:2080
	v_fma_f32 v120, -v125, v126, 1.0
	v_fmac_f32_e32 v126, v120, v126
	v_div_scale_f32 v120, vcc, 1.0, v124, 1.0
	v_mul_f32_e32 v121, v120, v126
	v_fma_f32 v122, -v125, v121, v120
	v_fmac_f32_e32 v121, v122, v126
	v_fma_f32 v120, -v125, v121, v120
	v_div_fmas_f32 v120, v120, v126, v121
	v_div_fixup_f32 v120, v120, v124, 1.0
	v_pk_mul_f32 v[110:111], v[110:111], v[120:121] op_sel_hi:[1,0]
	v_pk_mul_f32 v[108:109], v[108:109], v[120:121] op_sel_hi:[1,0]
	v_pk_mul_f32 v[110:111], v[142:143], v[110:111]
	v_pk_mul_f32 v[108:109], v[140:141], v[108:109]
	v_lshlrev_b32_e32 v123, 16, v151
	v_lshlrev_b32_e32 v122, 16, v150
	v_mov_b32_e32 v124, v108
	v_mov_b32_e32 v125, v110
	v_pk_mul_f32 v[122:123], v[124:125], v[122:123]
	v_and_b32_e32 v125, 0xffff0000, v151
	v_and_b32_e32 v124, 0xffff0000, v150
	v_mov_b32_e32 v110, v109
	v_pk_mul_f32 v[108:109], v[110:111], v[124:125]
	s_nop 0
	v_and_b32_sdwa v121, v109, v189 dst_sel:DWORD dst_unused:UNUSED_PAD src0_sel:WORD_1 src1_sel:DWORD
	v_cvt_pk_bf16_f32 v246, v122, v108
	v_cvt_pk_bf16_f32 v245, v123, v109
	v_add_co_u32_e32 v122, vcc, s93, v184
	v_pk_mul_f32 v[106:107], v[106:107], v[120:121] op_sel_hi:[1,0]
	v_pk_mul_f32 v[104:105], v[104:105], v[120:121] op_sel_hi:[1,0]
	v_mov_b32_e32 v109, v245
	v_mov_b32_e32 v108, v246
	v_addc_co_u32_e32 v123, vcc, 0, v185, vcc
	v_pk_mul_f32 v[104:105], v[136:137], v[104:105]
	v_pk_mul_f32 v[106:107], v[138:139], v[106:107]
	global_store_dwordx2 v[122:123], v[108:109], off offset:2048
	v_lshlrev_b32_e32 v109, 16, v149
	v_lshlrev_b32_e32 v108, 16, v148
	v_mov_b32_e32 v110, v104
	v_mov_b32_e32 v111, v106
	v_pk_mul_f32 v[108:109], v[110:111], v[108:109]
	v_and_b32_e32 v111, 0xffff0000, v149
	v_and_b32_e32 v110, 0xffff0000, v148
	v_mov_b32_e32 v106, v105
	v_pk_mul_f32 v[120:121], v[106:107], v[110:111]
	ds_read_b128 v[104:107], v210
	v_cvt_pk_bf16_f32 v248, v108, v120
	v_cvt_pk_bf16_f32 v247, v109, v121
	ds_read_b128 v[108:111], v210 offset:16
	s_waitcnt lgkmcnt(1)
	v_mov_b32_e32 v124, v105
	v_mov_b32_e32 v125, v106
	v_mov_b32_e32 v105, v107
	v_pk_add_f32 v[104:105], v[124:125], v[104:105]
	s_waitcnt lgkmcnt(0)
	v_mov_b32_e32 v106, v110
	v_mov_b32_e32 v107, v108
	v_mov_b32_e32 v108, v111
	v_pk_add_f32 v[106:107], v[106:107], v[108:109]
	v_add_f32_e32 v104, v104, v105
	v_add_f32_e32 v104, v104, v107
	v_add_f32_e32 v104, v106, v104
	v_fmamk_f32 v104, v104, 0x3b800000, v186
	v_mul_f32_e32 v105, 0x4f800000, v104
	v_cmp_gt_f32_e32 vcc, s91, v104
	s_nop 1
	v_cndmask_b32_e32 v104, v104, v105, vcc
	v_sqrt_f32_e32 v105, v104
	v_lshlrev_b32_e32 v111, 16, v147
	v_add_u32_e32 v108, -1, v105
	v_fma_f32 v109, -v108, v105, v104
	v_cmp_ge_f32_e64 s[8:9], 0, v109
	v_add_u32_e32 v109, 1, v105
	s_nop 0
	v_cndmask_b32_e64 v108, v105, v108, s[8:9]
	v_fma_f32 v105, -v109, v105, v104
	v_cmp_lt_f32_e64 s[8:9], 0, v105
	s_nop 1
	v_cndmask_b32_e64 v105, v108, v109, s[8:9]
	v_mul_f32_e32 v108, 0x37800000, v105
	v_cndmask_b32_e32 v105, v105, v108, vcc
	v_cmp_class_f32_e32 vcc, v104, v187
	s_nop 1
	v_cndmask_b32_e32 v108, v105, v104, vcc
	v_div_scale_f32 v109, s[8:9], v108, v108, 1.0
	v_rcp_f32_e32 v110, v109
	v_mov_b32_e32 v105, v247
	v_mov_b32_e32 v104, v248
	global_store_dwordx2 v[122:123], v[104:105], off offset:2080
	v_fma_f32 v104, -v109, v110, 1.0
	v_fmac_f32_e32 v110, v104, v110
	v_div_scale_f32 v104, vcc, 1.0, v108, 1.0
	v_mul_f32_e32 v105, v104, v110
	v_fma_f32 v106, -v109, v105, v104
	v_fmac_f32_e32 v105, v106, v110
	v_fma_f32 v104, -v109, v105, v104
	v_div_fmas_f32 v104, v104, v110, v105
	v_div_fixup_f32 v104, v104, v108, 1.0
	v_pk_mul_f32 v[106:107], v[118:119], v[104:105] op_sel_hi:[1,0]
	v_pk_mul_f32 v[108:109], v[116:117], v[104:105] op_sel_hi:[1,0]
	v_pk_mul_f32 v[106:107], v[142:143], v[106:107]
	v_pk_mul_f32 v[108:109], v[140:141], v[108:109]
	v_lshlrev_b32_e32 v110, 16, v146
	v_mov_b32_e32 v116, v108
	v_mov_b32_e32 v117, v106
	v_pk_mul_f32 v[110:111], v[116:117], v[110:111]
	v_and_b32_e32 v117, 0xffff0000, v147
	v_and_b32_e32 v116, 0xffff0000, v146
	v_mov_b32_e32 v106, v109
	v_pk_mul_f32 v[106:107], v[106:107], v[116:117]
	s_nop 0
	v_cvt_pk_bf16_f32 v249, v110, v106
	v_and_b32_sdwa v105, v111, v189 dst_sel:DWORD dst_unused:UNUSED_PAD src0_sel:WORD_1 src1_sel:DWORD
	v_cvt_pk_bf16_f32 v250, v111, v107
	v_add3_u32 v105, v111, v105, s89
	v_mov_b32_e32 v106, v249
	v_add_co_u32_e32 v108, vcc, s94, v184
	v_mov_b32_e32 v107, v250
	s_nop 0
	v_addc_co_u32_e32 v109, vcc, 0, v185, vcc
	global_store_dwordx2 v[108:109], v[106:107], off offset:2048
	v_pk_mul_f32 v[106:107], v[114:115], v[104:105] op_sel_hi:[1,0]
	v_pk_mul_f32 v[104:105], v[112:113], v[104:105] op_sel_hi:[1,0]
	v_pk_mul_f32 v[106:107], v[138:139], v[106:107]
	v_pk_mul_f32 v[104:105], v[136:137], v[104:105]
	v_lshlrev_b32_e32 v111, 16, v145
	v_lshlrev_b32_e32 v110, 16, v144
	v_mov_b32_e32 v112, v104
	v_mov_b32_e32 v113, v106
	v_pk_mul_f32 v[110:111], v[112:113], v[110:111]
	v_and_b32_e32 v113, 0xffff0000, v145
	v_and_b32_e32 v112, 0xffff0000, v144
	v_mov_b32_e32 v106, v105
	v_pk_mul_f32 v[104:105], v[106:107], v[112:113]
	s_nop 0
	v_cvt_pk_bf16_f32 v252, v110, v104
	v_cvt_pk_bf16_f32 v251, v111, v105
	v_mov_b32_e32 v105, v251
	v_mov_b32_e32 v104, v252
	global_store_dwordx2 v[108:109], v[104:105], off offset:2080
	s_barrier
	s_cbranch_scc0 .LBB0_557

; #define LAS __attribute__((address_space(3)))
; __device__ __forceinline__ float bflo(unsigned w) { return __uint_as_float(w << 16); }
; __device__ __forceinline__ float bfhi(unsigned w) { return __uint_as_float(w & 0xffff0000u); }
; __device__ __forceinline__ unsigned pk2(float lo, float hi) { return f2bf(lo) | (f2bf(hi) << 16); }
; __device__ __forceinline__ void phase_mixer_a(const Params& P, LAS unsigned char* lds, int ustart, int ustride, bool dry) {
;     ...
;             u32x2 pv[8]; float bsv[8];
; #pragma unroll
;             for (int mt = 0; mt < 8; ++mt) { const int t = 16 * mt + (lane & 15);
;                 pv[mt] = *(const u32x2*)(PJ + T_P + (size_t)(r0 + t) * 1024 + h * 128 + 16 * w + 4 * g4); bsv[mt] = P.b_spatial[h * 128 + t]; }
;             f32x4 acc[8];
; #pragma unroll
;             for (int mt = 0; mt < 8; ++mt) acc[mt] = (f32x4){0.f, 0.f, 0.f, 0.f};
; #pragma unroll
;             for (int ks = 0; ks < 4; ++ks) {
;                 const unsigned a0 = (unsigned)((32 * ks + 8 * g4 + q) * VN_P + 32 * w + 8 * p);
;                 const s16x4 lo = __builtin_amdgcn_ds_read_tr16_b64_v4i16((LAS s16x4*)(lds + a0)), hi = __builtin_amdgcn_ds_read_tr16_b64_v4i16((LAS s16x4*)(lds + a0 + 4 * VN_P));
;                 const bf16x8 vf = (bf16x8){lo[0], lo[1], lo[2], lo[3], hi[0], hi[1], hi[2], hi[3]};
; #pragma unroll
;                 for (int mt = 2 * ks; mt < 8; ++mt) {
;                     const bf16x8 wf = *(const LAS bf16x8*)(lds + W_OFF + (16 * mt + (lane & 15)) * W_P + (32 * ks + 8 * g4) * 2);
;                     acc[mt] = __builtin_amdgcn_mfma_f32_16x16x32_bf16(vf, wf, acc[mt], 0, 0, 0);
;                 }
;             }
; #pragma unroll
;             for (int mt = 0; mt < 8; ++mt) {
;                 const int t = 16 * mt + (lane & 15); const float bs = bsv[mt];
;                 u32x2 o; o.x = pk2(bflo(pv[mt].x) * (acc[mt][0] + bs), bfhi(pv[mt].x) * (acc[mt][1] + bs)); o.y = pk2(bflo(pv[mt].y) * (acc[mt][2] + bs), bfhi(pv[mt].y) * (acc[mt][3] + bs));
;                 if (!dry) *(u32x2*)((bf16_t*)P.out + (size_t)(r0 + t) * 2048 + h * 128 + 16 * w + 4 * g4) = o;
;             }
.LBB0_594:
	ds_read_b64_tr_b16 v[16:17], v171
	ds_read_b64_tr_b16 v[18:19], v171 offset:1152
	v_add_u32_e32 v37, v150, v151
	ds_read_b128 v[20:23], v37 offset:36864
	ds_read_b128 v[24:27], v37 offset:41216
	v_lshl_add_u64 v[136:137], v[102:103], 0, s[12:13]
	v_lshl_add_u64 v[212:213], v[68:69], 0, s[6:7]
	s_waitcnt lgkmcnt(1)
	v_mfma_f32_16x16x32_bf16 v[28:31], v[16:19], v[20:23], 0
	ds_read_b128 v[20:23], v37 offset:45568
	global_load_dwordx2 v[192:193], v[136:137], off
	ds_read_b128 v[136:139], v37 offset:49920
	global_load_dword v214, v[212:213], off
	ds_read_b128 v[176:179], v37 offset:54272
	ds_read_b128 v[180:183], v37 offset:58624
	v_lshl_add_u64 v[200:201], v[104:105], 0, s[12:13]
	v_add_u32_e32 v39, v150, v152
	ds_read_b128 v[184:187], v37 offset:62976
	ds_read_b64_tr_b16 v[188:189], v172
	ds_read_b64_tr_b16 v[190:191], v172 offset:1152
	ds_read_b128 v[196:199], v39 offset:62976
	v_add_u32_e32 v37, v153, v151
	global_load_dwordx2 v[216:217], v[200:201], off
	ds_read_b128 v[200:203], v37 offset:45568
	s_waitcnt lgkmcnt(8)
	v_mfma_f32_16x16x32_bf16 v[20:23], v[16:19], v[20:23], 0
	global_load_dword v218, v[212:213], off offset:64
	v_add_u32_e32 v39, v153, v152
	v_lshl_add_u64 v[208:209], v[106:107], 0, s[12:13]
	v_mfma_f32_16x16x32_bf16 v[24:27], v[16:19], v[24:27], 0
	v_lshl_add_u64 v[210:211], v[108:109], 0, s[12:13]
	v_lshl_add_u64 v[220:221], v[110:111], 0, s[12:13]
	v_lshl_add_u64 v[222:223], v[112:113], 0, s[12:13]
	s_waitcnt lgkmcnt(7)
	v_mfma_f32_16x16x32_bf16 v[136:139], v[16:19], v[136:139], 0
	v_lshl_add_u64 v[224:225], v[114:115], 0, s[12:13]
	v_add_u32_e32 v41, v155, v152
	v_lshl_add_u64 v[226:227], v[116:117], 0, s[12:13]
	s_waitcnt lgkmcnt(6)
	v_mfma_f32_16x16x32_bf16 v[176:179], v[16:19], v[176:179], 0
	v_lshl_add_u64 v[134:135], v[134:135], 0, s[10:11]
	v_lshl_add_u64 v[132:133], v[132:133], 0, s[10:11]
	v_lshl_add_u64 v[130:131], v[130:131], 0, s[10:11]
	s_waitcnt lgkmcnt(5)
	v_mfma_f32_16x16x32_bf16 v[180:183], v[16:19], v[180:183], 0
	v_lshl_add_u64 v[128:129], v[128:129], 0, s[10:11]
	s_waitcnt lgkmcnt(4)
	v_mfma_f32_16x16x32_bf16 v[184:187], v[16:19], v[184:187], 0
	s_waitcnt lgkmcnt(1)
	v_mfma_f32_16x16x32_bf16 v[16:19], v[16:19], v[196:199], 0
	ds_read_b128 v[196:199], v37 offset:49920
	s_waitcnt lgkmcnt(1)
	v_mfma_f32_16x16x32_bf16 v[200:203], v[188:191], v[200:203], v[20:23]
	s_nop 2
	ds_read_b128 v[20:23], v37 offset:54272
	s_waitcnt lgkmcnt(1)
	v_mfma_f32_16x16x32_bf16 v[136:139], v[188:191], v[196:199], v[136:139]
	ds_read_b128 v[196:199], v37 offset:58624
	s_waitcnt lgkmcnt(1)
	v_mfma_f32_16x16x32_bf16 v[20:23], v[188:191], v[20:23], v[176:179]
	s_nop 2
	ds_read_b128 v[176:179], v37 offset:62976
	s_waitcnt lgkmcnt(1)
	v_mfma_f32_16x16x32_bf16 v[180:183], v[188:191], v[196:199], v[180:183]
	ds_read_b64_tr_b16 v[196:197], v173
	ds_read_b64_tr_b16 v[198:199], v173 offset:1152
	ds_read_b128 v[204:207], v39 offset:62976
	v_add_u32_e32 v37, v154, v151
	global_load_dwordx2 v[228:229], v[208:209], off
	s_waitcnt lgkmcnt(3)
	v_mfma_f32_16x16x32_bf16 v[176:179], v[188:191], v[176:179], v[184:187]
	global_load_dword v230, v[212:213], off offset:128
	v_add_u32_e32 v39, v154, v152
	s_nop 0
	ds_read_b128 v[184:187], v37 offset:54272
	s_waitcnt lgkmcnt(1)
	v_mfma_f32_16x16x32_bf16 v[16:19], v[188:191], v[204:207], v[16:19]
	ds_read_b128 v[188:191], v37 offset:58624
	s_waitcnt lgkmcnt(1)
	v_mfma_f32_16x16x32_bf16 v[184:187], v[196:199], v[184:187], v[20:23]
	ds_read_b64_tr_b16 v[204:205], v174
	ds_read_b64_tr_b16 v[206:207], v174 offset:1152
	s_nop 0
	ds_read_b128 v[20:23], v37 offset:62976
	v_add_u32_e32 v37, v155, v151
	s_waitcnt lgkmcnt(3)
	v_mfma_f32_16x16x32_bf16 v[180:183], v[196:199], v[188:191], v[180:183]
	ds_read_b128 v[188:191], v39 offset:62976
	global_load_dwordx2 v[232:233], v[210:211], off
	s_nop 0
	global_load_dwordx2 v[220:221], v[220:221], off
	ds_read_b128 v[208:211], v37 offset:62976
	s_waitcnt lgkmcnt(2)
	v_mfma_f32_16x16x32_bf16 v[176:179], v[196:199], v[20:23], v[176:179]
	s_waitcnt lgkmcnt(1)
	v_mfma_f32_16x16x32_bf16 v[16:19], v[196:199], v[188:191], v[16:19]
	global_load_dwordx2 v[196:197], v[222:223], off
	global_load_dwordx2 v[198:199], v[224:225], off
	global_load_dwordx2 v[20:21], v[226:227], off
	ds_read_b128 v[188:191], v41 offset:62976
	s_waitcnt lgkmcnt(1)
	v_mfma_f32_16x16x32_bf16 v[176:179], v[204:207], v[208:211], v[176:179]
	global_load_dword v208, v[212:213], off offset:192
	global_load_dword v210, v[212:213], off offset:256
	global_load_dword v222, v[212:213], off offset:320
	global_load_dword v224, v[212:213], off offset:384
	global_load_dword v22, v[212:213], off offset:448
	s_waitcnt lgkmcnt(0)
	v_mfma_f32_16x16x32_bf16 v[16:19], v[204:207], v[188:191], v[16:19]
	v_mov_b32_e32 v190, v28
	v_mov_b32_e32 v191, v30
	s_waitcnt vmcnt(15)
	v_lshlrev_b32_e32 v189, 16, v193
	v_lshlrev_b32_e32 v188, 16, v192
	s_waitcnt vmcnt(14)
	v_pk_add_f32 v[190:191], v[214:215], v[190:191] op_sel_hi:[0,1]
	v_mov_b32_e32 v30, v29
	v_pk_mul_f32 v[188:189], v[190:191], v[188:189]
	v_and_b32_e32 v191, 0xffff0000, v193
	v_and_b32_e32 v190, 0xffff0000, v192
	v_pk_add_f32 v[28:29], v[214:215], v[30:31] op_sel_hi:[0,1]
	v_pk_mul_f32 v[28:29], v[28:29], v[190:191]
	s_nop 0
	v_cvt_pk_bf16_f32 v253, v189, v29
	v_cvt_pk_bf16_f32 v254, v188, v28
	v_mov_b32_e32 v29, v253
	v_mov_b32_e32 v28, v254
	v_lshl_add_u64 v[30:31], v[118:119], 0, s[12:13]
	global_store_dwordx2 v[30:31], v[28:29], off
	v_mov_b32_e32 v30, v24
	v_mov_b32_e32 v31, v26
	s_waitcnt vmcnt(14)
	v_lshlrev_b32_e32 v29, 16, v217
	v_lshlrev_b32_e32 v28, 16, v216
	s_waitcnt vmcnt(13)
; __device__ __forceinline__ float bflo(unsigned w) { return __uint_as_float(w << 16); }
; __device__ __forceinline__ float bfhi(unsigned w) { return __uint_as_float(w & 0xffff0000u); }
; __device__ __forceinline__ unsigned pk2(float lo, float hi) { return f2bf(lo) | (f2bf(hi) << 16); }
; __device__ __forceinline__ void phase_mixer_a(const Params& P, LAS unsigned char* lds, int ustart, int ustride, bool dry) {
;     ...
; #pragma unroll
;             for (int mt = 0; mt < 8; ++mt) {
;                 const int t = 16 * mt + (lane & 15); const float bs = bsv[mt];
;                 u32x2 o; o.x = pk2(bflo(pv[mt].x) * (acc[mt][0] + bs), bfhi(pv[mt].x) * (acc[mt][1] + bs)); o.y = pk2(bflo(pv[mt].y) * (acc[mt][2] + bs), bfhi(pv[mt].y) * (acc[mt][3] + bs));
;                 if (!dry) *(u32x2*)((bf16_t*)P.out + (size_t)(r0 + t) * 2048 + h * 128 + 16 * w + 4 * g4) = o;
;             }
;             __syncthreads();
	v_pk_add_f32 v[30:31], v[218:219], v[30:31] op_sel_hi:[0,1]
	v_mov_b32_e32 v26, v25
	v_pk_mul_f32 v[28:29], v[30:31], v[28:29]
	v_and_b32_e32 v31, 0xffff0000, v217
	v_and_b32_e32 v30, 0xffff0000, v216
	v_pk_add_f32 v[24:25], v[218:219], v[26:27] op_sel_hi:[0,1]
	v_pk_mul_f32 v[24:25], v[24:25], v[30:31]
	s_nop 0
	v_cvt_pk_bf16_f32 v237, v28, v24
	v_cvt_pk_bf16_f32 v255, v29, v25
	v_mov_b32_e32 v25, v255
	v_mov_b32_e32 v24, v237
	v_lshl_add_u64 v[26:27], v[120:121], 0, s[12:13]
	global_store_dwordx2 v[26:27], v[24:25], off
	v_mov_b32_e32 v26, v200
	v_mov_b32_e32 v27, v202
	s_waitcnt vmcnt(13)
	v_lshlrev_b32_e32 v25, 16, v229
	v_lshlrev_b32_e32 v24, 16, v228
	s_waitcnt vmcnt(12)
	v_pk_add_f32 v[26:27], v[230:231], v[26:27] op_sel_hi:[0,1]
	v_mov_b32_e32 v202, v201
	v_pk_mul_f32 v[24:25], v[26:27], v[24:25]
	v_and_b32_e32 v27, 0xffff0000, v229
	v_and_b32_e32 v26, 0xffff0000, v228
	v_pk_add_f32 v[28:29], v[230:231], v[202:203] op_sel_hi:[0,1]
	v_pk_mul_f32 v[26:27], v[28:29], v[26:27]
	s_nop 0
	v_cvt_pk_bf16_f32 v239, v24, v26
	v_cvt_pk_bf16_f32 v238, v25, v27
	v_mov_b32_e32 v25, v238
	v_mov_b32_e32 v24, v239
	v_lshl_add_u64 v[26:27], v[122:123], 0, s[12:13]
	global_store_dwordx2 v[26:27], v[24:25], off
	v_mov_b32_e32 v26, v136
	v_mov_b32_e32 v27, v138
	s_waitcnt vmcnt(12)
	v_lshlrev_b32_e32 v25, 16, v233
	v_lshlrev_b32_e32 v24, 16, v232
	s_waitcnt vmcnt(7)
	v_pk_add_f32 v[26:27], v[208:209], v[26:27] op_sel_hi:[0,1]
	v_mov_b32_e32 v138, v137
	v_pk_mul_f32 v[24:25], v[26:27], v[24:25]
	v_and_b32_e32 v27, 0xffff0000, v233
	v_and_b32_e32 v26, 0xffff0000, v232
	v_pk_add_f32 v[28:29], v[208:209], v[138:139] op_sel_hi:[0,1]
	v_pk_mul_f32 v[26:27], v[28:29], v[26:27]
	s_nop 0
	v_cvt_pk_bf16_f32 v241, v24, v26
	v_cvt_pk_bf16_f32 v240, v25, v27
	v_mov_b32_e32 v25, v240
	v_mov_b32_e32 v24, v241
	v_lshl_add_u64 v[26:27], v[124:125], 0, s[12:13]
	global_store_dwordx2 v[26:27], v[24:25], off
	v_mov_b32_e32 v26, v184
	v_mov_b32_e32 v27, v186
	v_lshlrev_b32_e32 v25, 16, v221
	v_lshlrev_b32_e32 v24, 16, v220
	s_waitcnt vmcnt(7)
	v_pk_add_f32 v[26:27], v[210:211], v[26:27] op_sel_hi:[0,1]
	v_mov_b32_e32 v186, v185
	v_pk_mul_f32 v[24:25], v[26:27], v[24:25]
	v_and_b32_e32 v27, 0xffff0000, v221
	v_and_b32_e32 v26, 0xffff0000, v220
	v_pk_add_f32 v[28:29], v[210:211], v[186:187] op_sel_hi:[0,1]
	v_pk_mul_f32 v[26:27], v[28:29], v[26:27]
	s_nop 0
	v_cvt_pk_bf16_f32 v243, v24, v26
	v_cvt_pk_bf16_f32 v242, v25, v27
	v_mov_b32_e32 v25, v242
	v_mov_b32_e32 v24, v243
	v_lshl_add_u64 v[26:27], v[126:127], 0, s[12:13]
	global_store_dwordx2 v[26:27], v[24:25], off
	v_mov_b32_e32 v26, v180
	v_mov_b32_e32 v27, v182
	v_lshlrev_b32_e32 v25, 16, v197
	v_lshlrev_b32_e32 v24, 16, v196
	s_waitcnt vmcnt(7)
	v_pk_add_f32 v[26:27], v[222:223], v[26:27] op_sel_hi:[0,1]
	v_mov_b32_e32 v182, v181
	v_pk_mul_f32 v[24:25], v[26:27], v[24:25]
	v_and_b32_e32 v27, 0xffff0000, v197
	v_and_b32_e32 v26, 0xffff0000, v196
	v_pk_add_f32 v[28:29], v[222:223], v[182:183] op_sel_hi:[0,1]
	v_pk_mul_f32 v[26:27], v[28:29], v[26:27]
	s_nop 0
	v_cvt_pk_bf16_f32 v245, v24, v26
	v_cvt_pk_bf16_f32 v244, v25, v27
	v_mov_b32_e32 v25, v244
	v_mov_b32_e32 v24, v245
	v_lshl_add_u64 v[26:27], v[100:101], 0, s[12:13]
	global_store_dwordx2 v[26:27], v[24:25], off
	v_mov_b32_e32 v26, v176
	v_mov_b32_e32 v27, v178
	v_lshlrev_b32_e32 v25, 16, v199
	v_lshlrev_b32_e32 v24, 16, v198
	s_waitcnt vmcnt(7)
	v_pk_add_f32 v[26:27], v[224:225], v[26:27] op_sel_hi:[0,1]
	v_mov_b32_e32 v178, v177
	v_pk_mul_f32 v[24:25], v[26:27], v[24:25]
	v_and_b32_e32 v27, 0xffff0000, v199
	v_and_b32_e32 v26, 0xffff0000, v198
	v_pk_add_f32 v[28:29], v[224:225], v[178:179] op_sel_hi:[0,1]
	v_pk_mul_f32 v[26:27], v[28:29], v[26:27]
	v_and_b32_sdwa v23, v25, v175 dst_sel:DWORD dst_unused:UNUSED_PAD src0_sel:WORD_1 src1_sel:DWORD
	v_cvt_pk_bf16_f32 v247, v24, v26
	v_add3_u32 v23, v25, v23, s15
	v_cvt_pk_bf16_f32 v246, v25, v27
	v_mov_b32_e32 v25, v246
	v_mov_b32_e32 v24, v247
	v_lshl_add_u64 v[26:27], v[98:99], 0, s[12:13]
	global_store_dwordx2 v[26:27], v[24:25], off
	v_mov_b32_e32 v27, v18
	v_mov_b32_e32 v18, v17
	v_lshlrev_b32_e32 v25, 16, v21
	v_lshlrev_b32_e32 v24, 16, v20
	v_mov_b32_e32 v26, v16
	v_and_b32_e32 v21, 0xffff0000, v21
	v_and_b32_e32 v20, 0xffff0000, v20
	s_waitcnt vmcnt(7)
	v_pk_add_f32 v[16:17], v[22:23], v[18:19] op_sel_hi:[0,1]
	v_pk_add_f32 v[26:27], v[22:23], v[26:27] op_sel_hi:[0,1]
	v_pk_mul_f32 v[16:17], v[16:17], v[20:21]
	v_pk_mul_f32 v[24:25], v[26:27], v[24:25]
	s_nop 0
	v_cvt_pk_bf16_f32 v248, v25, v17
	v_cvt_pk_bf16_f32 v249, v24, v16
	v_mov_b32_e32 v17, v248
	v_mov_b32_e32 v16, v249
	v_lshl_add_u64 v[18:19], v[96:97], 0, s[12:13]
	s_add_u32 s12, s12, 0x100
	s_addc_u32 s13, s13, 0
	s_add_u32 s6, s6, 0x200
	s_addc_u32 s7, s7, 0
	s_cmpk_eq_i32 s12, 0x800
	global_store_dwordx2 v[18:19], v[16:17], off
	s_barrier
	s_cbranch_scc1 .LBB0_582
; #define LAS __attribute__((address_space(3)))
; __device__ __forceinline__ float bflo(unsigned w) { return __uint_as_float(w << 16); }
; __device__ __forceinline__ float bfhi(unsigned w) { return __uint_as_float(w & 0xffff0000u); }
; __device__ __forceinline__ unsigned pk2(float lo, float hi) { return f2bf(lo) | (f2bf(hi) << 16); }
; __device__ __forceinline__ void phase_mixer_a(const Params& P, LAS unsigned char* lds, int ustart, int ustride, bool dry) {
;     ...
;             for (int i = 0; i < 4; ++i) {
;                 const int item = tid + 512 * i, c8 = item & 15, s = item >> 4;
;                 const u32x4 gv = pgv[i];
;                 const float mean = stats[2 * s], rstd = stats[2 * s + 1];
;                 const f32x4 g0 = *(const f32x4*)(P.ln_v_g + h * 128 + c8 * 8), g1 = *(const f32x4*)(P.ln_v_g + h * 128 + c8 * 8 + 4);
;                 const f32x4 b0 = *(const f32x4*)(P.ln_v_b + h * 128 + c8 * 8), b1 = *(const f32x4*)(P.ln_v_b + h * 128 + c8 * 8 + 4);
;                 u32x4 o;
;                 o.x = pk2((bflo(gv.x) - mean) * rstd * g0[0] + b0[0], (bfhi(gv.x) - mean) * rstd * g0[1] + b0[1]);
;                 o.y = pk2((bflo(gv.y) - mean) * rstd * g0[2] + b0[2], (bfhi(gv.y) - mean) * rstd * g0[3] + b0[3]);
;                 o.z = pk2((bflo(gv.z) - mean) * rstd * g1[0] + b1[0], (bfhi(gv.z) - mean) * rstd * g1[1] + b1[1]);
;                 o.w = pk2((bflo(gv.w) - mean) * rstd * g1[2] + b1[2], (bfhi(gv.w) - mean) * rstd * g1[3] + b1[3]);
;                 *(LAS u32x4*)(lds + s * VN_P + c8 * 16) = o;
;                 *(LAS u32x4*)(lds + W_OFF + s * W_P + c8 * 16) = *(const u32x4*)(WsT + h * 16384 + item * 8);
;             }
;             __syncthreads();
.LBB0_595:
	v_lshl_add_u64 v[16:17], v[72:73], 0, s[6:7]
	global_load_dwordx4 v[24:27], v[16:17], off offset:-16
	v_lshl_add_u64 v[20:21], v[76:77], 0, s[6:7]
	global_load_dwordx4 v[28:31], v[20:21], off offset:-16
	s_nop 0
	global_load_dwordx4 v[16:19], v[16:17], off
	s_nop 0
	global_load_dwordx4 v[20:23], v[20:21], off
	s_nop 0
	global_load_dwordx4 v[176:179], v[134:135], off
	global_load_dwordx4 v[180:183], v[132:133], off
	ds_read_b64 v[136:137], v159
	s_waitcnt vmcnt(9)
	v_lshlrev_b32_e32 v139, 16, v1
	v_lshlrev_b32_e32 v138, 16, v0
	v_and_b32_e32 v185, 0xffff0000, v1
	v_and_b32_e32 v184, 0xffff0000, v0
	v_lshlrev_b32_e32 v187, 16, v3
	v_lshlrev_b32_e32 v186, 16, v2
	v_and_b32_e32 v189, 0xffff0000, v3
	v_and_b32_e32 v188, 0xffff0000, v2
	s_waitcnt lgkmcnt(0)
	v_pk_add_f32 v[138:139], v[138:139], v[136:137] op_sel_hi:[1,0] neg_lo:[0,1] neg_hi:[0,1]
	v_pk_add_f32 v[184:185], v[184:185], v[136:137] op_sel_hi:[1,0] neg_lo:[0,1] neg_hi:[0,1]
	v_pk_add_f32 v[186:187], v[186:187], v[136:137] op_sel_hi:[1,0] neg_lo:[0,1] neg_hi:[0,1]
	v_pk_add_f32 v[188:189], v[188:189], v[136:137] op_sel_hi:[1,0] neg_lo:[0,1] neg_hi:[0,1]
	v_pk_mul_f32 v[198:199], v[136:137], v[138:139] op_sel:[1,0]
	v_pk_mul_f32 v[184:185], v[136:137], v[184:185] op_sel:[1,0]
	v_pk_mul_f32 v[186:187], v[136:137], v[186:187] op_sel:[1,0]
	v_pk_mul_f32 v[188:189], v[136:137], v[188:189] op_sel:[1,0]
	s_waitcnt vmcnt(8)
	v_lshlrev_b32_e32 v191, 16, v5
	v_lshlrev_b32_e32 v190, 16, v4
	v_and_b32_e32 v193, 0xffff0000, v5
	v_and_b32_e32 v192, 0xffff0000, v4
	v_lshlrev_b32_e32 v197, 16, v7
	v_lshlrev_b32_e32 v196, 16, v6
	s_cmpk_lg_i32 s12, 0x700
	s_waitcnt vmcnt(4)
	v_mov_b32_e32 v138, v28
	v_mov_b32_e32 v136, v24
	v_mov_b32_e32 v137, v26
	v_mov_b32_e32 v139, v30
	v_mov_b32_e32 v26, v25
	v_mov_b32_e32 v30, v29
	s_waitcnt vmcnt(3)
	v_mov_b32_e32 v24, v16
	v_mov_b32_e32 v25, v18
	s_waitcnt vmcnt(2)
	v_mov_b32_e32 v28, v20
	v_mov_b32_e32 v29, v22
	v_mov_b32_e32 v18, v17
	v_mov_b32_e32 v22, v21
	v_pk_fma_f32 v[16:17], v[198:199], v[136:137], v[138:139]
	v_pk_fma_f32 v[20:21], v[184:185], v[26:27], v[30:31]
	v_pk_fma_f32 v[184:185], v[186:187], v[24:25], v[28:29]
	v_pk_fma_f32 v[186:187], v[188:189], v[18:19], v[22:23]
	v_cvt_pk_bf16_f32 v251, v16, v20
	v_cvt_pk_bf16_f32 v250, v17, v21
	v_cvt_pk_bf16_f32 v187, v185, v187
	v_cvt_pk_bf16_f32 v186, v184, v186
	v_mov_b32_e32 v185, v250
	v_mov_b32_e32 v184, v251
	ds_write_b128 v160, v[184:187]
	s_waitcnt vmcnt(1)
	ds_write_b128 v161, v[176:179] offset:36864
	ds_read_b64 v[16:17], v162
	global_load_dwordx4 v[176:179], v[130:131], off
	v_and_b32_e32 v21, 0xffff0000, v7
	v_and_b32_e32 v20, 0xffff0000, v6
	s_waitcnt lgkmcnt(0)
	v_pk_add_f32 v[184:185], v[190:191], v[16:17] op_sel_hi:[1,0] neg_lo:[0,1] neg_hi:[0,1]
	v_pk_add_f32 v[186:187], v[192:193], v[16:17] op_sel_hi:[1,0] neg_lo:[0,1] neg_hi:[0,1]
	v_pk_add_f32 v[188:189], v[196:197], v[16:17] op_sel_hi:[1,0] neg_lo:[0,1] neg_hi:[0,1]
	v_pk_add_f32 v[20:21], v[20:21], v[16:17] op_sel_hi:[1,0] neg_lo:[0,1] neg_hi:[0,1]
	v_pk_mul_f32 v[184:185], v[16:17], v[184:185] op_sel:[1,0]
	v_pk_mul_f32 v[186:187], v[16:17], v[186:187] op_sel:[1,0]
	v_pk_mul_f32 v[188:189], v[16:17], v[188:189] op_sel:[1,0]
	v_pk_mul_f32 v[16:17], v[16:17], v[20:21] op_sel:[1,0]
	v_pk_fma_f32 v[20:21], v[136:137], v[184:185], v[138:139]
	v_pk_fma_f32 v[16:17], v[18:19], v[16:17], v[22:23]
	v_pk_fma_f32 v[184:185], v[26:27], v[186:187], v[30:31]
	v_pk_fma_f32 v[186:187], v[24:25], v[188:189], v[28:29]
	s_nop 0
	v_cvt_pk_bf16_f32 v253, v186, v16
	v_cvt_pk_bf16_f32 v252, v187, v17
	v_cvt_pk_bf16_f32 v254, v21, v185
	v_cvt_pk_bf16_f32 v255, v20, v184
	v_mov_b32_e32 v187, v252
	v_mov_b32_e32 v186, v253
	v_mov_b32_e32 v185, v254
	v_mov_b32_e32 v184, v255
	ds_write_b128 v163, v[184:187]
	s_waitcnt vmcnt(1)
	ds_write_b128 v164, v[180:183] offset:36864
	ds_read_b64 v[16:17], v165
	v_and_b32_e32 v181, 0xffff0000, v9
	v_and_b32_e32 v180, 0xffff0000, v8
	v_lshlrev_b32_e32 v21, 16, v9
	v_lshlrev_b32_e32 v20, 16, v8
	s_waitcnt lgkmcnt(0)
	v_pk_add_f32 v[180:181], v[180:181], v[16:17] op_sel_hi:[1,0] neg_lo:[0,1] neg_hi:[0,1]
	v_and_b32_e32 v189, 0xffff0000, v11
	v_pk_mul_f32 v[180:181], v[16:17], v[180:181] op_sel:[1,0]
	v_and_b32_e32 v188, 0xffff0000, v10
	v_pk_fma_f32 v[184:185], v[26:27], v[180:181], v[30:31]
	v_lshlrev_b32_e32 v181, 16, v11
	v_lshlrev_b32_e32 v180, 16, v10
	v_pk_add_f32 v[180:181], v[180:181], v[16:17] op_sel_hi:[1,0] neg_lo:[0,1] neg_hi:[0,1]
	v_pk_add_f32 v[20:21], v[20:21], v[16:17] op_sel_hi:[1,0] neg_lo:[0,1] neg_hi:[0,1]
	v_pk_mul_f32 v[180:181], v[16:17], v[180:181] op_sel:[1,0]
	v_pk_add_f32 v[188:189], v[188:189], v[16:17] op_sel_hi:[1,0] neg_lo:[0,1] neg_hi:[0,1]
	v_pk_fma_f32 v[186:187], v[24:25], v[180:181], v[28:29]
	global_load_dwordx4 v[180:183], v[128:129], off
	v_pk_mul_f32 v[20:21], v[16:17], v[20:21] op_sel:[1,0]
	v_pk_mul_f32 v[16:17], v[16:17], v[188:189] op_sel:[1,0]
	v_pk_fma_f32 v[20:21], v[136:137], v[20:21], v[138:139]
	v_pk_fma_f32 v[16:17], v[18:19], v[16:17], v[22:23]
	s_nop 0
	v_cvt_pk_bf16_f32 v238, v186, v16
	v_cvt_pk_bf16_f32 v237, v187, v17
	v_cvt_pk_bf16_f32 v239, v21, v185
	v_cvt_pk_bf16_f32 v240, v20, v184
	v_mov_b32_e32 v187, v237
	v_mov_b32_e32 v186, v238
	v_mov_b32_e32 v185, v239
	v_mov_b32_e32 v184, v240
	ds_write_b128 v166, v[184:187]
	s_waitcnt vmcnt(1)
	ds_write_b128 v167, v[176:179] offset:36864
	ds_read_b64 v[16:17], v168
	v_lshlrev_b32_e32 v21, 16, v13
	v_lshlrev_b32_e32 v20, 16, v12
	s_waitcnt lgkmcnt(0)
	v_pk_add_f32 v[20:21], v[20:21], v[16:17] op_sel_hi:[1,0] neg_lo:[0,1] neg_hi:[0,1]
	s_nop 0
	v_pk_mul_f32 v[20:21], v[16:17], v[20:21] op_sel:[1,0]
	s_nop 0
	v_pk_fma_f32 v[20:21], v[136:137], v[20:21], v[138:139]
	v_and_b32_e32 v137, 0xffff0000, v13
	v_and_b32_e32 v136, 0xffff0000, v12
	v_pk_add_f32 v[136:137], v[136:137], v[16:17] op_sel_hi:[1,0] neg_lo:[0,1] neg_hi:[0,1]
	s_nop 0
	v_pk_mul_f32 v[136:137], v[16:17], v[136:137] op_sel:[1,0]
	s_nop 0
	v_pk_fma_f32 v[26:27], v[26:27], v[136:137], v[30:31]
	v_lshlrev_b32_e32 v31, 16, v15
	v_lshlrev_b32_e32 v30, 16, v14
	v_pk_add_f32 v[30:31], v[30:31], v[16:17] op_sel_hi:[1,0] neg_lo:[0,1] neg_hi:[0,1]
	s_nop 0
	v_pk_mul_f32 v[30:31], v[16:17], v[30:31] op_sel:[1,0]
	s_nop 0
	v_pk_fma_f32 v[24:25], v[24:25], v[30:31], v[28:29]
	v_and_b32_e32 v29, 0xffff0000, v15
	v_and_b32_e32 v28, 0xffff0000, v14
	v_pk_add_f32 v[28:29], v[28:29], v[16:17] op_sel_hi:[1,0] neg_lo:[0,1] neg_hi:[0,1]
	s_nop 0
	v_pk_mul_f32 v[16:17], v[16:17], v[28:29] op_sel:[1,0]
	s_nop 0
	v_pk_fma_f32 v[16:17], v[18:19], v[16:17], v[22:23]
	s_nop 0
	v_cvt_pk_bf16_f32 v242, v24, v16
	v_cvt_pk_bf16_f32 v241, v25, v17
	v_cvt_pk_bf16_f32 v244, v20, v26
	v_cvt_pk_bf16_f32 v243, v21, v27
	v_mov_b32_e32 v19, v241
	v_mov_b32_e32 v18, v242
	v_mov_b32_e32 v17, v243
	v_mov_b32_e32 v16, v244
	ds_write_b128 v169, v[16:19]
	s_waitcnt vmcnt(0)
	ds_write_b128 v170, v[180:183] offset:36864
	s_waitcnt lgkmcnt(0)
	s_barrier
; __device__ __forceinline__ void phase_mixer_a(const Params& P, LAS unsigned char* lds, int ustart, int ustride, bool dry) {
;     ...
;             if (h + 1 < 8) {
; #pragma unroll
;                 for (int i = 0; i < 4; ++i) { const int item = tid + 512 * i, c8 = item & 15, s = item >> 4;
;                     pgv[i] = *(const u32x4*)(PJ + T_GV + (size_t)(r0 + s) * 1024 + (h + 1) * 128 + c8 * 8); }
;             }
	s_cbranch_scc0 .LBB0_594
	v_lshl_add_u64 v[12:13], v[94:95], 0, s[12:13]
	v_lshl_add_u64 v[8:9], v[92:93], 0, s[12:13]
	v_lshl_add_u64 v[4:5], v[90:91], 0, s[12:13]
	v_lshl_add_u64 v[0:1], v[88:89], 0, s[12:13]
	global_load_dwordx4 v[0:3], v[0:1], off
	s_nop 0
	global_load_dwordx4 v[4:7], v[4:5], off
	s_nop 0
	global_load_dwordx4 v[8:11], v[8:9], off
	s_nop 0
	global_load_dwordx4 v[12:15], v[12:13], off
	s_branch .LBB0_594

; #define LAS __attribute__((address_space(3)))
; __device__ __forceinline__ float bflo(unsigned w) { return __uint_as_float(w << 16); }
; __device__ __forceinline__ float bfhi(unsigned w) { return __uint_as_float(w & 0xffff0000u); }
; __device__ __forceinline__ unsigned pk2(float lo, float hi) { return f2bf(lo) | (f2bf(hi) << 16); }
; __device__ __forceinline__ void phase_mixer_a(const Params& P, LAS unsigned char* lds, int ustart, int ustride, bool dry) {
;     ...
;             u32x2 pv[8]; float bsv[8];
; #pragma unroll
;             for (int mt = 0; mt < 8; ++mt) { const int t = 16 * mt + (lane & 15);
;                 pv[mt] = *(const u32x2*)(PJ + T_P + (size_t)(r0 + t) * 1024 + h * 128 + 16 * w + 4 * g4); bsv[mt] = P.b_spatial[h * 128 + t]; }
;             f32x4 acc[8];
; #pragma unroll
;             for (int mt = 0; mt < 8; ++mt) acc[mt] = (f32x4){0.f, 0.f, 0.f, 0.f};
; #pragma unroll
;             for (int ks = 0; ks < 4; ++ks) {
;                 const unsigned a0 = (unsigned)((32 * ks + 8 * g4 + q) * VN_P + 32 * w + 8 * p);
;                 const s16x4 lo = __builtin_amdgcn_ds_read_tr16_b64_v4i16((LAS s16x4*)(lds + a0)), hi = __builtin_amdgcn_ds_read_tr16_b64_v4i16((LAS s16x4*)(lds + a0 + 4 * VN_P));
;                 const bf16x8 vf = (bf16x8){lo[0], lo[1], lo[2], lo[3], hi[0], hi[1], hi[2], hi[3]};
; #pragma unroll
;                 for (int mt = 2 * ks; mt < 8; ++mt) {
;                     const bf16x8 wf = *(const LAS bf16x8*)(lds + W_OFF + (16 * mt + (lane & 15)) * W_P + (32 * ks + 8 * g4) * 2);
;                     acc[mt] = __builtin_amdgcn_mfma_f32_16x16x32_bf16(vf, wf, acc[mt], 0, 0, 0);
;                 }
;             }
; #pragma unroll
;             for (int mt = 0; mt < 8; ++mt) {
;                 const int t = 16 * mt + (lane & 15); const float bs = bsv[mt];
;                 u32x2 o; o.x = pk2(bflo(pv[mt].x) * (acc[mt][0] + bs), bfhi(pv[mt].x) * (acc[mt][1] + bs)); o.y = pk2(bflo(pv[mt].y) * (acc[mt][2] + bs), bfhi(pv[mt].y) * (acc[mt][3] + bs));
;                 if (!dry) *(u32x2*)((bf16_t*)P.out + (size_t)(r0 + t) * 2048 + h * 128 + 16 * w + 4 * g4) = o;
;             }
.LBB0_631:
	ds_read_b64_tr_b16 v[16:17], v163
	ds_read_b64_tr_b16 v[18:19], v163 offset:1152
	v_add_u32_e32 v41, v142, v143
	ds_read_b128 v[20:23], v41 offset:36864
	ds_read_b128 v[24:27], v41 offset:41216
	v_lshl_add_u64 v[128:129], v[94:95], 0, s[16:17]
	v_lshl_add_u64 v[204:205], v[58:59], 0, s[6:7]
	s_waitcnt lgkmcnt(1)
	v_mfma_f32_16x16x32_bf16 v[28:31], v[16:19], v[20:23], 0
	ds_read_b128 v[20:23], v41 offset:45568
	global_load_dwordx2 v[192:193], v[128:129], off
	ds_read_b128 v[128:131], v41 offset:49920
	global_load_dword v206, v[204:205], off
	ds_read_b128 v[168:171], v41 offset:54272
	ds_read_b128 v[172:175], v41 offset:58624
	v_lshl_add_u64 v[188:189], v[96:97], 0, s[16:17]
	v_add_u32_e32 v43, v142, v144
	ds_read_b128 v[176:179], v41 offset:62976
	ds_read_b64_tr_b16 v[180:181], v164
	ds_read_b64_tr_b16 v[182:183], v164 offset:1152
	ds_read_b128 v[184:187], v43 offset:62976
	v_add_u32_e32 v41, v145, v143
	global_load_dwordx2 v[208:209], v[188:189], off
	ds_read_b128 v[188:191], v41 offset:45568
	s_waitcnt lgkmcnt(8)
	v_mfma_f32_16x16x32_bf16 v[20:23], v[16:19], v[20:23], 0
	global_load_dword v210, v[204:205], off offset:64
	v_add_u32_e32 v43, v145, v144
	v_lshl_add_u64 v[200:201], v[98:99], 0, s[16:17]
	v_mfma_f32_16x16x32_bf16 v[24:27], v[16:19], v[24:27], 0
	v_lshl_add_u64 v[202:203], v[100:101], 0, s[16:17]
	v_lshl_add_u64 v[212:213], v[102:103], 0, s[16:17]
	v_lshl_add_u64 v[214:215], v[104:105], 0, s[16:17]
	s_waitcnt lgkmcnt(7)
	v_mfma_f32_16x16x32_bf16 v[128:131], v[16:19], v[128:131], 0
	v_lshl_add_u64 v[216:217], v[106:107], 0, s[16:17]
	v_add_u32_e32 v45, v147, v144
	v_lshl_add_u64 v[218:219], v[108:109], 0, s[16:17]
	s_waitcnt lgkmcnt(6)
	v_mfma_f32_16x16x32_bf16 v[168:171], v[16:19], v[168:171], 0
	v_lshl_add_u64 v[126:127], v[126:127], 0, s[14:15]
	v_lshl_add_u64 v[124:125], v[124:125], 0, s[14:15]
	v_lshl_add_u64 v[122:123], v[122:123], 0, s[14:15]
	s_waitcnt lgkmcnt(5)
	v_mfma_f32_16x16x32_bf16 v[172:175], v[16:19], v[172:175], 0
	v_lshl_add_u64 v[120:121], v[120:121], 0, s[14:15]
	s_waitcnt lgkmcnt(4)
	v_mfma_f32_16x16x32_bf16 v[176:179], v[16:19], v[176:179], 0
	s_waitcnt lgkmcnt(1)
	v_mfma_f32_16x16x32_bf16 v[16:19], v[16:19], v[184:187], 0
	ds_read_b128 v[184:187], v41 offset:49920
	s_waitcnt lgkmcnt(1)
	v_mfma_f32_16x16x32_bf16 v[188:191], v[180:183], v[188:191], v[20:23]
	s_nop 2
	ds_read_b128 v[20:23], v41 offset:54272
	s_waitcnt lgkmcnt(1)
	v_mfma_f32_16x16x32_bf16 v[128:131], v[180:183], v[184:187], v[128:131]
	ds_read_b128 v[184:187], v41 offset:58624
	s_waitcnt lgkmcnt(1)
	v_mfma_f32_16x16x32_bf16 v[20:23], v[180:183], v[20:23], v[168:171]
	s_nop 2
	ds_read_b128 v[168:171], v41 offset:62976
	s_waitcnt lgkmcnt(1)
	v_mfma_f32_16x16x32_bf16 v[172:175], v[180:183], v[184:187], v[172:175]
	ds_read_b64_tr_b16 v[184:185], v165
	ds_read_b64_tr_b16 v[186:187], v165 offset:1152
	ds_read_b128 v[196:199], v43 offset:62976
	v_add_u32_e32 v41, v146, v143
	global_load_dwordx2 v[220:221], v[200:201], off
	s_waitcnt lgkmcnt(3)
	v_mfma_f32_16x16x32_bf16 v[168:171], v[180:183], v[168:171], v[176:179]
	global_load_dword v222, v[204:205], off offset:128
	v_add_u32_e32 v43, v146, v144
	s_nop 0
	ds_read_b128 v[176:179], v41 offset:54272
	s_waitcnt lgkmcnt(1)
	v_mfma_f32_16x16x32_bf16 v[16:19], v[180:183], v[196:199], v[16:19]
	ds_read_b128 v[180:183], v41 offset:58624
	s_waitcnt lgkmcnt(1)
	v_mfma_f32_16x16x32_bf16 v[176:179], v[184:187], v[176:179], v[20:23]
	ds_read_b64_tr_b16 v[196:197], v166
	ds_read_b64_tr_b16 v[198:199], v166 offset:1152
	s_nop 0
	ds_read_b128 v[20:23], v41 offset:62976
	v_add_u32_e32 v41, v147, v143
	s_waitcnt lgkmcnt(3)
	v_mfma_f32_16x16x32_bf16 v[172:175], v[184:187], v[180:183], v[172:175]
	ds_read_b128 v[180:183], v43 offset:62976
	global_load_dwordx2 v[224:225], v[202:203], off
	s_nop 0
	global_load_dwordx2 v[212:213], v[212:213], off
	ds_read_b128 v[200:203], v41 offset:62976
	s_waitcnt lgkmcnt(2)
	v_mfma_f32_16x16x32_bf16 v[168:171], v[184:187], v[20:23], v[168:171]
	s_waitcnt lgkmcnt(1)
	v_mfma_f32_16x16x32_bf16 v[16:19], v[184:187], v[180:183], v[16:19]
	global_load_dwordx2 v[184:185], v[214:215], off
	global_load_dwordx2 v[186:187], v[216:217], off
	global_load_dwordx2 v[20:21], v[218:219], off
	ds_read_b128 v[180:183], v45 offset:62976
	s_waitcnt lgkmcnt(1)
	v_mfma_f32_16x16x32_bf16 v[168:171], v[196:199], v[200:203], v[168:171]
	global_load_dword v200, v[204:205], off offset:192
	global_load_dword v202, v[204:205], off offset:256
	global_load_dword v214, v[204:205], off offset:320
	global_load_dword v216, v[204:205], off offset:384
	global_load_dword v22, v[204:205], off offset:448
	s_waitcnt lgkmcnt(0)
	v_mfma_f32_16x16x32_bf16 v[16:19], v[196:199], v[180:183], v[16:19]
	v_mov_b32_e32 v182, v28
	v_mov_b32_e32 v183, v30
	s_waitcnt vmcnt(15)
	v_lshlrev_b32_e32 v181, 16, v193
	v_lshlrev_b32_e32 v180, 16, v192
	s_waitcnt vmcnt(14)
	v_pk_add_f32 v[182:183], v[206:207], v[182:183] op_sel_hi:[0,1]
	v_mov_b32_e32 v30, v29
	v_pk_mul_f32 v[180:181], v[182:183], v[180:181]
	v_and_b32_e32 v183, 0xffff0000, v193
	v_and_b32_e32 v182, 0xffff0000, v192
	v_pk_add_f32 v[28:29], v[206:207], v[30:31] op_sel_hi:[0,1]
	v_pk_mul_f32 v[28:29], v[28:29], v[182:183]
	s_nop 0
	v_cvt_pk_bf16_f32 v232, v181, v29
	v_cvt_pk_bf16_f32 v233, v180, v28
	v_mov_b32_e32 v29, v232
	v_mov_b32_e32 v28, v233
	v_lshl_add_u64 v[30:31], v[110:111], 0, s[16:17]
	global_store_dwordx2 v[30:31], v[28:29], off
	v_mov_b32_e32 v30, v24
	v_mov_b32_e32 v31, v26
	s_waitcnt vmcnt(14)
	v_lshlrev_b32_e32 v29, 16, v209
	v_lshlrev_b32_e32 v28, 16, v208
	s_waitcnt vmcnt(13)
; __device__ __forceinline__ float bflo(unsigned w) { return __uint_as_float(w << 16); }
; __device__ __forceinline__ float bfhi(unsigned w) { return __uint_as_float(w & 0xffff0000u); }
; __device__ __forceinline__ unsigned pk2(float lo, float hi) { return f2bf(lo) | (f2bf(hi) << 16); }
; __device__ __forceinline__ void phase_mixer_a(const Params& P, LAS unsigned char* lds, int ustart, int ustride, bool dry) {
;     ...
; #pragma unroll
;             for (int mt = 0; mt < 8; ++mt) {
;                 const int t = 16 * mt + (lane & 15); const float bs = bsv[mt];
;                 u32x2 o; o.x = pk2(bflo(pv[mt].x) * (acc[mt][0] + bs), bfhi(pv[mt].x) * (acc[mt][1] + bs)); o.y = pk2(bflo(pv[mt].y) * (acc[mt][2] + bs), bfhi(pv[mt].y) * (acc[mt][3] + bs));
;                 if (!dry) *(u32x2*)((bf16_t*)P.out + (size_t)(r0 + t) * 2048 + h * 128 + 16 * w + 4 * g4) = o;
;             }
;             __syncthreads();
	v_pk_add_f32 v[30:31], v[210:211], v[30:31] op_sel_hi:[0,1]
	v_mov_b32_e32 v26, v25
	v_pk_mul_f32 v[28:29], v[30:31], v[28:29]
	v_and_b32_e32 v31, 0xffff0000, v209
	v_and_b32_e32 v30, 0xffff0000, v208
	v_pk_add_f32 v[24:25], v[210:211], v[26:27] op_sel_hi:[0,1]
	v_pk_mul_f32 v[24:25], v[24:25], v[30:31]
	s_nop 0
	v_cvt_pk_bf16_f32 v235, v28, v24
	v_cvt_pk_bf16_f32 v234, v29, v25
	v_mov_b32_e32 v25, v234
	v_mov_b32_e32 v24, v235
	v_lshl_add_u64 v[26:27], v[112:113], 0, s[16:17]
	global_store_dwordx2 v[26:27], v[24:25], off
	v_mov_b32_e32 v26, v188
	v_mov_b32_e32 v27, v190
	s_waitcnt vmcnt(13)
	v_lshlrev_b32_e32 v25, 16, v221
	v_lshlrev_b32_e32 v24, 16, v220
	s_waitcnt vmcnt(12)
	v_pk_add_f32 v[26:27], v[222:223], v[26:27] op_sel_hi:[0,1]
	v_mov_b32_e32 v190, v189
	v_pk_mul_f32 v[24:25], v[26:27], v[24:25]
	v_and_b32_e32 v27, 0xffff0000, v221
	v_and_b32_e32 v26, 0xffff0000, v220
	v_pk_add_f32 v[28:29], v[222:223], v[190:191] op_sel_hi:[0,1]
	v_pk_mul_f32 v[26:27], v[28:29], v[26:27]
	s_nop 0
	v_cvt_pk_bf16_f32 v252, v24, v26
	v_cvt_pk_bf16_f32 v237, v25, v27
	v_mov_b32_e32 v25, v237
	v_mov_b32_e32 v24, v252
	v_lshl_add_u64 v[26:27], v[114:115], 0, s[16:17]
	global_store_dwordx2 v[26:27], v[24:25], off
	v_mov_b32_e32 v26, v128
	v_mov_b32_e32 v27, v130
	s_waitcnt vmcnt(12)
	v_lshlrev_b32_e32 v25, 16, v225
	v_lshlrev_b32_e32 v24, 16, v224
	s_waitcnt vmcnt(7)
	v_pk_add_f32 v[26:27], v[200:201], v[26:27] op_sel_hi:[0,1]
	v_mov_b32_e32 v130, v129
	v_pk_mul_f32 v[24:25], v[26:27], v[24:25]
	v_and_b32_e32 v27, 0xffff0000, v225
	v_and_b32_e32 v26, 0xffff0000, v224
	v_pk_add_f32 v[28:29], v[200:201], v[130:131] op_sel_hi:[0,1]
	v_pk_mul_f32 v[26:27], v[28:29], v[26:27]
	s_nop 0
	v_cvt_pk_bf16_f32 v254, v24, v26
	v_cvt_pk_bf16_f32 v253, v25, v27
	v_mov_b32_e32 v25, v253
	v_mov_b32_e32 v24, v254
	v_lshl_add_u64 v[26:27], v[116:117], 0, s[16:17]
	global_store_dwordx2 v[26:27], v[24:25], off
	v_mov_b32_e32 v26, v176
	v_mov_b32_e32 v27, v178
	v_lshlrev_b32_e32 v25, 16, v213
	v_lshlrev_b32_e32 v24, 16, v212
	s_waitcnt vmcnt(7)
	v_pk_add_f32 v[26:27], v[202:203], v[26:27] op_sel_hi:[0,1]
	v_mov_b32_e32 v178, v177
	v_pk_mul_f32 v[24:25], v[26:27], v[24:25]
	v_and_b32_e32 v27, 0xffff0000, v213
	v_and_b32_e32 v26, 0xffff0000, v212
	v_pk_add_f32 v[28:29], v[202:203], v[178:179] op_sel_hi:[0,1]
	v_pk_mul_f32 v[26:27], v[28:29], v[26:27]
	s_nop 0
	v_cvt_pk_bf16_f32 v232, v24, v26
	v_cvt_pk_bf16_f32 v255, v25, v27
	v_mov_b32_e32 v25, v255
	v_mov_b32_e32 v24, v232
	v_lshl_add_u64 v[26:27], v[118:119], 0, s[16:17]
	global_store_dwordx2 v[26:27], v[24:25], off
	v_mov_b32_e32 v26, v172
	v_mov_b32_e32 v27, v174
	v_lshlrev_b32_e32 v25, 16, v185
	v_lshlrev_b32_e32 v24, 16, v184
	s_waitcnt vmcnt(7)
	v_pk_add_f32 v[26:27], v[214:215], v[26:27] op_sel_hi:[0,1]
	v_mov_b32_e32 v174, v173
	v_pk_mul_f32 v[24:25], v[26:27], v[24:25]
	v_and_b32_e32 v27, 0xffff0000, v185
	v_and_b32_e32 v26, 0xffff0000, v184
	v_pk_add_f32 v[28:29], v[214:215], v[174:175] op_sel_hi:[0,1]
	v_pk_mul_f32 v[26:27], v[28:29], v[26:27]
	s_nop 0
	v_cvt_pk_bf16_f32 v234, v24, v26
	v_cvt_pk_bf16_f32 v233, v25, v27
	v_mov_b32_e32 v25, v233
	v_mov_b32_e32 v24, v234
	v_lshl_add_u64 v[26:27], v[92:93], 0, s[16:17]
	global_store_dwordx2 v[26:27], v[24:25], off
	v_mov_b32_e32 v26, v168
	v_mov_b32_e32 v27, v170
	v_lshlrev_b32_e32 v25, 16, v187
	v_lshlrev_b32_e32 v24, 16, v186
	s_waitcnt vmcnt(7)
	v_pk_add_f32 v[26:27], v[216:217], v[26:27] op_sel_hi:[0,1]
	v_mov_b32_e32 v170, v169
	v_pk_mul_f32 v[24:25], v[26:27], v[24:25]
	v_and_b32_e32 v27, 0xffff0000, v187
	v_and_b32_e32 v26, 0xffff0000, v186
	v_pk_add_f32 v[28:29], v[216:217], v[170:171] op_sel_hi:[0,1]
	v_pk_mul_f32 v[26:27], v[28:29], v[26:27]
	v_and_b32_sdwa v23, v25, v167 dst_sel:DWORD dst_unused:UNUSED_PAD src0_sel:WORD_1 src1_sel:DWORD
	v_cvt_pk_bf16_f32 v237, v24, v26
	v_add3_u32 v23, v25, v23, s18
	v_cvt_pk_bf16_f32 v235, v25, v27
	v_mov_b32_e32 v25, v235
	v_mov_b32_e32 v24, v237
	v_lshl_add_u64 v[26:27], v[90:91], 0, s[16:17]
	global_store_dwordx2 v[26:27], v[24:25], off
	v_mov_b32_e32 v27, v18
	v_mov_b32_e32 v18, v17
	v_lshlrev_b32_e32 v25, 16, v21
	v_lshlrev_b32_e32 v24, 16, v20
	v_mov_b32_e32 v26, v16
	v_and_b32_e32 v21, 0xffff0000, v21
	v_and_b32_e32 v20, 0xffff0000, v20
	s_waitcnt vmcnt(7)
	v_pk_add_f32 v[16:17], v[22:23], v[18:19] op_sel_hi:[0,1]
	v_pk_add_f32 v[26:27], v[22:23], v[26:27] op_sel_hi:[0,1]
	v_pk_mul_f32 v[16:17], v[16:17], v[20:21]
	v_pk_mul_f32 v[24:25], v[26:27], v[24:25]
	s_nop 0
	v_cvt_pk_bf16_f32 v252, v25, v17
	v_cvt_pk_bf16_f32 v253, v24, v16
	v_mov_b32_e32 v17, v252
	v_mov_b32_e32 v16, v253
	v_lshl_add_u64 v[18:19], v[88:89], 0, s[16:17]
	s_add_u32 s16, s16, 0x100
	s_addc_u32 s17, s17, 0
	s_add_u32 s6, s6, 0x200
	s_addc_u32 s7, s7, 0
	s_cmpk_eq_i32 s16, 0x800
	global_store_dwordx2 v[18:19], v[16:17], off
	s_barrier
	s_cbranch_scc1 .LBB0_619
; #define LAS __attribute__((address_space(3)))
; __device__ __forceinline__ float bflo(unsigned w) { return __uint_as_float(w << 16); }
; __device__ __forceinline__ float bfhi(unsigned w) { return __uint_as_float(w & 0xffff0000u); }
; __device__ __forceinline__ unsigned pk2(float lo, float hi) { return f2bf(lo) | (f2bf(hi) << 16); }
; __device__ __forceinline__ void phase_mixer_a(const Params& P, LAS unsigned char* lds, int ustart, int ustride, bool dry) {
;     ...
;             for (int i = 0; i < 4; ++i) {
;                 const int item = tid + 512 * i, c8 = item & 15, s = item >> 4;
;                 const u32x4 gv = pgv[i];
;                 const float mean = stats[2 * s], rstd = stats[2 * s + 1];
;                 const f32x4 g0 = *(const f32x4*)(P.ln_v_g + h * 128 + c8 * 8), g1 = *(const f32x4*)(P.ln_v_g + h * 128 + c8 * 8 + 4);
;                 const f32x4 b0 = *(const f32x4*)(P.ln_v_b + h * 128 + c8 * 8), b1 = *(const f32x4*)(P.ln_v_b + h * 128 + c8 * 8 + 4);
;                 u32x4 o;
;                 o.x = pk2((bflo(gv.x) - mean) * rstd * g0[0] + b0[0], (bfhi(gv.x) - mean) * rstd * g0[1] + b0[1]);
;                 o.y = pk2((bflo(gv.y) - mean) * rstd * g0[2] + b0[2], (bfhi(gv.y) - mean) * rstd * g0[3] + b0[3]);
;                 o.z = pk2((bflo(gv.z) - mean) * rstd * g1[0] + b1[0], (bfhi(gv.z) - mean) * rstd * g1[1] + b1[1]);
;                 o.w = pk2((bflo(gv.w) - mean) * rstd * g1[2] + b1[2], (bfhi(gv.w) - mean) * rstd * g1[3] + b1[3]);
;                 *(LAS u32x4*)(lds + s * VN_P + c8 * 16) = o;
;                 *(LAS u32x4*)(lds + W_OFF + s * W_P + c8 * 16) = *(const u32x4*)(WsT + h * 16384 + item * 8);
;             }
;             __syncthreads();
.LBB0_632:
	v_lshl_add_u64 v[16:17], v[62:63], 0, s[6:7]
	global_load_dwordx4 v[24:27], v[16:17], off offset:-16
	v_lshl_add_u64 v[20:21], v[66:67], 0, s[6:7]
	global_load_dwordx4 v[28:31], v[20:21], off offset:-16
	s_nop 0
	global_load_dwordx4 v[16:19], v[16:17], off
	s_nop 0
	global_load_dwordx4 v[20:23], v[20:21], off
	s_nop 0
	global_load_dwordx4 v[168:171], v[126:127], off
	global_load_dwordx4 v[172:175], v[124:125], off
	ds_read_b64 v[128:129], v151
	s_waitcnt vmcnt(9)
	v_lshlrev_b32_e32 v131, 16, v1
	v_lshlrev_b32_e32 v130, 16, v0
	v_and_b32_e32 v177, 0xffff0000, v1
	v_and_b32_e32 v176, 0xffff0000, v0
	v_lshlrev_b32_e32 v179, 16, v3
	v_lshlrev_b32_e32 v178, 16, v2
	v_and_b32_e32 v181, 0xffff0000, v3
	v_and_b32_e32 v180, 0xffff0000, v2
	s_waitcnt lgkmcnt(0)
	v_pk_add_f32 v[130:131], v[130:131], v[128:129] op_sel_hi:[1,0] neg_lo:[0,1] neg_hi:[0,1]
	v_pk_add_f32 v[176:177], v[176:177], v[128:129] op_sel_hi:[1,0] neg_lo:[0,1] neg_hi:[0,1]
	v_pk_add_f32 v[178:179], v[178:179], v[128:129] op_sel_hi:[1,0] neg_lo:[0,1] neg_hi:[0,1]
	v_pk_add_f32 v[180:181], v[180:181], v[128:129] op_sel_hi:[1,0] neg_lo:[0,1] neg_hi:[0,1]
	v_pk_mul_f32 v[188:189], v[128:129], v[130:131] op_sel:[1,0]
	v_pk_mul_f32 v[176:177], v[128:129], v[176:177] op_sel:[1,0]
	v_pk_mul_f32 v[178:179], v[128:129], v[178:179] op_sel:[1,0]
	v_pk_mul_f32 v[180:181], v[128:129], v[180:181] op_sel:[1,0]
	s_waitcnt vmcnt(8)
	v_lshlrev_b32_e32 v183, 16, v5
	v_lshlrev_b32_e32 v182, 16, v4
	v_and_b32_e32 v185, 0xffff0000, v5
	v_and_b32_e32 v184, 0xffff0000, v4
	v_lshlrev_b32_e32 v187, 16, v7
	v_lshlrev_b32_e32 v186, 16, v6
	s_cmpk_lg_i32 s16, 0x700
	s_waitcnt vmcnt(4)
	v_mov_b32_e32 v130, v28
	v_mov_b32_e32 v128, v24
	v_mov_b32_e32 v129, v26
	v_mov_b32_e32 v131, v30
	v_mov_b32_e32 v26, v25
	v_mov_b32_e32 v30, v29
	s_waitcnt vmcnt(3)
	v_mov_b32_e32 v24, v16
	v_mov_b32_e32 v25, v18
	s_waitcnt vmcnt(2)
	v_mov_b32_e32 v28, v20
	v_mov_b32_e32 v29, v22
	v_mov_b32_e32 v18, v17
	v_mov_b32_e32 v22, v21
	v_pk_fma_f32 v[16:17], v[188:189], v[128:129], v[130:131]
	v_pk_fma_f32 v[20:21], v[176:177], v[26:27], v[30:31]
	v_pk_fma_f32 v[176:177], v[178:179], v[24:25], v[28:29]
	v_pk_fma_f32 v[178:179], v[180:181], v[18:19], v[22:23]
	v_cvt_pk_bf16_f32 v255, v16, v20
	v_cvt_pk_bf16_f32 v254, v17, v21
	v_cvt_pk_bf16_f32 v179, v177, v179
	v_cvt_pk_bf16_f32 v178, v176, v178
	v_mov_b32_e32 v177, v254
	v_mov_b32_e32 v176, v255
	ds_write_b128 v152, v[176:179]
	s_waitcnt vmcnt(1)
	ds_write_b128 v153, v[168:171] offset:36864
	ds_read_b64 v[16:17], v154
	global_load_dwordx4 v[168:171], v[122:123], off
	v_and_b32_e32 v21, 0xffff0000, v7
	v_and_b32_e32 v20, 0xffff0000, v6
	s_waitcnt lgkmcnt(0)
	v_pk_add_f32 v[176:177], v[182:183], v[16:17] op_sel_hi:[1,0] neg_lo:[0,1] neg_hi:[0,1]
	v_pk_add_f32 v[178:179], v[184:185], v[16:17] op_sel_hi:[1,0] neg_lo:[0,1] neg_hi:[0,1]
	v_pk_add_f32 v[180:181], v[186:187], v[16:17] op_sel_hi:[1,0] neg_lo:[0,1] neg_hi:[0,1]
	v_pk_add_f32 v[20:21], v[20:21], v[16:17] op_sel_hi:[1,0] neg_lo:[0,1] neg_hi:[0,1]
	v_pk_mul_f32 v[176:177], v[16:17], v[176:177] op_sel:[1,0]
	v_pk_mul_f32 v[178:179], v[16:17], v[178:179] op_sel:[1,0]
	v_pk_mul_f32 v[180:181], v[16:17], v[180:181] op_sel:[1,0]
	v_pk_mul_f32 v[16:17], v[16:17], v[20:21] op_sel:[1,0]
	v_pk_fma_f32 v[20:21], v[128:129], v[176:177], v[130:131]
	v_pk_fma_f32 v[16:17], v[18:19], v[16:17], v[22:23]
	v_pk_fma_f32 v[176:177], v[26:27], v[178:179], v[30:31]
	v_pk_fma_f32 v[178:179], v[24:25], v[180:181], v[28:29]
	s_nop 0
	v_cvt_pk_bf16_f32 v233, v178, v16
	v_cvt_pk_bf16_f32 v232, v179, v17
	v_cvt_pk_bf16_f32 v234, v21, v177
	v_cvt_pk_bf16_f32 v235, v20, v176
	v_mov_b32_e32 v179, v232
	v_mov_b32_e32 v178, v233
	v_mov_b32_e32 v177, v234
	v_mov_b32_e32 v176, v235
	ds_write_b128 v155, v[176:179]
	s_waitcnt vmcnt(1)
	ds_write_b128 v156, v[172:175] offset:36864
	ds_read_b64 v[16:17], v157
	v_and_b32_e32 v173, 0xffff0000, v9
	v_and_b32_e32 v172, 0xffff0000, v8
	v_lshlrev_b32_e32 v21, 16, v9
	v_lshlrev_b32_e32 v20, 16, v8
	s_waitcnt lgkmcnt(0)
	v_pk_add_f32 v[172:173], v[172:173], v[16:17] op_sel_hi:[1,0] neg_lo:[0,1] neg_hi:[0,1]
	v_and_b32_e32 v181, 0xffff0000, v11
	v_pk_mul_f32 v[172:173], v[16:17], v[172:173] op_sel:[1,0]
	v_and_b32_e32 v180, 0xffff0000, v10
	v_pk_fma_f32 v[176:177], v[26:27], v[172:173], v[30:31]
	v_lshlrev_b32_e32 v173, 16, v11
	v_lshlrev_b32_e32 v172, 16, v10
	v_pk_add_f32 v[172:173], v[172:173], v[16:17] op_sel_hi:[1,0] neg_lo:[0,1] neg_hi:[0,1]
	v_pk_add_f32 v[20:21], v[20:21], v[16:17] op_sel_hi:[1,0] neg_lo:[0,1] neg_hi:[0,1]
	v_pk_mul_f32 v[172:173], v[16:17], v[172:173] op_sel:[1,0]
	v_pk_add_f32 v[180:181], v[180:181], v[16:17] op_sel_hi:[1,0] neg_lo:[0,1] neg_hi:[0,1]
	v_pk_fma_f32 v[178:179], v[24:25], v[172:173], v[28:29]
	global_load_dwordx4 v[172:175], v[120:121], off
	v_pk_mul_f32 v[20:21], v[16:17], v[20:21] op_sel:[1,0]
	v_pk_mul_f32 v[16:17], v[16:17], v[180:181] op_sel:[1,0]
	v_pk_fma_f32 v[20:21], v[128:129], v[20:21], v[130:131]
	v_pk_fma_f32 v[16:17], v[18:19], v[16:17], v[22:23]
	s_nop 0
	v_cvt_pk_bf16_f32 v252, v178, v16
	v_cvt_pk_bf16_f32 v237, v179, v17
	v_cvt_pk_bf16_f32 v253, v21, v177
	v_cvt_pk_bf16_f32 v254, v20, v176
	v_mov_b32_e32 v179, v237
	v_mov_b32_e32 v178, v252
	v_mov_b32_e32 v177, v253
	v_mov_b32_e32 v176, v254
	ds_write_b128 v158, v[176:179]
	s_waitcnt vmcnt(1)
	ds_write_b128 v159, v[168:171] offset:36864
	ds_read_b64 v[16:17], v160
	v_lshlrev_b32_e32 v21, 16, v13
	v_lshlrev_b32_e32 v20, 16, v12
	s_waitcnt lgkmcnt(0)
	v_pk_add_f32 v[20:21], v[20:21], v[16:17] op_sel_hi:[1,0] neg_lo:[0,1] neg_hi:[0,1]
	s_nop 0
	v_pk_mul_f32 v[20:21], v[16:17], v[20:21] op_sel:[1,0]
	s_nop 0
	v_pk_fma_f32 v[20:21], v[128:129], v[20:21], v[130:131]
	v_and_b32_e32 v129, 0xffff0000, v13
	v_and_b32_e32 v128, 0xffff0000, v12
	v_pk_add_f32 v[128:129], v[128:129], v[16:17] op_sel_hi:[1,0] neg_lo:[0,1] neg_hi:[0,1]
	s_nop 0
	v_pk_mul_f32 v[128:129], v[16:17], v[128:129] op_sel:[1,0]
	s_nop 0
	v_pk_fma_f32 v[26:27], v[26:27], v[128:129], v[30:31]
	v_lshlrev_b32_e32 v31, 16, v15
	v_lshlrev_b32_e32 v30, 16, v14
	v_pk_add_f32 v[30:31], v[30:31], v[16:17] op_sel_hi:[1,0] neg_lo:[0,1] neg_hi:[0,1]
	s_nop 0
	v_pk_mul_f32 v[30:31], v[16:17], v[30:31] op_sel:[1,0]
	s_nop 0
	v_pk_fma_f32 v[24:25], v[24:25], v[30:31], v[28:29]
	v_and_b32_e32 v29, 0xffff0000, v15
	v_and_b32_e32 v28, 0xffff0000, v14
	v_pk_add_f32 v[28:29], v[28:29], v[16:17] op_sel_hi:[1,0] neg_lo:[0,1] neg_hi:[0,1]
	s_nop 0
	v_pk_mul_f32 v[16:17], v[16:17], v[28:29] op_sel:[1,0]
	s_nop 0
	v_pk_fma_f32 v[16:17], v[18:19], v[16:17], v[22:23]
	s_nop 0
	v_cvt_pk_bf16_f32 v232, v24, v16
	v_cvt_pk_bf16_f32 v255, v25, v17
	v_cvt_pk_bf16_f32 v234, v20, v26
	v_cvt_pk_bf16_f32 v233, v21, v27
	v_mov_b32_e32 v19, v255
	v_mov_b32_e32 v18, v232
	v_mov_b32_e32 v17, v233
	v_mov_b32_e32 v16, v234
	ds_write_b128 v161, v[16:19]
	s_waitcnt vmcnt(0)
	ds_write_b128 v162, v[172:175] offset:36864
	s_waitcnt lgkmcnt(0)
	s_barrier
; __device__ __forceinline__ void phase_mixer_a(const Params& P, LAS unsigned char* lds, int ustart, int ustride, bool dry) {
;     ...
;             if (h + 1 < 8) {
; #pragma unroll
;                 for (int i = 0; i < 4; ++i) { const int item = tid + 512 * i, c8 = item & 15, s = item >> 4;
;                     pgv[i] = *(const u32x4*)(PJ + T_GV + (size_t)(r0 + s) * 1024 + (h + 1) * 128 + c8 * 8); }
;             }
	s_cbranch_scc0 .LBB0_631
	v_lshl_add_u64 v[12:13], v[86:87], 0, s[16:17]
	v_lshl_add_u64 v[8:9], v[84:85], 0, s[16:17]
	v_lshl_add_u64 v[4:5], v[82:83], 0, s[16:17]
	v_lshl_add_u64 v[0:1], v[80:81], 0, s[16:17]
	global_load_dwordx4 v[0:3], v[0:1], off
	s_nop 0
	global_load_dwordx4 v[4:7], v[4:5], off
	s_nop 0
	global_load_dwordx4 v[8:11], v[8:9], off
	s_nop 0
	global_load_dwordx4 v[12:15], v[12:13], off
	s_branch .LBB0_631

; #define LAS __attribute__((address_space(3)))
; __device__ __forceinline__ float bflo(unsigned w) { return __uint_as_float(w << 16); }
; __device__ __forceinline__ float bfhi(unsigned w) { return __uint_as_float(w & 0xffff0000u); }
; __device__ __forceinline__ unsigned pk2(float lo, float hi) { return f2bf(lo) | (f2bf(hi) << 16); }
; template <bool FULL>
; __device__ __forceinline__ void gla_pass(const Params& P, LAS unsigned char* lds, f32x4 (&S)[8][2], int bh, int c0, int L, bool dry) {
;     ...
;         if (FULL) {
;             f32x4 gn[2];
; #pragma unroll
;             for (int vt = 0; vt < 2; ++vt) gn[vt] = *(const f32x4*)(P.gla_norm_g + 32 * w + 4 * g + 16 * vt);
; #pragma unroll
;             for (int tt = 0; tt < 4; ++tt) {
;                 const int t = 16 * tt + fr;
;                 const f32x4 r0 = *(const LAS f32x4*)(red + t * 8), r1 = *(const LAS f32x4*)(red + t * 8 + 4);
;                 const float rstd = 1.0f / sqrtf(((r0[0] + r0[1]) + (r0[2] + r0[3]) + (r1[0] + r1[1]) + (r1[2] + r1[3])) * (1.0f / 256.0f) + RMS_EPS);
; #pragma unroll
;                 for (int vt = 0; vt < 2; ++vt) {
;                     bf16_t* op = (bf16_t*)P.out + (row0 + t) * 2048 + 1024 + h * 256 + 32 * w + 16 * vt + 4 * g;
;                     const u32x2 z = zb[vt][tt]; const f32x4 ov = o[vt][tt] * rstd * gn[vt];
;                     u32x2 r; r.x = pk2(ov[0] * bflo(z.x), ov[1] * bfhi(z.x)); r.y = pk2(ov[2] * bflo(z.y), ov[3] * bfhi(z.y));
;                     if (!dry) *(u32x2*)op = r;
;                 }
;             }
.LBB0_698:
	v_mov_b32_e32 v140, v238
	v_mov_b32_e32 v141, v239
	v_mov_b32_e32 v142, v240
	v_mov_b32_e32 v143, v241
	v_mov_b32_e32 v136, v242
	v_mov_b32_e32 v137, v243
	v_mov_b32_e32 v138, v244
	v_mov_b32_e32 v139, v245
	ds_read_b128 v[208:211], v190
	ds_read_b128 v[212:215], v190 offset:16
	s_waitcnt vmcnt(7)
	v_lshlrev_b32_e32 v217, 16, v181
	v_lshlrev_b32_e32 v216, 16, v180
	v_and_b32_e32 v181, 0xffff0000, v181
	s_waitcnt lgkmcnt(1)
	v_mov_b32_e32 v220, v209
	v_mov_b32_e32 v221, v210
	v_mov_b32_e32 v209, v211
	s_waitcnt lgkmcnt(0)
	v_mov_b32_e32 v210, v214
	v_mov_b32_e32 v211, v212
	v_mov_b32_e32 v212, v215
	v_pk_add_f32 v[208:209], v[220:221], v[208:209]
	v_pk_add_f32 v[210:211], v[210:211], v[212:213]
	v_add_f32_e32 v208, v208, v209
	v_add_f32_e32 v208, v208, v211
	v_add_f32_e32 v208, v210, v208
	v_fmamk_f32 v208, v208, 0x3b800000, v202
	v_mul_f32_e32 v209, 0x4f800000, v208
	v_cmp_gt_f32_e32 vcc, s26, v208
	v_and_b32_e32 v180, 0xffff0000, v180
	s_waitcnt vmcnt(4)
	v_lshlrev_b32_e32 v219, 16, v179
	v_cndmask_b32_e32 v210, v208, v209, vcc
	v_sqrt_f32_e32 v211, v210
	v_lshlrev_b32_e32 v218, 16, v178
	v_and_b32_e32 v179, 0xffff0000, v179
	v_and_b32_e32 v178, 0xffff0000, v178
	v_add_u32_e32 v212, -1, v211
	v_add_u32_e32 v213, 1, v211
	v_fma_f32 v214, -v212, v211, v210
	v_fma_f32 v215, -v213, v211, v210
	v_cmp_ge_f32_e64 s[8:9], 0, v214
	v_add_u32_e32 v160, s27, v193
	v_lshlrev_b64 v[208:209], 12, v[160:161]
	v_cndmask_b32_e64 v211, v211, v212, s[8:9]
	v_cmp_lt_f32_e64 s[8:9], 0, v215
	v_lshl_add_u64 v[208:209], v[168:169], 0, v[208:209]
	s_add_i32 s27, s27, 64
	v_cndmask_b32_e64 v211, v211, v213, s[8:9]
	v_mul_f32_e32 v212, 0x37800000, v211
	v_cndmask_b32_e32 v211, v211, v212, vcc
	v_cmp_class_f32_e32 vcc, v210, v203
	s_add_i32 s0, s0, 1
	v_lshl_add_u64 v[170:171], v[170:171], 0, s[14:15]
	v_cndmask_b32_e32 v210, v211, v210, vcc
	v_div_scale_f32 v211, s[8:9], v210, v210, 1.0
	v_rcp_f32_e32 v212, v211
	v_div_scale_f32 v213, vcc, 1.0, v210, 1.0
	s_cmpk_eq_i32 s27, 0x400
	v_fma_f32 v214, -v211, v212, 1.0
	v_fmac_f32_e32 v212, v214, v212
	v_mul_f32_e32 v214, v213, v212
	v_fma_f32 v215, -v211, v214, v213
	v_fmac_f32_e32 v214, v215, v212
	v_fma_f32 v211, -v211, v214, v213
	v_div_fmas_f32 v211, v211, v212, v214
	v_div_fixup_f32 v210, v211, v210, 1.0
	v_pk_mul_f32 v[134:135], v[134:135], v[210:211] op_sel_hi:[1,0]
	v_pk_mul_f32 v[132:133], v[132:133], v[210:211] op_sel_hi:[1,0]
	v_pk_mul_f32 v[130:131], v[130:131], v[210:211] op_sel_hi:[1,0]
	v_pk_mul_f32 v[128:129], v[128:129], v[210:211] op_sel_hi:[1,0]
	v_lshl_add_u64 v[172:173], v[172:173], 0, s[16:17]
	s_waitcnt vmcnt(0)
	v_pk_mul_f32 v[132:133], v[140:141], v[132:133]
	v_pk_mul_f32 v[134:135], v[142:143], v[134:135]
	v_pk_mul_f32 v[128:129], v[136:137], v[128:129]
	v_pk_mul_f32 v[130:131], v[138:139], v[130:131]
	v_mov_b32_e32 v210, v132
	v_mov_b32_e32 v211, v134
	v_mov_b32_e32 v134, v133
	v_mov_b32_e32 v132, v128
	v_mov_b32_e32 v133, v130
	v_mov_b32_e32 v130, v129
	v_pk_mul_f32 v[128:129], v[210:211], v[216:217]
	v_pk_mul_f32 v[134:135], v[134:135], v[180:181]
	v_pk_mul_f32 v[178:179], v[130:131], v[178:179]
	v_cvt_pk_bf16_f32 v254, v128, v134
	v_cvt_pk_bf16_f32 v253, v129, v135
	v_pk_mul_f32 v[132:133], v[132:133], v[218:219]
	v_mov_b32_e32 v129, v253
	v_mov_b32_e32 v128, v254
	global_store_dwordx2 v[208:209], v[128:129], off offset:2048
	ds_read_b128 v[128:131], v205
	v_cvt_pk_bf16_f32 v232, v132, v178
	v_cvt_pk_bf16_f32 v255, v133, v179
	ds_read_b128 v[132:135], v205 offset:16
	s_waitcnt lgkmcnt(1)
	v_mov_b32_e32 v180, v129
	v_mov_b32_e32 v181, v130
	v_mov_b32_e32 v129, v131
	v_pk_add_f32 v[128:129], v[180:181], v[128:129]
	s_waitcnt lgkmcnt(0)
	v_mov_b32_e32 v130, v134
	v_mov_b32_e32 v131, v132
	v_mov_b32_e32 v132, v135
	v_pk_add_f32 v[130:131], v[130:131], v[132:133]
	v_add_f32_e32 v128, v128, v129
	v_add_f32_e32 v128, v128, v131
	v_add_f32_e32 v128, v130, v128
	v_fmamk_f32 v128, v128, 0x3b800000, v202
	v_mul_f32_e32 v129, 0x4f800000, v128
	v_cmp_gt_f32_e32 vcc, s26, v128
	s_nop 1
	v_cndmask_b32_e32 v128, v128, v129, vcc
	v_sqrt_f32_e32 v129, v128
	s_nop 0
	v_add_u32_e32 v132, -1, v129
	v_fma_f32 v133, -v132, v129, v128
	v_cmp_ge_f32_e64 s[8:9], 0, v133
	v_add_u32_e32 v133, 1, v129
	s_nop 0
	v_cndmask_b32_e64 v132, v129, v132, s[8:9]
	v_fma_f32 v129, -v133, v129, v128
	v_cmp_lt_f32_e64 s[8:9], 0, v129
	s_nop 1
	v_cndmask_b32_e64 v129, v132, v133, s[8:9]
	v_mul_f32_e32 v132, 0x37800000, v129
	v_cndmask_b32_e32 v129, v129, v132, vcc
	v_cmp_class_f32_e32 vcc, v128, v203
	s_nop 1
	v_cndmask_b32_e32 v132, v129, v128, vcc
	v_div_scale_f32 v133, s[8:9], v132, v132, 1.0
	v_rcp_f32_e32 v134, v133
	v_mov_b32_e32 v129, v255
	v_mov_b32_e32 v128, v232
	global_store_dwordx2 v[208:209], v[128:129], off offset:2080
	v_fma_f32 v128, -v133, v134, 1.0
	v_fmac_f32_e32 v134, v128, v134
	v_div_scale_f32 v128, vcc, 1.0, v132, 1.0
	v_mul_f32_e32 v129, v128, v134
	v_fma_f32 v130, -v133, v129, v128
	v_fmac_f32_e32 v129, v130, v134
	v_fma_f32 v128, -v133, v129, v128
	v_div_fmas_f32 v128, v128, v134, v129
	v_div_fixup_f32 v128, v128, v132, 1.0
	v_pk_mul_f32 v[126:127], v[126:127], v[128:129] op_sel_hi:[1,0]
	v_pk_mul_f32 v[124:125], v[124:125], v[128:129] op_sel_hi:[1,0]
	v_pk_mul_f32 v[126:127], v[142:143], v[126:127]
	v_pk_mul_f32 v[124:125], v[140:141], v[124:125]
	v_lshlrev_b32_e32 v133, 16, v177
	v_lshlrev_b32_e32 v132, 16, v176
	v_mov_b32_e32 v134, v124
	v_mov_b32_e32 v135, v126
	v_pk_mul_f32 v[132:133], v[134:135], v[132:133]
	v_and_b32_e32 v135, 0xffff0000, v177
	v_and_b32_e32 v134, 0xffff0000, v176
	v_mov_b32_e32 v126, v125
	v_pk_mul_f32 v[124:125], v[126:127], v[134:135]
	s_nop 0
	v_and_b32_sdwa v129, v125, v204 dst_sel:DWORD dst_unused:UNUSED_PAD src0_sel:WORD_1 src1_sel:DWORD
	v_cvt_pk_bf16_f32 v234, v132, v124
	v_add_u32_e32 v130, 16, v160
	v_mov_b32_e32 v131, v161
	v_cvt_pk_bf16_f32 v233, v133, v125
	v_lshlrev_b64 v[130:131], 12, v[130:131]
	v_pk_mul_f32 v[122:123], v[122:123], v[128:129] op_sel_hi:[1,0]
	v_pk_mul_f32 v[120:121], v[120:121], v[128:129] op_sel_hi:[1,0]
	v_mov_b32_e32 v125, v233
	v_mov_b32_e32 v124, v234
	v_lshl_add_u64 v[130:131], v[168:169], 0, v[130:131]
	v_pk_mul_f32 v[120:121], v[136:137], v[120:121]
	v_pk_mul_f32 v[122:123], v[138:139], v[122:123]
	global_store_dwordx2 v[130:131], v[124:125], off offset:2048
	v_lshlrev_b32_e32 v125, 16, v175
	v_lshlrev_b32_e32 v124, 16, v174
	v_mov_b32_e32 v126, v120
	v_mov_b32_e32 v127, v122
	v_pk_mul_f32 v[124:125], v[126:127], v[124:125]
	v_and_b32_e32 v127, 0xffff0000, v175
	v_and_b32_e32 v126, 0xffff0000, v174
	v_mov_b32_e32 v122, v121
	v_pk_mul_f32 v[128:129], v[122:123], v[126:127]
	ds_read_b128 v[120:123], v206
	v_cvt_pk_bf16_f32 v237, v124, v128
	v_cvt_pk_bf16_f32 v235, v125, v129
	ds_read_b128 v[124:127], v206 offset:16
	s_waitcnt lgkmcnt(1)
; #define LAS __attribute__((address_space(3)))
; __device__ __forceinline__ float bflo(unsigned w) { return __uint_as_float(w << 16); }
; __device__ __forceinline__ float bfhi(unsigned w) { return __uint_as_float(w & 0xffff0000u); }
; __device__ __forceinline__ unsigned pk2(float lo, float hi) { return f2bf(lo) | (f2bf(hi) << 16); }
; template <bool FULL>
; __device__ __forceinline__ void gla_pass(const Params& P, LAS unsigned char* lds, f32x4 (&S)[8][2], int bh, int c0, int L, bool dry) {
;     ...
;         if (FULL) {
;             f32x4 gn[2];
; #pragma unroll
;             for (int vt = 0; vt < 2; ++vt) gn[vt] = *(const f32x4*)(P.gla_norm_g + 32 * w + 4 * g + 16 * vt);
; #pragma unroll
;             for (int tt = 0; tt < 4; ++tt) {
;                 const int t = 16 * tt + fr;
;                 const f32x4 r0 = *(const LAS f32x4*)(red + t * 8), r1 = *(const LAS f32x4*)(red + t * 8 + 4);
;                 const float rstd = 1.0f / sqrtf(((r0[0] + r0[1]) + (r0[2] + r0[3]) + (r1[0] + r1[1]) + (r1[2] + r1[3])) * (1.0f / 256.0f) + RMS_EPS);
; #pragma unroll
;                 for (int vt = 0; vt < 2; ++vt) {
;                     bf16_t* op = (bf16_t*)P.out + (row0 + t) * 2048 + 1024 + h * 256 + 32 * w + 16 * vt + 4 * g;
;                     const u32x2 z = zb[vt][tt]; const f32x4 ov = o[vt][tt] * rstd * gn[vt];
;                     u32x2 r; r.x = pk2(ov[0] * bflo(z.x), ov[1] * bfhi(z.x)); r.y = pk2(ov[2] * bflo(z.y), ov[3] * bfhi(z.y));
;                     if (!dry) *(u32x2*)op = r;
;                 }
;             }
;         }
;         __syncthreads();
	v_mov_b32_e32 v132, v121
	v_mov_b32_e32 v133, v122
	v_mov_b32_e32 v121, v123
	v_pk_add_f32 v[120:121], v[132:133], v[120:121]
	s_waitcnt lgkmcnt(0)
	v_mov_b32_e32 v122, v126
	v_mov_b32_e32 v123, v124
	v_mov_b32_e32 v124, v127
	v_pk_add_f32 v[122:123], v[122:123], v[124:125]
	v_add_f32_e32 v120, v120, v121
	v_add_f32_e32 v120, v120, v123
	v_add_f32_e32 v120, v122, v120
	v_fmamk_f32 v120, v120, 0x3b800000, v202
	v_mul_f32_e32 v121, 0x4f800000, v120
	v_cmp_gt_f32_e32 vcc, s26, v120
	s_nop 1
	v_cndmask_b32_e32 v120, v120, v121, vcc
	v_sqrt_f32_e32 v121, v120
	s_nop 0
	v_add_u32_e32 v124, -1, v121
	v_fma_f32 v125, -v124, v121, v120
	v_cmp_ge_f32_e64 s[8:9], 0, v125
	v_add_u32_e32 v125, 1, v121
	s_nop 0
	v_cndmask_b32_e64 v124, v121, v124, s[8:9]
	v_fma_f32 v121, -v125, v121, v120
	v_cmp_lt_f32_e64 s[8:9], 0, v121
	s_nop 1
	v_cndmask_b32_e64 v121, v124, v125, s[8:9]
	v_mul_f32_e32 v124, 0x37800000, v121
	v_cndmask_b32_e32 v121, v121, v124, vcc
	v_cmp_class_f32_e32 vcc, v120, v203
	s_nop 1
	v_cndmask_b32_e32 v124, v121, v120, vcc
	v_div_scale_f32 v125, s[8:9], v124, v124, 1.0
	v_rcp_f32_e32 v126, v125
	v_mov_b32_e32 v121, v235
	v_mov_b32_e32 v120, v237
	global_store_dwordx2 v[130:131], v[120:121], off offset:2080
	v_fma_f32 v120, -v125, v126, 1.0
	v_fmac_f32_e32 v126, v120, v126
	v_div_scale_f32 v120, vcc, 1.0, v124, 1.0
	v_mul_f32_e32 v121, v120, v126
	v_fma_f32 v122, -v125, v121, v120
	v_fmac_f32_e32 v121, v122, v126
	v_fma_f32 v120, -v125, v121, v120
	v_div_fmas_f32 v120, v120, v126, v121
	v_div_fixup_f32 v120, v120, v124, 1.0
	v_pk_mul_f32 v[110:111], v[110:111], v[120:121] op_sel_hi:[1,0]
	v_pk_mul_f32 v[108:109], v[108:109], v[120:121] op_sel_hi:[1,0]
	v_pk_mul_f32 v[110:111], v[142:143], v[110:111]
	v_pk_mul_f32 v[108:109], v[140:141], v[108:109]
	v_lshlrev_b32_e32 v125, 16, v151
	v_lshlrev_b32_e32 v124, 16, v150
	v_mov_b32_e32 v126, v108
	v_mov_b32_e32 v127, v110
	v_pk_mul_f32 v[124:125], v[126:127], v[124:125]
	v_and_b32_e32 v127, 0xffff0000, v151
	v_and_b32_e32 v126, 0xffff0000, v150
	v_mov_b32_e32 v110, v109
	v_pk_mul_f32 v[108:109], v[110:111], v[126:127]
	s_nop 0
	v_and_b32_sdwa v121, v109, v204 dst_sel:DWORD dst_unused:UNUSED_PAD src0_sel:WORD_1 src1_sel:DWORD
	v_cvt_pk_bf16_f32 v253, v124, v108
	v_add_u32_e32 v122, 32, v160
	v_mov_b32_e32 v123, v161
	v_cvt_pk_bf16_f32 v252, v125, v109
	v_lshlrev_b64 v[122:123], 12, v[122:123]
	v_pk_mul_f32 v[106:107], v[106:107], v[120:121] op_sel_hi:[1,0]
	v_pk_mul_f32 v[104:105], v[104:105], v[120:121] op_sel_hi:[1,0]
	v_mov_b32_e32 v109, v252
	v_mov_b32_e32 v108, v253
	v_lshl_add_u64 v[122:123], v[168:169], 0, v[122:123]
	v_pk_mul_f32 v[104:105], v[136:137], v[104:105]
	v_pk_mul_f32 v[106:107], v[138:139], v[106:107]
	global_store_dwordx2 v[122:123], v[108:109], off offset:2048
	v_lshlrev_b32_e32 v109, 16, v149
	v_lshlrev_b32_e32 v108, 16, v148
	v_mov_b32_e32 v110, v104
	v_mov_b32_e32 v111, v106
	v_pk_mul_f32 v[108:109], v[110:111], v[108:109]
	v_and_b32_e32 v111, 0xffff0000, v149
	v_and_b32_e32 v110, 0xffff0000, v148
	v_mov_b32_e32 v106, v105
	v_pk_mul_f32 v[120:121], v[106:107], v[110:111]
	ds_read_b128 v[104:107], v207
	v_cvt_pk_bf16_f32 v255, v108, v120
	v_cvt_pk_bf16_f32 v254, v109, v121
	ds_read_b128 v[108:111], v207 offset:16
	s_waitcnt lgkmcnt(1)
	v_mov_b32_e32 v124, v105
	v_mov_b32_e32 v125, v106
	v_mov_b32_e32 v105, v107
	v_pk_add_f32 v[104:105], v[124:125], v[104:105]
	s_waitcnt lgkmcnt(0)
	v_mov_b32_e32 v106, v110
	v_mov_b32_e32 v107, v108
	v_mov_b32_e32 v108, v111
	v_pk_add_f32 v[106:107], v[106:107], v[108:109]
	v_add_f32_e32 v104, v104, v105
	v_add_f32_e32 v104, v104, v107
	v_add_f32_e32 v104, v106, v104
	v_fmamk_f32 v104, v104, 0x3b800000, v202
	v_mul_f32_e32 v105, 0x4f800000, v104
	v_cmp_gt_f32_e32 vcc, s26, v104
	s_nop 1
	v_cndmask_b32_e32 v104, v104, v105, vcc
	v_sqrt_f32_e32 v105, v104
	v_add_u32_e32 v160, 48, v160
	v_add_u32_e32 v108, -1, v105
	v_fma_f32 v109, -v108, v105, v104
	v_cmp_ge_f32_e64 s[8:9], 0, v109
	v_add_u32_e32 v109, 1, v105
	s_nop 0
	v_cndmask_b32_e64 v108, v105, v108, s[8:9]
	v_fma_f32 v105, -v109, v105, v104
	v_cmp_lt_f32_e64 s[8:9], 0, v105
	s_nop 1
	v_cndmask_b32_e64 v105, v108, v109, s[8:9]
	v_mul_f32_e32 v108, 0x37800000, v105
	v_cndmask_b32_e32 v105, v105, v108, vcc
	v_cmp_class_f32_e32 vcc, v104, v203
	s_nop 1
	v_cndmask_b32_e32 v108, v105, v104, vcc
	v_div_scale_f32 v109, s[8:9], v108, v108, 1.0
	v_rcp_f32_e32 v110, v109
	v_mov_b32_e32 v105, v254
	v_mov_b32_e32 v104, v255
	global_store_dwordx2 v[122:123], v[104:105], off offset:2080
	v_fma_f32 v104, -v109, v110, 1.0
	v_fmac_f32_e32 v110, v104, v110
	v_div_scale_f32 v104, vcc, 1.0, v108, 1.0
	v_mul_f32_e32 v105, v104, v110
	v_fma_f32 v106, -v109, v105, v104
	v_fmac_f32_e32 v105, v106, v110
	v_fma_f32 v104, -v109, v105, v104
	v_div_fmas_f32 v104, v104, v110, v105
	v_div_fixup_f32 v104, v104, v108, 1.0
	v_pk_mul_f32 v[108:109], v[118:119], v[104:105] op_sel_hi:[1,0]
	v_pk_mul_f32 v[110:111], v[116:117], v[104:105] op_sel_hi:[1,0]
	v_pk_mul_f32 v[108:109], v[142:143], v[108:109]
	v_pk_mul_f32 v[110:111], v[140:141], v[110:111]
	v_lshlrev_b32_e32 v117, 16, v147
	v_lshlrev_b32_e32 v116, 16, v146
	v_mov_b32_e32 v118, v110
	v_mov_b32_e32 v119, v108
	v_pk_mul_f32 v[116:117], v[118:119], v[116:117]
	v_and_b32_e32 v119, 0xffff0000, v147
	v_and_b32_e32 v118, 0xffff0000, v146
	v_mov_b32_e32 v108, v111
	v_pk_mul_f32 v[108:109], v[108:109], v[118:119]
	s_nop 0
	v_cvt_pk_bf16_f32 v233, v116, v108
	v_and_b32_sdwa v105, v117, v204 dst_sel:DWORD dst_unused:UNUSED_PAD src0_sel:WORD_1 src1_sel:DWORD
	v_cvt_pk_bf16_f32 v232, v117, v109
	v_lshlrev_b64 v[106:107], 12, v[160:161]
	v_add3_u32 v105, v117, v105, s1
	v_mov_b32_e32 v109, v232
	v_mov_b32_e32 v108, v233
	v_lshl_add_u64 v[106:107], v[168:169], 0, v[106:107]
	global_store_dwordx2 v[106:107], v[108:109], off offset:2048
	v_pk_mul_f32 v[108:109], v[114:115], v[104:105] op_sel_hi:[1,0]
	v_pk_mul_f32 v[104:105], v[112:113], v[104:105] op_sel_hi:[1,0]
	v_pk_mul_f32 v[108:109], v[138:139], v[108:109]
	v_pk_mul_f32 v[104:105], v[136:137], v[104:105]
	v_lshlrev_b32_e32 v111, 16, v145
	v_lshlrev_b32_e32 v110, 16, v144
	v_mov_b32_e32 v112, v104
	v_mov_b32_e32 v113, v108
	v_pk_mul_f32 v[110:111], v[112:113], v[110:111]
	v_and_b32_e32 v113, 0xffff0000, v145
	v_and_b32_e32 v112, 0xffff0000, v144
	v_mov_b32_e32 v108, v105
	v_pk_mul_f32 v[104:105], v[108:109], v[112:113]
	s_nop 0
	v_cvt_pk_bf16_f32 v235, v110, v104
	v_cvt_pk_bf16_f32 v234, v111, v105
	v_mov_b32_e32 v105, v234
	v_mov_b32_e32 v104, v235
	global_store_dwordx2 v[106:107], v[104:105], off offset:2080
	s_barrier
	s_cbranch_scc1 .LBB0_714
